# attention loops: next-unit K/V prefetch addresses as 32-bit row offsets with SGPR bases (saddr loads, 4 VALU per row instead of 12), q rows used directly as MFMA B operands
# speedup vs baseline: 1.0062x; 1.0062x over previous
; #define LAS __attribute__((address_space(3)))
; __device__ __forceinline__ void attn_issue(const AUnit& w, const bf16_t* Qb, const bf16_t* Kb, const bf16_t* Vb, int tid, int wave, int lane, u32x4 (&kv)[6], u32x4 (&vv)[6]) {
;     const int ch = tid & 7;
; #pragma unroll
;     for (int i = 0; i < 6; ++i) { const int row = (tid + 512 * i) >> 3; int pk = w.i0 - 64 + row; pk = pk < 0 ? 0 : (pk >= w.L ? w.L - 1 : pk);
;         const size_t off = ((size_t)(w.b * 24 + w.hd) * SEQ + (size_t)(w.r * w.L + pk)) * 64 + ch * 8; kv[i] = *(const u32x4*)(Kb + off); vv[i] = *(const u32x4*)(Vb + off); }
; }
; template <bool FUSED> __device__ __forceinline__ void attn_phase(const Args& a, LAS unsigned char* lds, int tid, int lane, int wave) {
;     ...
;         {
;             const int ch = tid & 7;
;             const f32x4 g0 = *(const f32x4*)(a.kw + hd * 64 + ch * 8), g1 = *(const f32x4*)(a.kw + hd * 64 + ch * 8 + 4);
; #pragma unroll
;             for (int i = 0; i < 6; ++i) { const int row = (tid + 512 * i) >> 3;
;                 const float e0 = bflo(kv[i].x), e1 = bfhi(kv[i].x), e2 = bflo(kv[i].y), e3 = bfhi(kv[i].y), e4 = bflo(kv[i].z), e5 = bfhi(kv[i].z), e6 = bflo(kv[i].w), e7 = bfhi(kv[i].w);
;                 float ss = (e0 * e0 + e1 * e1) + (e2 * e2 + e3 * e3) + (e4 * e4 + e5 * e5) + (e6 * e6 + e7 * e7);
;                 ss += dpp_movf<0xB1>(ss); ss += dpp_movf<0x4E>(ss); ss += dpp_movf<0x141>(ss);
;                 const float rk = __builtin_amdgcn_rsqf(ss * (1.f / 64.f) + 1e-6f);
;                 u32x4 wv; wv.x = pk2(e0 * rk * g0.x, e1 * rk * g0.y); wv.y = pk2(e2 * rk * g0.z, e3 * rk * g0.w); wv.z = pk2(e4 * rk * g1.x, e5 * rk * g1.y); wv.w = pk2(e6 * rk * g1.z, e7 * rk * g1.w);
;                 *(LAS u32x4*)(lds + row * KP + ch * 16) = wv;
;                 *(LAS u32x4*)(lds + LDS_VOFF + row * VP + ch * 16) = vv[i];
;                 if (i & 1) __builtin_amdgcn_sched_barrier(0); }
;         }
;         bf16x8 qf[4];
;         {
;             float ss = 0.f;
; #pragma unroll
;             for (int ks = 0; ks < 4; ++ks)
; #pragma unroll
;                 for (int e = 0; e < 4; ++e) { const float lo = bflo(qv[ks][e]), hi = bfhi(qv[ks][e]); ss += lo * lo + hi * hi; }
;             ss += __shfl_xor(ss, 32);
;             const float rq = 0.125f * LOG2E * __builtin_amdgcn_rsqf(ss * (1.f / 64.f) + 1e-6f);
; #pragma unroll
.LBB0_280:
	s_ashr_i32 s6, s67, 5
	s_lshr_b32 s7, s6, 28
	s_add_i32 s7, s6, s7
	s_and_b32 s7, s7, -16
	s_sub_i32 s66, s6, s7
	s_add_i32 s68, s66, 8
	s_ashr_i32 s69, s68, 31
	s_lshl_b64 s[6:7], s[68:69], 2
	s_add_u32 s6, s87, s6
	s_addc_u32 s7, s88, s7
	global_load_dword v222, v147, s[6:7]
	s_waitcnt vmcnt(15)
	ds_write_b128 v177, v[64:67]
	ds_write_b128 v188, v[68:71] offset:55296
	s_waitcnt vmcnt(13)
	ds_write_b128 v189, v[72:75]
	ds_write_b128 v190, v[76:79] offset:55296
	s_waitcnt vmcnt(11)
	ds_write_b128 v191, v[80:83]
	ds_write_b128 v192, v[84:87] offset:55296
	s_waitcnt vmcnt(9)
	ds_write_b128 v193, v[96:99]
	ds_write_b128 v194, v[104:107] offset:55296
	s_waitcnt vmcnt(7)
	ds_write_b128 v195, v[112:115]
	ds_write_b128 v196, v[116:119] offset:55296
	s_waitcnt vmcnt(5)
	ds_write_b128 v197, v[120:123]
	ds_write_b128 v198, v[124:127] offset:55296
	s_add_i32 s69, s67, s54
	s_cmpk_lt_i32 s69, 0x1000
	s_cselect_b64 s[72:73], -1, 0
	s_cmpk_gt_i32 s69, 0xfff
	s_cselect_b64 s[70:71], -1, 0
	s_and_b64 vcc, exec, s[70:71]
	s_waitcnt vmcnt(1)
	s_waitcnt lgkmcnt(0)
	s_barrier
	s_cbranch_vccnz .LBB0_282
	s_ashr_i32 s7, s69, 5
	s_lshr_b32 s8, s7, 28
	s_add_i32 s8, s7, s8
	s_and_b32 s8, s8, -16
	s_sub_i32 s7, s7, s8
	s_add_i32 s7, s7, 8
	s_ashr_i32 s9, s7, 2
	s_and_b32 s9, s9, -2
	s_lshr_b32 s10, 32, s9
	s_and_b32 s6, s69, 31
	s_lshr_b32 s11, 0x2000, s9
	s_sub_i32 s9, 5, s9
	s_add_i32 s10, s10, -1
	s_lshr_b32 s9, s6, s9
	s_and_b32 s6, s10, s6
	s_lshl_b32 s10, s6, 8
	s_add_i32 s12, s11, -1
	s_mul_i32 s9, s9, s11
	s_ashr_i32 s8, s69, 31
	s_lshr_b32 s8, s8, 23
	s_add_i32 s8, s69, s8
	s_ashr_i32 s8, s8, 9
	s_mul_i32 s8, s8, 24
	s_add_i32 s6, s7, s8
	s_ashr_i32 s7, s6, 31
	s_lshl_b64 s[6:7], s[6:7], 20
	s_add_u32 s94, s58, s6
	s_addc_u32 s95, s59, s7
	s_add_u32 s96, s60, s6
	s_addc_u32 s97, s61, s7
	v_add_u32_e32 v68, s10, v155
	v_med3_i32 v68, v68, 0, s12
	v_add_lshl_u32 v68, v68, s9, 7
	v_lshl_or_b32 v68, v144, 1, v68
	global_load_dwordx4 v[64:67], v68, s[94:95]
	global_load_dwordx4 v[68:71], v68, s[96:97]
	v_add_u32_e32 v76, s10, v170
	v_med3_i32 v76, v76, 0, s12
	v_add_lshl_u32 v76, v76, s9, 7
	v_lshl_or_b32 v76, v144, 1, v76
	global_load_dwordx4 v[72:75], v76, s[94:95]
	global_load_dwordx4 v[76:79], v76, s[96:97]
	v_add_u32_e32 v84, s10, v171
	v_med3_i32 v84, v84, 0, s12
	v_add_lshl_u32 v84, v84, s9, 7
	v_lshl_or_b32 v84, v144, 1, v84
	global_load_dwordx4 v[80:83], v84, s[94:95]
	global_load_dwordx4 v[84:87], v84, s[96:97]
	v_add_u32_e32 v104, s10, v172
	v_med3_i32 v104, v104, 0, s12
	v_add_lshl_u32 v104, v104, s9, 7
	v_lshl_or_b32 v104, v144, 1, v104
	global_load_dwordx4 v[96:99], v104, s[94:95]
	global_load_dwordx4 v[104:107], v104, s[96:97]
	v_add_u32_e32 v116, s10, v173
	v_med3_i32 v116, v116, 0, s12
	v_add_lshl_u32 v116, v116, s9, 7
	v_lshl_or_b32 v116, v144, 1, v116
	global_load_dwordx4 v[112:115], v116, s[94:95]
	global_load_dwordx4 v[116:119], v116, s[96:97]
	v_add_u32_e32 v124, s10, v174
	v_med3_i32 v124, v124, 0, s12
	v_add_lshl_u32 v124, v124, s9, 7
	v_lshl_or_b32 v124, v144, 1, v124
	global_load_dwordx4 v[120:123], v124, s[94:95]
	global_load_dwordx4 v[124:127], v124, s[96:97]
	s_and_b32 s7, s66, 7
	s_add_i32 s7, s7, 1
	s_ashr_i32 s6, s68, 2
	s_and_b32 s75, s6, -2
	s_lshr_b32 s6, 32, s75
	v_mov_b32_e32 v48, v175
	ds_read_b128 v[42:45], v199 offset:32
	ds_read_b128 v[38:41], v199
	v_cvt_f32_ubyte0_e32 v32, s7
	s_waitcnt vmcnt(12)
	s_branch .Lattn1_join

; #define LAS __attribute__((address_space(3)))
; __device__ __forceinline__ unsigned pk2(float lo, float hi) { f32x2_t v = {lo, hi}; bf16x2_t b = __builtin_convertvector(v, bf16x2_t); return __builtin_bit_cast(unsigned, b); }
; __device__ __forceinline__ s16x4 trrd(LAS const unsigned char* p) { return __builtin_bit_cast(s16x4, __builtin_amdgcn_ds_read_tr16_b64_v4i16((LAS v4i16_t*)p)); }
; template <bool FUSED> __device__ __forceinline__ void attn_phase(const Args& a, LAS unsigned char* lds, int tid, int lane, int wave) {
;     ...
;         const float bsl = __builtin_amdgcn_exp2f(-(float)(slot + 1)) * (float)w.dil * LOG2E;
;         int tl = 4 * h - l31; asm volatile("" : "+v"(tl));
;         const float tlf = (float)tl;
;         const int lo_i = -iq > -64 ? -iq : -64, hi_i = (L - 1 - iq) < 64 ? (L - 1 - iq) : 64;
;         const float rlo = (float)lo_i, rhi = (float)hi_i;
;         const int wq0 = i0 + 32 * wave;
;         const bool edge = (wq0 < 64) || (wq0 + 32 > L - 64);
;         float sum = 0.f;
;         f32x16 o[2]; o[0] = f32x16{}; o[1] = f32x16{};
; #pragma unroll
;         for (int j = 0; j < 5; ++j) {
;             f32x16 st;
; #pragma unroll
;             for (int i = 0; i < 16; ++i) st[i] = -mb;
;             LAS const unsigned char* kp = lds + (32 * wave + 32 * j + l31) * KP + 16 * h;
; #pragma unroll
;             for (int ks = 0; ks < 4; ++ks) { const bf16x8 kf = *(LAS const bf16x8*)(kp + 32 * ks); st = __builtin_amdgcn_mfma_f32_32x32x16_bf16(kf, qf[ks], st, 0, 0, 0); }
;             sum += attn_tile_exp(st, j, tlf, bsl, rlo, rhi);
; #pragma unroll
;             for (int s2 = 0; s2 < 2; ++s2) { u32x4 pw; pw.x = pk2(st[8 * s2 + 0], st[8 * s2 + 1]); pw.y = pk2(st[8 * s2 + 2], st[8 * s2 + 3]); pw.z = pk2(st[8 * s2 + 4], st[8 * s2 + 5]); pw.w = pk2(st[8 * s2 + 6], st[8 * s2 + 7]);
;                 const bf16x8 pf = __builtin_bit_cast(bf16x8, pw);
;                 LAS const unsigned char* vp = lds + LDS_VOFF + (32 * wave + 32 * j + 16 * s2 + 4 * h + q) * VP + 32 * blk + 8 * p;
; #pragma unroll
;                 for (int dt = 0; dt < 2; ++dt) { const s16x4 lo = trrd(vp + dt * 64), hi = trrd(vp + 8 * VP + dt * 64);
;                     const bf16x8 vf = __builtin_shufflevector(lo, hi, 0, 1, 2, 3, 4, 5, 6, 7);
;                     o[dt] = __builtin_amdgcn_mfma_f32_32x32x16_bf16(vf, pf, o[dt], 0, 0, 0); } }
.Lattn1_join:
	v_xor_b32_e32 v0, 0x80000000, v222
	v_mov_b32_e32 v1, v0
	v_mov_b32_e32 v2, v0
	v_mov_b32_e32 v3, v0
	v_mov_b32_e32 v4, v0
	v_mov_b32_e32 v5, v0
	v_mov_b32_e32 v6, v0
	v_mov_b32_e32 v7, v0
	v_mov_b32_e32 v8, v0
	v_mov_b32_e32 v9, v0
	v_mov_b32_e32 v10, v0
	v_mov_b32_e32 v11, v0
	v_mov_b32_e32 v12, v0
	v_mov_b32_e32 v13, v0
	v_mov_b32_e32 v14, v0
	v_mov_b32_e32 v15, v0
	v_exp_f32_e64 v46, -v32
	s_waitcnt lgkmcnt(0)
	v_mfma_f32_32x32x16_bf16 v[16:31], v[38:41], v[88:91], v[0:15]
	ds_read_b128 v[38:41], v199 offset:64
	s_and_b32 s77, s67, 31
	ds_read_b128 v[32:35], v199 offset:96
	s_add_i32 s6, s6, -1
	s_and_b32 s6, s6, s77
	v_mfma_f32_32x32x16_bf16 v[16:31], v[42:45], v[92:95], v[16:31]
	s_lshr_b32 s76, 0x2000, s75
	v_lshl_add_u32 v168, s6, 8, v145
	s_lshl_b32 s6, 1, s75
	v_sub_u32_e32 v37, 0, v168
	v_cvt_f32_u32_e32 v42, s6
	v_cvt_f32_i32_e32 v225, v48
	v_max_i32_e32 v37, 0xffffffc0, v37
	s_waitcnt lgkmcnt(1)
	v_mfma_f32_32x32x16_bf16 v[16:31], v[38:41], v[100:103], v[16:31]
	v_xad_u32 v38, v168, -1, s76
	v_min_i32_e32 v38, 64, v38
	v_cvt_f32_i32_e32 v169, v37
	v_cvt_f32_i32_e32 v223, v38
	v_mul_f32_e32 v36, v46, v42
	v_mul_f32_e32 v224, 0xbfb8aa3b, v36
	s_waitcnt lgkmcnt(0)
	v_mfma_f32_32x32x16_bf16 v[16:31], v[32:35], v[108:111], v[16:31]
	v_add_f32_e32 v32, 0xc2800000, v225
	v_cmp_nge_f32_e32 vcc, v32, v169
	v_cmp_nle_f32_e64 s[6:7], v32, v223
	s_or_b64 vcc, vcc, s[6:7]
	v_add_f32_e32 v33, 0xc27c0000, v225
	v_cmp_nle_f32_e64 s[6:7], v33, v223
	s_nop 5
	v_fma_f32 v16, v224, |v32|, v16
	v_cndmask_b32_e32 v16, v16, v221, vcc
	v_cmp_nge_f32_e32 vcc, v33, v169
	v_fma_f32 v17, v224, |v33|, v17
	s_or_b64 vcc, vcc, s[6:7]
	v_cndmask_b32_e32 v17, v17, v221, vcc
	v_exp_f32_e32 v33, v17
	v_add_f32_e32 v17, 0xc2780000, v225
	v_cmp_nge_f32_e32 vcc, v17, v169
	v_cmp_nle_f32_e64 s[6:7], v17, v223
	v_fma_f32 v18, v224, |v17|, v18
	s_or_b64 vcc, vcc, s[6:7]
	v_cndmask_b32_e32 v17, v18, v221, vcc
	v_exp_f32_e32 v34, v17
	v_add_f32_e32 v17, 0xc2740000, v225
	v_cmp_nge_f32_e32 vcc, v17, v169
	v_cmp_nle_f32_e64 s[6:7], v17, v223
	v_fma_f32 v18, v224, |v17|, v19
	s_or_b64 vcc, vcc, s[6:7]
	v_cndmask_b32_e32 v17, v18, v221, vcc
	v_exp_f32_e32 v35, v17
	v_add_f32_e32 v17, 0xc2600000, v225
	v_cmp_nge_f32_e32 vcc, v17, v169
	v_cmp_nle_f32_e64 s[6:7], v17, v223
	v_fma_f32 v18, v224, |v17|, v20
	s_or_b64 vcc, vcc, s[6:7]
	v_cndmask_b32_e32 v17, v18, v221, vcc
	v_exp_f32_e32 v36, v17
	v_add_f32_e32 v17, 0xc25c0000, v225
	v_cmp_nge_f32_e32 vcc, v17, v169
	v_cmp_nle_f32_e64 s[6:7], v17, v223
	v_fma_f32 v18, v224, |v17|, v21
	s_or_b64 vcc, vcc, s[6:7]
	v_cndmask_b32_e32 v17, v18, v221, vcc
	v_exp_f32_e32 v37, v17
	v_add_f32_e32 v17, 0xc2580000, v225
	v_cmp_nge_f32_e32 vcc, v17, v169
	v_cmp_nle_f32_e64 s[6:7], v17, v223
	v_fma_f32 v18, v224, |v17|, v22
	s_or_b64 vcc, vcc, s[6:7]
	v_cndmask_b32_e32 v17, v18, v221, vcc
	v_exp_f32_e32 v32, v16
	v_exp_f32_e32 v38, v17
	v_add_f32_e32 v17, 0xc2540000, v225
	v_cmp_nge_f32_e32 vcc, v17, v169
	v_cmp_nle_f32_e64 s[6:7], v17, v223
	v_fma_f32 v18, v224, |v17|, v23
	s_or_b64 vcc, vcc, s[6:7]
	v_cndmask_b32_e32 v17, v18, v221, vcc
	v_add_f32_e32 v16, 0, v32
	v_exp_f32_e32 v23, v17
	v_add_f32_e32 v17, 0xc2400000, v225
	v_add_f32_e32 v16, v33, v16
	v_cmp_nge_f32_e32 vcc, v17, v169
	v_cmp_nle_f32_e64 s[6:7], v17, v223
	v_add_f32_e32 v16, v34, v16
	v_fma_f32 v18, v224, |v17|, v24
	s_or_b64 vcc, vcc, s[6:7]
	v_add_f32_e32 v16, v35, v16
	v_cndmask_b32_e32 v17, v18, v221, vcc
	v_add_f32_e32 v16, v36, v16
	v_exp_f32_e32 v52, v17
	v_add_f32_e32 v16, v37, v16
	v_add_f32_e32 v16, v38, v16
	v_add_f32_e32 v16, v23, v16
	v_add_f32_e32 v60, v52, v16
	v_add_f32_e32 v16, 0xc23c0000, v225
	v_cmp_nge_f32_e32 vcc, v16, v169
	v_cmp_nle_f32_e64 s[6:7], v16, v223
	v_fma_f32 v17, v224, |v16|, v25
	s_or_b64 vcc, vcc, s[6:7]
	v_cndmask_b32_e32 v16, v17, v221, vcc
	v_exp_f32_e32 v61, v16
	v_add_f32_e32 v16, 0xc2380000, v225
	v_cmp_nge_f32_e32 vcc, v16, v169
	v_cmp_nle_f32_e64 s[6:7], v16, v223
	v_fma_f32 v17, v224, |v16|, v26
	s_or_b64 vcc, vcc, s[6:7]
	v_cndmask_b32_e32 v16, v17, v221, vcc
	v_exp_f32_e32 v62, v16
	v_add_f32_e32 v16, 0xc2340000, v225
	v_cmp_nge_f32_e32 vcc, v16, v169
	v_cmp_nle_f32_e64 s[6:7], v16, v223
	v_fma_f32 v17, v224, |v16|, v27
	s_or_b64 vcc, vcc, s[6:7]
	v_cndmask_b32_e32 v16, v17, v221, vcc
	v_exp_f32_e32 v63, v16
	v_add_f32_e32 v16, 0xc2200000, v225
	v_cmp_nge_f32_e32 vcc, v16, v169
	v_cmp_nle_f32_e64 s[6:7], v16, v223
	v_fma_f32 v17, v224, |v16|, v28
	s_or_b64 vcc, vcc, s[6:7]
	v_cndmask_b32_e32 v16, v17, v221, vcc
	v_exp_f32_e32 v226, v16
	v_add_f32_e32 v16, 0xc21c0000, v225
	v_cmp_nge_f32_e32 vcc, v16, v169
	v_cmp_nle_f32_e64 s[6:7], v16, v223
	v_fma_f32 v17, v224, |v16|, v29
	s_or_b64 vcc, vcc, s[6:7]
	v_cndmask_b32_e32 v16, v17, v221, vcc
	v_exp_f32_e32 v227, v16
	v_add_f32_e32 v16, 0xc2180000, v225
	v_cmp_nge_f32_e32 vcc, v16, v169
	v_cmp_nle_f32_e64 s[6:7], v16, v223
	v_fma_f32 v17, v224, |v16|, v30
	s_or_b64 vcc, vcc, s[6:7]
	v_cndmask_b32_e32 v20, v17, v221, vcc
	ds_read_b64_tr_b16 v[16:17], v200 offset:55296
	ds_read_b64_tr_b16 v[18:19], v200 offset:56832
	ds_read_b64_tr_b16 v[26:27], v200 offset:56896
	ds_read_b64_tr_b16 v[24:25], v200 offset:55360
	v_add_f32_e32 v28, 0xc2140000, v225
	v_exp_f32_e32 v228, v20
	v_cvt_pk_bf16_f32 v20, v32, v33
	v_cvt_pk_bf16_f32 v21, v34, v35
	v_cvt_pk_bf16_f32 v22, v36, v37
	v_cvt_pk_bf16_f32 v23, v38, v23
	v_cmp_nge_f32_e32 vcc, v28, v169
	v_cmp_nle_f32_e64 s[6:7], v28, v223
	s_waitcnt lgkmcnt(2)
	v_mfma_f32_32x32x16_bf16 v[32:47], v[16:19], v[20:23], 0
	v_fma_f32 v16, v224, |v28|, v31
	s_or_b64 vcc, vcc, s[6:7]
	v_cndmask_b32_e32 v53, v16, v221, vcc
	ds_read_b64_tr_b16 v[48:49], v200 offset:58368
	ds_read_b64_tr_b16 v[50:51], v200 offset:59904
	v_exp_f32_e32 v229, v53
	ds_read_b64_tr_b16 v[58:59], v200 offset:59968
	ds_read_b64_tr_b16 v[56:57], v200 offset:58432
	v_cvt_pk_bf16_f32 v52, v52, v61
	s_waitcnt lgkmcnt(4)
	v_mfma_f32_32x32x16_bf16 v[16:31], v[24:27], v[20:23], 0
	v_cvt_pk_bf16_f32 v53, v62, v63
	v_cvt_pk_bf16_f32 v54, v226, v227
	v_cvt_pk_bf16_f32 v55, v228, v229
	s_waitcnt lgkmcnt(2)
	s_nop 0
	v_mfma_f32_32x32x16_bf16 v[32:47], v[48:51], v[52:55], v[32:47]
	v_add_f32_e32 v48, v61, v60
	v_add_f32_e32 v48, v62, v48
	v_add_f32_e32 v48, v63, v48
	v_add_f32_e32 v48, v226, v48
	v_add_f32_e32 v48, v227, v48
	v_add_f32_e32 v48, v228, v48
	v_add_f32_e32 v48, v229, v48
	s_waitcnt lgkmcnt(0)
	v_mfma_f32_32x32x16_bf16 v[16:31], v[56:59], v[52:55], v[16:31]
	v_add_f32_e32 v238, 0, v48
	v_cmp_neq_f32_e32 vcc, 0xc2800000, v169
	s_mov_b64 s[6:7], vcc
	v_cmp_neq_f32_e32 vcc, 0x42800000, v223
	s_or_b64 vcc, vcc, s[6:7]
	s_cbranch_vccnz .Lattn1_slow
; #define LAS __attribute__((address_space(3)))
; __device__ __forceinline__ unsigned pk2(float lo, float hi) { f32x2_t v = {lo, hi}; bf16x2_t b = __builtin_convertvector(v, bf16x2_t); return __builtin_bit_cast(unsigned, b); }
; __device__ __forceinline__ s16x4 trrd(LAS const unsigned char* p) { return __builtin_bit_cast(s16x4, __builtin_amdgcn_ds_read_tr16_b64_v4i16((LAS v4i16_t*)p)); }
; __device__ __forceinline__ float attn_tile_exp(f32x16& st, int j, float tlf, float bsl, float rlo, float rhi) {
;     float sum = 0.f;
; #pragma unroll
;     for (int i = 0; i < 16; ++i) { const float tmp = (float)(32 * j - 64 + (i & 3) + 8 * (i >> 2)) + tlf;
;         float arg = __builtin_fmaf(-bsl, __builtin_fabsf(tmp), st[i]);
;         arg = (tmp >= rlo && tmp <= rhi) ? arg : -1.0e30f;
;         const float pe = __builtin_amdgcn_exp2f(arg); st[i] = pe; sum += pe; }
;     return sum;
; }
; template <bool FUSED> __device__ __forceinline__ void attn_phase(const Args& a, LAS unsigned char* lds, int tid, int lane, int wave) {
;     ...
; #pragma unroll
;         for (int j = 0; j < 5; ++j) {
;             f32x16 st;
; #pragma unroll
;             for (int i = 0; i < 16; ++i) st[i] = -mb;
;             LAS const unsigned char* kp = lds + (32 * wave + 32 * j + l31) * KP + 16 * h;
; #pragma unroll
;             for (int ks = 0; ks < 4; ++ks) { const bf16x8 kf = *(LAS const bf16x8*)(kp + 32 * ks); st = __builtin_amdgcn_mfma_f32_32x32x16_bf16(kf, qf[ks], st, 0, 0, 0); }
;             sum += attn_tile_exp(st, j, tlf, bsl, rlo, rhi);
; #pragma unroll
;             for (int s2 = 0; s2 < 2; ++s2) { u32x4 pw; pw.x = pk2(st[8 * s2 + 0], st[8 * s2 + 1]); pw.y = pk2(st[8 * s2 + 2], st[8 * s2 + 3]); pw.z = pk2(st[8 * s2 + 4], st[8 * s2 + 5]); pw.w = pk2(st[8 * s2 + 6], st[8 * s2 + 7]);
;                 const bf16x8 pf = __builtin_bit_cast(bf16x8, pw);
;                 LAS const unsigned char* vp = lds + LDS_VOFF + (32 * wave + 32 * j + 16 * s2 + 4 * h + q) * VP + 32 * blk + 8 * p;
; #pragma unroll
;                 for (int dt = 0; dt < 2; ++dt) { const s16x4 lo = trrd(vp + dt * 64), hi = trrd(vp + 8 * VP + dt * 64);
;                     const bf16x8 vf = __builtin_shufflevector(lo, hi, 0, 1, 2, 3, 4, 5, 6, 7);
;                     o[dt] = __builtin_amdgcn_mfma_f32_32x32x16_bf16(vf, pf, o[dt], 0, 0, 0); } }
	ds_read_b128 v[226:229], v201
	ds_read_b128 v[230:233], v201 offset:32
	v_add_f32_e32 v239, 0xc2000000, v225
	v_add_f32_e32 v240, 0xc1f80000, v225
	s_waitcnt lgkmcnt(1)
	v_mfma_f32_32x32x16_bf16 v[48:63], v[226:229], v[88:91], v[0:15]
	ds_read_b128 v[226:229], v201 offset:64
	ds_read_b128 v[234:237], v201 offset:96
	v_add_f32_e32 v241, 0xc1f00000, v225
	v_add_f32_e32 v242, 0xc1e80000, v225
	s_waitcnt lgkmcnt(2)
	v_mfma_f32_32x32x16_bf16 v[48:63], v[230:233], v[92:95], v[48:63]
	v_add_f32_e32 v230, 0xc1c00000, v225
	v_add_f32_e32 v231, 0xc1b80000, v225
	s_waitcnt lgkmcnt(1)
	v_mfma_f32_32x32x16_bf16 v[48:63], v[226:229], v[100:103], v[48:63]
	s_waitcnt lgkmcnt(0)
	v_mfma_f32_32x32x16_bf16 v[48:63], v[234:237], v[108:111], v[48:63]
	s_nop 11
	v_fma_f32 v48, v224, |v239|, v48
	v_fma_f32 v49, v224, |v240|, v49
	v_fma_f32 v50, v224, |v241|, v50
	v_fma_f32 v51, v224, |v242|, v51
	v_fma_f32 v52, v224, |v230|, v52
	v_fma_f32 v53, v224, |v231|, v53
	v_exp_f32_e32 v227, v49
	v_mov_b32_e32 v49, v53
	v_exp_f32_e32 v231, v49
	v_add_f32_e32 v49, 0xc1b00000, v225
	v_exp_f32_e32 v228, v50
	v_fma_f32 v49, v224, |v49|, v54
	v_exp_f32_e32 v226, v48
	v_exp_f32_e32 v232, v49
	v_add_f32_e32 v49, 0xc1a80000, v225
	v_fma_f32 v49, v224, |v49|, v55
	v_exp_f32_e32 v229, v51
	v_exp_f32_e32 v230, v52
	v_add_f32_e32 v48, 0, v226
	v_exp_f32_e32 v55, v49
	v_add_f32_e32 v49, 0xc1800000, v225
	v_add_f32_e32 v48, v227, v48
	v_add_f32_e32 v48, v228, v48
	v_fma_f32 v49, v224, |v49|, v56
	v_add_f32_e32 v48, v229, v48
	v_add_f32_e32 v48, v230, v48
	v_exp_f32_e32 v233, v49
	v_add_f32_e32 v48, v231, v48
	v_add_f32_e32 v48, v232, v48
	v_add_f32_e32 v48, v55, v48
	v_add_f32_e32 v234, v233, v48
	v_add_f32_e32 v48, 0xc1700000, v225
	v_fma_f32 v48, v224, |v48|, v57
	v_exp_f32_e32 v235, v48
	v_add_f32_e32 v48, 0xc1600000, v225
	v_fma_f32 v48, v224, |v48|, v58
	v_exp_f32_e32 v236, v48
	v_add_f32_e32 v48, 0xc1500000, v225
	v_fma_f32 v48, v224, |v48|, v59
	v_exp_f32_e32 v237, v48
	v_add_f32_e32 v48, 0xc1000000, v225
	v_fma_f32 v48, v224, |v48|, v60
	v_exp_f32_e32 v60, v48
	v_add_f32_e32 v48, 0xc0e00000, v225
	v_fma_f32 v48, v224, |v48|, v61
	v_exp_f32_e32 v61, v48
	v_add_f32_e32 v48, 0xc0c00000, v225
	v_fma_f32 v52, v224, |v48|, v62
	ds_read_b64_tr_b16 v[48:49], v202 offset:55296
	ds_read_b64_tr_b16 v[50:51], v202 offset:56832
	ds_read_b64_tr_b16 v[58:59], v202 offset:56896
	ds_read_b64_tr_b16 v[56:57], v202 offset:55360
	v_exp_f32_e32 v62, v52
	v_add_f32_e32 v239, 0xc0a00000, v225
	v_cvt_pk_bf16_f32 v52, v226, v227
	v_cvt_pk_bf16_f32 v53, v228, v229
	v_cvt_pk_bf16_f32 v54, v230, v231
	v_cvt_pk_bf16_f32 v55, v232, v55
	s_waitcnt lgkmcnt(2)
	s_nop 0
	v_mfma_f32_32x32x16_bf16 v[32:47], v[48:51], v[52:55], v[32:47]
	v_fma_f32 v63, v224, |v239|, v63
	ds_read_b64_tr_b16 v[48:49], v202 offset:58368
	ds_read_b64_tr_b16 v[50:51], v202 offset:59904
	v_exp_f32_e32 v63, v63
	s_waitcnt lgkmcnt(2)
	v_mfma_f32_32x32x16_bf16 v[16:31], v[56:59], v[52:55], v[16:31]
	ds_read_b64_tr_b16 v[58:59], v202 offset:59968
	ds_read_b64_tr_b16 v[56:57], v202 offset:58432
	v_cvt_pk_bf16_f32 v52, v233, v235
	v_cvt_pk_bf16_f32 v53, v236, v237
	v_cvt_pk_bf16_f32 v54, v60, v61
	v_cvt_pk_bf16_f32 v55, v62, v63
	s_waitcnt lgkmcnt(2)
	s_nop 0
	v_mfma_f32_32x32x16_bf16 v[32:47], v[48:51], v[52:55], v[32:47]
	v_add_f32_e32 v48, v235, v234
	v_add_f32_e32 v48, v236, v48
	v_add_f32_e32 v48, v237, v48
	v_add_f32_e32 v48, v60, v48
	v_add_f32_e32 v48, v61, v48
	v_add_f32_e32 v48, v62, v48
	v_add_f32_e32 v48, v63, v48
	s_waitcnt lgkmcnt(0)
	v_mfma_f32_32x32x16_bf16 v[16:31], v[56:59], v[52:55], v[16:31]
	v_add_f32_e32 v238, v238, v48
	ds_read_b128 v[226:229], v203
	ds_read_b128 v[230:233], v203 offset:32
	v_add_f32_e32 v239, 1.0, v225
	s_waitcnt lgkmcnt(1)
	v_mfma_f32_32x32x16_bf16 v[48:63], v[226:229], v[88:91], v[0:15]
	ds_read_b128 v[226:229], v203 offset:64
	ds_read_b128 v[234:237], v203 offset:96
	s_waitcnt lgkmcnt(2)
	v_mfma_f32_32x32x16_bf16 v[48:63], v[230:233], v[92:95], v[48:63]
	v_add_f32_e32 v230, 2.0, v225
	v_add_f32_e32 v231, 0x40400000, v225
	v_add_f32_e32 v232, 0x41000000, v225
	s_waitcnt lgkmcnt(1)
	v_mfma_f32_32x32x16_bf16 v[48:63], v[226:229], v[100:103], v[48:63]
	v_add_f32_e32 v233, 0x41100000, v225
	s_waitcnt lgkmcnt(0)
	v_mfma_f32_32x32x16_bf16 v[48:63], v[234:237], v[108:111], v[48:63]
	s_nop 11
	v_fma_f32 v48, v224, |v225|, v48
	v_fma_f32 v49, v224, |v239|, v49
	v_fma_f32 v50, v224, |v230|, v50
	v_fma_f32 v51, v224, |v231|, v51
	v_fma_f32 v52, v224, |v232|, v52
	v_fma_f32 v53, v224, |v233|, v53
	v_exp_f32_e32 v227, v49
	v_mov_b32_e32 v49, v53
	v_exp_f32_e32 v231, v49
	v_add_f32_e32 v49, 0x41200000, v225
	v_exp_f32_e32 v228, v50
	v_fma_f32 v49, v224, |v49|, v54
	v_exp_f32_e32 v226, v48
	v_exp_f32_e32 v232, v49
	v_add_f32_e32 v49, 0x41300000, v225
	v_fma_f32 v49, v224, |v49|, v55
	v_exp_f32_e32 v229, v51
	v_exp_f32_e32 v230, v52
	v_add_f32_e32 v48, 0, v226
	v_exp_f32_e32 v55, v49
	v_add_f32_e32 v49, 0x41800000, v225
	v_add_f32_e32 v48, v227, v48
	v_add_f32_e32 v48, v228, v48
	v_fma_f32 v49, v224, |v49|, v56
	v_add_f32_e32 v48, v229, v48
	v_add_f32_e32 v48, v230, v48
	v_exp_f32_e32 v233, v49
	v_add_f32_e32 v48, v231, v48
	v_add_f32_e32 v48, v232, v48
	v_add_f32_e32 v48, v55, v48
	v_add_f32_e32 v234, v233, v48
	v_add_f32_e32 v48, 0x41880000, v225
	v_fma_f32 v48, v224, |v48|, v57
	v_exp_f32_e32 v235, v48
	v_add_f32_e32 v48, 0x41900000, v225
	v_fma_f32 v48, v224, |v48|, v58
	v_exp_f32_e32 v236, v48
	v_add_f32_e32 v48, 0x41980000, v225
	v_fma_f32 v48, v224, |v48|, v59
	v_exp_f32_e32 v237, v48
	v_add_f32_e32 v48, 0x41c00000, v225
	v_fma_f32 v48, v224, |v48|, v60
	v_exp_f32_e32 v60, v48
	v_add_f32_e32 v48, 0x41c80000, v225
	v_fma_f32 v48, v224, |v48|, v61
	v_exp_f32_e32 v61, v48
	v_add_f32_e32 v48, 0x41d00000, v225
	v_fma_f32 v52, v224, |v48|, v62
	ds_read_b64_tr_b16 v[48:49], v204 offset:55296
	ds_read_b64_tr_b16 v[50:51], v204 offset:56832
	ds_read_b64_tr_b16 v[58:59], v204 offset:56896
	ds_read_b64_tr_b16 v[56:57], v204 offset:55360
	v_exp_f32_e32 v62, v52
	v_add_f32_e32 v239, 0x41d80000, v225
	v_cvt_pk_bf16_f32 v52, v226, v227
	v_cvt_pk_bf16_f32 v53, v228, v229
	v_cvt_pk_bf16_f32 v54, v230, v231
	v_cvt_pk_bf16_f32 v55, v232, v55
	s_waitcnt lgkmcnt(2)
; #define LAS __attribute__((address_space(3)))
; __device__ __forceinline__ unsigned pk2(float lo, float hi) { f32x2_t v = {lo, hi}; bf16x2_t b = __builtin_convertvector(v, bf16x2_t); return __builtin_bit_cast(unsigned, b); }
; __device__ __forceinline__ s16x4 trrd(LAS const unsigned char* p) { return __builtin_bit_cast(s16x4, __builtin_amdgcn_ds_read_tr16_b64_v4i16((LAS v4i16_t*)p)); }
; __device__ __forceinline__ float attn_tile_exp(f32x16& st, int j, float tlf, float bsl, float rlo, float rhi) {
;     float sum = 0.f;
; #pragma unroll
;     for (int i = 0; i < 16; ++i) { const float tmp = (float)(32 * j - 64 + (i & 3) + 8 * (i >> 2)) + tlf;
;         float arg = __builtin_fmaf(-bsl, __builtin_fabsf(tmp), st[i]);
;         arg = (tmp >= rlo && tmp <= rhi) ? arg : -1.0e30f;
;         const float pe = __builtin_amdgcn_exp2f(arg); st[i] = pe; sum += pe; }
;     return sum;
; }
; template <bool FUSED> __device__ __forceinline__ void attn_phase(const Args& a, LAS unsigned char* lds, int tid, int lane, int wave) {
;     ...
; #pragma unroll
;         for (int j = 0; j < 5; ++j) {
;             f32x16 st;
; #pragma unroll
;             for (int i = 0; i < 16; ++i) st[i] = -mb;
;             LAS const unsigned char* kp = lds + (32 * wave + 32 * j + l31) * KP + 16 * h;
; #pragma unroll
;             for (int ks = 0; ks < 4; ++ks) { const bf16x8 kf = *(LAS const bf16x8*)(kp + 32 * ks); st = __builtin_amdgcn_mfma_f32_32x32x16_bf16(kf, qf[ks], st, 0, 0, 0); }
;             sum += attn_tile_exp(st, j, tlf, bsl, rlo, rhi);
; #pragma unroll
;             for (int s2 = 0; s2 < 2; ++s2) { u32x4 pw; pw.x = pk2(st[8 * s2 + 0], st[8 * s2 + 1]); pw.y = pk2(st[8 * s2 + 2], st[8 * s2 + 3]); pw.z = pk2(st[8 * s2 + 4], st[8 * s2 + 5]); pw.w = pk2(st[8 * s2 + 6], st[8 * s2 + 7]);
;                 const bf16x8 pf = __builtin_bit_cast(bf16x8, pw);
;                 LAS const unsigned char* vp = lds + LDS_VOFF + (32 * wave + 32 * j + 16 * s2 + 4 * h + q) * VP + 32 * blk + 8 * p;
; #pragma unroll
;                 for (int dt = 0; dt < 2; ++dt) { const s16x4 lo = trrd(vp + dt * 64), hi = trrd(vp + 8 * VP + dt * 64);
;                     const bf16x8 vf = __builtin_shufflevector(lo, hi, 0, 1, 2, 3, 4, 5, 6, 7);
;                     o[dt] = __builtin_amdgcn_mfma_f32_32x32x16_bf16(vf, pf, o[dt], 0, 0, 0); } }
;             __builtin_amdgcn_sched_barrier(0);
;         }
	s_nop 0
	v_mfma_f32_32x32x16_bf16 v[32:47], v[48:51], v[52:55], v[32:47]
	v_fma_f32 v63, v224, |v239|, v63
	ds_read_b64_tr_b16 v[48:49], v204 offset:58368
	ds_read_b64_tr_b16 v[50:51], v204 offset:59904
	v_exp_f32_e32 v63, v63
	s_waitcnt lgkmcnt(2)
	v_mfma_f32_32x32x16_bf16 v[16:31], v[56:59], v[52:55], v[16:31]
	ds_read_b64_tr_b16 v[58:59], v204 offset:59968
	ds_read_b64_tr_b16 v[56:57], v204 offset:58432
	v_cvt_pk_bf16_f32 v52, v233, v235
	v_cvt_pk_bf16_f32 v53, v236, v237
	v_cvt_pk_bf16_f32 v54, v60, v61
	v_cvt_pk_bf16_f32 v55, v62, v63
	s_waitcnt lgkmcnt(2)
	s_nop 0
	v_mfma_f32_32x32x16_bf16 v[32:47], v[48:51], v[52:55], v[32:47]
	v_add_f32_e32 v48, v235, v234
	v_add_f32_e32 v48, v236, v48
	v_add_f32_e32 v48, v237, v48
	v_add_f32_e32 v48, v60, v48
	v_add_f32_e32 v48, v61, v48
	v_add_f32_e32 v48, v62, v48
	v_add_f32_e32 v48, v63, v48
	s_waitcnt lgkmcnt(0)
	v_mfma_f32_32x32x16_bf16 v[16:31], v[56:59], v[52:55], v[16:31]
	v_add_f32_e32 v238, v238, v48
	ds_read_b128 v[226:229], v205
	ds_read_b128 v[230:233], v205 offset:32
	v_add_f32_e32 v239, 0x42000000, v225
	v_add_f32_e32 v240, 0x42040000, v225
	s_waitcnt lgkmcnt(1)
	v_mfma_f32_32x32x16_bf16 v[48:63], v[226:229], v[88:91], v[0:15]
	ds_read_b128 v[226:229], v205 offset:64
	ds_read_b128 v[234:237], v205 offset:96
	v_add_f32_e32 v241, 0x42080000, v225
	v_add_f32_e32 v242, 0x420c0000, v225
	s_waitcnt lgkmcnt(2)
	v_mfma_f32_32x32x16_bf16 v[48:63], v[230:233], v[92:95], v[48:63]
	v_add_f32_e32 v230, 0x42200000, v225
	v_add_f32_e32 v231, 0x42240000, v225
	s_waitcnt lgkmcnt(1)
	v_mfma_f32_32x32x16_bf16 v[48:63], v[226:229], v[100:103], v[48:63]
	s_waitcnt lgkmcnt(0)
	v_mfma_f32_32x32x16_bf16 v[48:63], v[234:237], v[108:111], v[48:63]
	s_nop 11
	v_fma_f32 v48, v224, |v239|, v48
	v_fma_f32 v49, v224, |v240|, v49
	v_fma_f32 v50, v224, |v241|, v50
	v_fma_f32 v51, v224, |v242|, v51
	v_fma_f32 v52, v224, |v230|, v52
	v_fma_f32 v53, v224, |v231|, v53
	v_exp_f32_e32 v227, v49
	v_mov_b32_e32 v49, v53
	v_exp_f32_e32 v231, v49
	v_add_f32_e32 v49, 0x42280000, v225
	v_exp_f32_e32 v228, v50
	v_fma_f32 v49, v224, |v49|, v54
	v_exp_f32_e32 v226, v48
	v_exp_f32_e32 v232, v49
	v_add_f32_e32 v49, 0x422c0000, v225
	v_fma_f32 v49, v224, |v49|, v55
	v_exp_f32_e32 v229, v51
	v_exp_f32_e32 v230, v52
	v_add_f32_e32 v48, 0, v226
	v_exp_f32_e32 v55, v49
	v_add_f32_e32 v49, 0x42400000, v225
	v_add_f32_e32 v48, v227, v48
	v_add_f32_e32 v48, v228, v48
	v_fma_f32 v49, v224, |v49|, v56
	v_add_f32_e32 v48, v229, v48
	v_add_f32_e32 v48, v230, v48
	v_exp_f32_e32 v233, v49
	v_add_f32_e32 v48, v231, v48
	v_add_f32_e32 v48, v232, v48
	v_add_f32_e32 v48, v55, v48
	v_add_f32_e32 v234, v233, v48
	v_add_f32_e32 v48, 0x42440000, v225
	v_fma_f32 v48, v224, |v48|, v57
	v_exp_f32_e32 v235, v48
	v_add_f32_e32 v48, 0x42480000, v225
	v_fma_f32 v48, v224, |v48|, v58
	v_exp_f32_e32 v236, v48
	v_add_f32_e32 v48, 0x424c0000, v225
	v_fma_f32 v48, v224, |v48|, v59
	v_exp_f32_e32 v237, v48
	v_add_f32_e32 v48, 0x42600000, v225
	v_fma_f32 v48, v224, |v48|, v60
	v_exp_f32_e32 v60, v48
	v_add_f32_e32 v48, 0x42640000, v225
	v_fma_f32 v48, v224, |v48|, v61
	v_exp_f32_e32 v61, v48
	v_add_f32_e32 v48, 0x42680000, v225
	v_fma_f32 v52, v224, |v48|, v62
	ds_read_b64_tr_b16 v[48:49], v206 offset:55296
	ds_read_b64_tr_b16 v[50:51], v206 offset:56832
	ds_read_b64_tr_b16 v[58:59], v206 offset:56896
	ds_read_b64_tr_b16 v[56:57], v206 offset:55360
	v_exp_f32_e32 v62, v52
	v_add_f32_e32 v239, 0x426c0000, v225
	v_cvt_pk_bf16_f32 v52, v226, v227
	v_cvt_pk_bf16_f32 v53, v228, v229
	v_cvt_pk_bf16_f32 v54, v230, v231
	v_cvt_pk_bf16_f32 v55, v232, v55
	s_waitcnt lgkmcnt(2)
	s_nop 0
	v_mfma_f32_32x32x16_bf16 v[32:47], v[48:51], v[52:55], v[32:47]
	v_fma_f32 v63, v224, |v239|, v63
	ds_read_b64_tr_b16 v[48:49], v206 offset:58368
	ds_read_b64_tr_b16 v[50:51], v206 offset:59904
	v_exp_f32_e32 v63, v63
	s_waitcnt lgkmcnt(2)
	v_mfma_f32_32x32x16_bf16 v[16:31], v[56:59], v[52:55], v[16:31]
	ds_read_b64_tr_b16 v[58:59], v206 offset:59968
	ds_read_b64_tr_b16 v[56:57], v206 offset:58432
	v_cvt_pk_bf16_f32 v52, v233, v235
	v_cvt_pk_bf16_f32 v53, v236, v237
	v_cvt_pk_bf16_f32 v54, v60, v61
	v_cvt_pk_bf16_f32 v55, v62, v63
	s_waitcnt lgkmcnt(2)
	s_nop 0
	v_mfma_f32_32x32x16_bf16 v[32:47], v[48:51], v[52:55], v[32:47]
	v_add_f32_e32 v48, v235, v234
	v_add_f32_e32 v48, v236, v48
	v_add_f32_e32 v48, v237, v48
	v_add_f32_e32 v48, v60, v48
	v_add_f32_e32 v48, v61, v48
	v_add_f32_e32 v48, v62, v48
	v_add_f32_e32 v48, v63, v48
	s_waitcnt lgkmcnt(0)
	v_mfma_f32_32x32x16_bf16 v[16:31], v[56:59], v[52:55], v[16:31]
	v_add_f32_e32 v60, v238, v48
	s_branch .Lattn1_t4
; #define LAS __attribute__((address_space(3)))
; __device__ __forceinline__ unsigned pk2(float lo, float hi) { f32x2_t v = {lo, hi}; bf16x2_t b = __builtin_convertvector(v, bf16x2_t); return __builtin_bit_cast(unsigned, b); }
; __device__ __forceinline__ s16x4 trrd(LAS const unsigned char* p) { return __builtin_bit_cast(s16x4, __builtin_amdgcn_ds_read_tr16_b64_v4i16((LAS v4i16_t*)p)); }
; __device__ __forceinline__ float attn_tile_exp(f32x16& st, int j, float tlf, float bsl, float rlo, float rhi) {
;     float sum = 0.f;
; #pragma unroll
;     for (int i = 0; i < 16; ++i) { const float tmp = (float)(32 * j - 64 + (i & 3) + 8 * (i >> 2)) + tlf;
;         float arg = __builtin_fmaf(-bsl, __builtin_fabsf(tmp), st[i]);
;         arg = (tmp >= rlo && tmp <= rhi) ? arg : -1.0e30f;
;         const float pe = __builtin_amdgcn_exp2f(arg); st[i] = pe; sum += pe; }
;     return sum;
; }
; template <bool FUSED> __device__ __forceinline__ void attn_phase(const Args& a, LAS unsigned char* lds, int tid, int lane, int wave) {
;     ...
; #pragma unroll
;         for (int j = 0; j < 5; ++j) {
;             f32x16 st;
; #pragma unroll
;             for (int i = 0; i < 16; ++i) st[i] = -mb;
;             LAS const unsigned char* kp = lds + (32 * wave + 32 * j + l31) * KP + 16 * h;
; #pragma unroll
;             for (int ks = 0; ks < 4; ++ks) { const bf16x8 kf = *(LAS const bf16x8*)(kp + 32 * ks); st = __builtin_amdgcn_mfma_f32_32x32x16_bf16(kf, qf[ks], st, 0, 0, 0); }
;             sum += attn_tile_exp(st, j, tlf, bsl, rlo, rhi);
; #pragma unroll
;             for (int s2 = 0; s2 < 2; ++s2) { u32x4 pw; pw.x = pk2(st[8 * s2 + 0], st[8 * s2 + 1]); pw.y = pk2(st[8 * s2 + 2], st[8 * s2 + 3]); pw.z = pk2(st[8 * s2 + 4], st[8 * s2 + 5]); pw.w = pk2(st[8 * s2 + 6], st[8 * s2 + 7]);
;                 const bf16x8 pf = __builtin_bit_cast(bf16x8, pw);
;                 LAS const unsigned char* vp = lds + LDS_VOFF + (32 * wave + 32 * j + 16 * s2 + 4 * h + q) * VP + 32 * blk + 8 * p;
; #pragma unroll
;                 for (int dt = 0; dt < 2; ++dt) { const s16x4 lo = trrd(vp + dt * 64), hi = trrd(vp + 8 * VP + dt * 64);
;                     const bf16x8 vf = __builtin_shufflevector(lo, hi, 0, 1, 2, 3, 4, 5, 6, 7);
;                     o[dt] = __builtin_amdgcn_mfma_f32_32x32x16_bf16(vf, pf, o[dt], 0, 0, 0); } }
.Lattn1_slow:
	ds_read_b128 v[226:229], v201
	ds_read_b128 v[230:233], v201 offset:32
	v_add_f32_e32 v239, 0xc2000000, v225
	v_add_f32_e32 v240, 0xc1f80000, v225
	v_cmp_nge_f32_e32 vcc, v239, v169
	s_waitcnt lgkmcnt(1)
	v_mfma_f32_32x32x16_bf16 v[48:63], v[226:229], v[88:91], v[0:15]
	ds_read_b128 v[226:229], v201 offset:64
	ds_read_b128 v[234:237], v201 offset:96
	v_cmp_nle_f32_e64 s[6:7], v239, v223
	v_add_f32_e32 v241, 0xc1f00000, v225
	v_cmp_nge_f32_e64 s[8:9], v240, v169
	v_cmp_nle_f32_e64 s[10:11], v240, v223
	s_or_b64 vcc, vcc, s[6:7]
	v_add_f32_e32 v242, 0xc1e80000, v225
	s_waitcnt lgkmcnt(2)
	v_mfma_f32_32x32x16_bf16 v[48:63], v[230:233], v[92:95], v[48:63]
	v_cmp_nge_f32_e64 s[12:13], v241, v169
	v_cmp_nle_f32_e64 s[14:15], v241, v223
	v_add_f32_e32 v230, 0xc1c00000, v225
	v_cmp_nge_f32_e64 s[16:17], v242, v169
	v_cmp_nle_f32_e64 s[20:21], v242, v223
	v_add_f32_e32 v231, 0xc1b80000, v225
	v_cmp_nge_f32_e64 s[22:23], v230, v169
	s_waitcnt lgkmcnt(1)
	v_mfma_f32_32x32x16_bf16 v[48:63], v[226:229], v[100:103], v[48:63]
	v_cmp_nle_f32_e64 s[24:25], v230, v223
	v_cmp_nge_f32_e64 s[26:27], v231, v169
	v_cmp_nle_f32_e64 s[28:29], v231, v223
	s_waitcnt lgkmcnt(0)
	v_mfma_f32_32x32x16_bf16 v[48:63], v[234:237], v[108:111], v[48:63]
	s_nop 11
	v_fma_f32 v48, v224, |v239|, v48
	v_fma_f32 v49, v224, |v240|, v49
	v_cndmask_b32_e32 v48, v48, v221, vcc
	s_or_b64 vcc, s[8:9], s[10:11]
	v_fma_f32 v50, v224, |v241|, v50
	v_cndmask_b32_e32 v49, v49, v221, vcc
	s_or_b64 vcc, s[12:13], s[14:15]
	v_fma_f32 v51, v224, |v242|, v51
	v_cndmask_b32_e32 v50, v50, v221, vcc
	s_or_b64 vcc, s[16:17], s[20:21]
	v_fma_f32 v52, v224, |v230|, v52
	v_cndmask_b32_e32 v51, v51, v221, vcc
	s_or_b64 vcc, s[22:23], s[24:25]
	v_fma_f32 v53, v224, |v231|, v53
	v_cndmask_b32_e32 v52, v52, v221, vcc
	s_or_b64 vcc, s[26:27], s[28:29]
	v_exp_f32_e32 v227, v49
	v_cndmask_b32_e32 v49, v53, v221, vcc
	v_exp_f32_e32 v231, v49
	v_add_f32_e32 v49, 0xc1b00000, v225
	v_cmp_nge_f32_e32 vcc, v49, v169
	v_cmp_nle_f32_e64 s[6:7], v49, v223
	v_exp_f32_e32 v228, v50
	v_fma_f32 v50, v224, |v49|, v54
	s_or_b64 vcc, vcc, s[6:7]
	v_cndmask_b32_e32 v49, v50, v221, vcc
	v_exp_f32_e32 v226, v48
	v_exp_f32_e32 v232, v49
	v_add_f32_e32 v49, 0xc1a80000, v225
	v_cmp_nge_f32_e32 vcc, v49, v169
	v_cmp_nle_f32_e64 s[6:7], v49, v223
	v_fma_f32 v50, v224, |v49|, v55
	s_or_b64 vcc, vcc, s[6:7]
	v_exp_f32_e32 v229, v51
	v_cndmask_b32_e32 v49, v50, v221, vcc
	v_exp_f32_e32 v230, v52
	v_add_f32_e32 v48, 0, v226
	v_exp_f32_e32 v55, v49
	v_add_f32_e32 v49, 0xc1800000, v225
	v_add_f32_e32 v48, v227, v48
	v_cmp_nge_f32_e32 vcc, v49, v169
	v_cmp_nle_f32_e64 s[6:7], v49, v223
	v_add_f32_e32 v48, v228, v48
	v_fma_f32 v50, v224, |v49|, v56
	s_or_b64 vcc, vcc, s[6:7]
	v_add_f32_e32 v48, v229, v48
	v_cndmask_b32_e32 v49, v50, v221, vcc
	v_add_f32_e32 v48, v230, v48
	v_exp_f32_e32 v233, v49
	v_add_f32_e32 v48, v231, v48
	v_add_f32_e32 v48, v232, v48
	v_add_f32_e32 v48, v55, v48
	v_add_f32_e32 v234, v233, v48
	v_add_f32_e32 v48, 0xc1700000, v225
	v_cmp_nge_f32_e32 vcc, v48, v169
	v_cmp_nle_f32_e64 s[6:7], v48, v223
	v_fma_f32 v49, v224, |v48|, v57
	s_or_b64 vcc, vcc, s[6:7]
	v_cndmask_b32_e32 v48, v49, v221, vcc
	v_exp_f32_e32 v235, v48
	v_add_f32_e32 v48, 0xc1600000, v225
	v_cmp_nge_f32_e32 vcc, v48, v169
	v_cmp_nle_f32_e64 s[6:7], v48, v223
	v_fma_f32 v49, v224, |v48|, v58
	s_or_b64 vcc, vcc, s[6:7]
	v_cndmask_b32_e32 v48, v49, v221, vcc
	v_exp_f32_e32 v236, v48
	v_add_f32_e32 v48, 0xc1500000, v225
	v_cmp_nge_f32_e32 vcc, v48, v169
	v_cmp_nle_f32_e64 s[6:7], v48, v223
	v_fma_f32 v49, v224, |v48|, v59
	s_or_b64 vcc, vcc, s[6:7]
	v_cndmask_b32_e32 v48, v49, v221, vcc
	v_exp_f32_e32 v237, v48
	v_add_f32_e32 v48, 0xc1000000, v225
	v_cmp_nge_f32_e32 vcc, v48, v169
	v_cmp_nle_f32_e64 s[6:7], v48, v223
	v_fma_f32 v49, v224, |v48|, v60
	s_or_b64 vcc, vcc, s[6:7]
	v_cndmask_b32_e32 v48, v49, v221, vcc
	v_exp_f32_e32 v60, v48
	v_add_f32_e32 v48, 0xc0e00000, v225
	v_cmp_nge_f32_e32 vcc, v48, v169
	v_cmp_nle_f32_e64 s[6:7], v48, v223
	v_fma_f32 v49, v224, |v48|, v61
	s_or_b64 vcc, vcc, s[6:7]
	v_cndmask_b32_e32 v48, v49, v221, vcc
	v_exp_f32_e32 v61, v48
	v_add_f32_e32 v48, 0xc0c00000, v225
	v_cmp_nge_f32_e32 vcc, v48, v169
	v_cmp_nle_f32_e64 s[6:7], v48, v223
	v_fma_f32 v49, v224, |v48|, v62
	s_or_b64 vcc, vcc, s[6:7]
	v_cndmask_b32_e32 v52, v49, v221, vcc
	ds_read_b64_tr_b16 v[48:49], v202 offset:55296
	ds_read_b64_tr_b16 v[50:51], v202 offset:56832
	ds_read_b64_tr_b16 v[58:59], v202 offset:56896
	ds_read_b64_tr_b16 v[56:57], v202 offset:55360
	v_exp_f32_e32 v62, v52
	v_add_f32_e32 v239, 0xc0a00000, v225
	v_cvt_pk_bf16_f32 v52, v226, v227
	v_cvt_pk_bf16_f32 v53, v228, v229
	v_cvt_pk_bf16_f32 v54, v230, v231
	v_cvt_pk_bf16_f32 v55, v232, v55
	v_cmp_nge_f32_e32 vcc, v239, v169
	v_cmp_nle_f32_e64 s[6:7], v239, v223
	s_waitcnt lgkmcnt(2)
	v_mfma_f32_32x32x16_bf16 v[32:47], v[48:51], v[52:55], v[32:47]
	v_fma_f32 v48, v224, |v239|, v63
	s_or_b64 vcc, vcc, s[6:7]
	v_cndmask_b32_e32 v63, v48, v221, vcc
	ds_read_b64_tr_b16 v[48:49], v202 offset:58368
	ds_read_b64_tr_b16 v[50:51], v202 offset:59904
	v_exp_f32_e32 v63, v63
	s_waitcnt lgkmcnt(2)
	v_mfma_f32_32x32x16_bf16 v[16:31], v[56:59], v[52:55], v[16:31]
	ds_read_b64_tr_b16 v[58:59], v202 offset:59968
	ds_read_b64_tr_b16 v[56:57], v202 offset:58432
	v_cvt_pk_bf16_f32 v52, v233, v235
	v_cvt_pk_bf16_f32 v53, v236, v237
	v_cvt_pk_bf16_f32 v54, v60, v61
	v_cvt_pk_bf16_f32 v55, v62, v63
	s_waitcnt lgkmcnt(2)
	s_nop 0
	v_mfma_f32_32x32x16_bf16 v[32:47], v[48:51], v[52:55], v[32:47]
	v_add_f32_e32 v48, v235, v234
	v_add_f32_e32 v48, v236, v48
	v_add_f32_e32 v48, v237, v48
	v_add_f32_e32 v48, v60, v48
	v_add_f32_e32 v48, v61, v48
	v_add_f32_e32 v48, v62, v48
	v_add_f32_e32 v48, v63, v48
	s_waitcnt lgkmcnt(0)
; #define LAS __attribute__((address_space(3)))
; __device__ __forceinline__ unsigned pk2(float lo, float hi) { f32x2_t v = {lo, hi}; bf16x2_t b = __builtin_convertvector(v, bf16x2_t); return __builtin_bit_cast(unsigned, b); }
; __device__ __forceinline__ s16x4 trrd(LAS const unsigned char* p) { return __builtin_bit_cast(s16x4, __builtin_amdgcn_ds_read_tr16_b64_v4i16((LAS v4i16_t*)p)); }
; __device__ __forceinline__ float attn_tile_exp(f32x16& st, int j, float tlf, float bsl, float rlo, float rhi) {
;     float sum = 0.f;
; #pragma unroll
;     for (int i = 0; i < 16; ++i) { const float tmp = (float)(32 * j - 64 + (i & 3) + 8 * (i >> 2)) + tlf;
;         float arg = __builtin_fmaf(-bsl, __builtin_fabsf(tmp), st[i]);
;         arg = (tmp >= rlo && tmp <= rhi) ? arg : -1.0e30f;
;         const float pe = __builtin_amdgcn_exp2f(arg); st[i] = pe; sum += pe; }
;     return sum;
; }
; template <bool FUSED> __device__ __forceinline__ void attn_phase(const Args& a, LAS unsigned char* lds, int tid, int lane, int wave) {
;     ...
; #pragma unroll
;         for (int j = 0; j < 5; ++j) {
;             f32x16 st;
; #pragma unroll
;             for (int i = 0; i < 16; ++i) st[i] = -mb;
;             LAS const unsigned char* kp = lds + (32 * wave + 32 * j + l31) * KP + 16 * h;
; #pragma unroll
;             for (int ks = 0; ks < 4; ++ks) { const bf16x8 kf = *(LAS const bf16x8*)(kp + 32 * ks); st = __builtin_amdgcn_mfma_f32_32x32x16_bf16(kf, qf[ks], st, 0, 0, 0); }
;             sum += attn_tile_exp(st, j, tlf, bsl, rlo, rhi);
; #pragma unroll
;             for (int s2 = 0; s2 < 2; ++s2) { u32x4 pw; pw.x = pk2(st[8 * s2 + 0], st[8 * s2 + 1]); pw.y = pk2(st[8 * s2 + 2], st[8 * s2 + 3]); pw.z = pk2(st[8 * s2 + 4], st[8 * s2 + 5]); pw.w = pk2(st[8 * s2 + 6], st[8 * s2 + 7]);
;                 const bf16x8 pf = __builtin_bit_cast(bf16x8, pw);
;                 LAS const unsigned char* vp = lds + LDS_VOFF + (32 * wave + 32 * j + 16 * s2 + 4 * h + q) * VP + 32 * blk + 8 * p;
; #pragma unroll
;                 for (int dt = 0; dt < 2; ++dt) { const s16x4 lo = trrd(vp + dt * 64), hi = trrd(vp + 8 * VP + dt * 64);
;                     const bf16x8 vf = __builtin_shufflevector(lo, hi, 0, 1, 2, 3, 4, 5, 6, 7);
;                     o[dt] = __builtin_amdgcn_mfma_f32_32x32x16_bf16(vf, pf, o[dt], 0, 0, 0); } }
	v_mfma_f32_32x32x16_bf16 v[16:31], v[56:59], v[52:55], v[16:31]
	v_add_f32_e32 v238, v238, v48
	ds_read_b128 v[226:229], v203
	ds_read_b128 v[230:233], v203 offset:32
	v_cmp_nge_f32_e32 vcc, v225, v169
	v_cmp_nle_f32_e64 s[6:7], v225, v223
	v_add_f32_e32 v239, 1.0, v225
	s_waitcnt lgkmcnt(1)
	v_mfma_f32_32x32x16_bf16 v[48:63], v[226:229], v[88:91], v[0:15]
	ds_read_b128 v[226:229], v203 offset:64
	ds_read_b128 v[234:237], v203 offset:96
	v_cmp_nge_f32_e64 s[8:9], v239, v169
	v_cmp_nle_f32_e64 s[10:11], v239, v223
	s_or_b64 vcc, vcc, s[6:7]
	s_waitcnt lgkmcnt(2)
	v_mfma_f32_32x32x16_bf16 v[48:63], v[230:233], v[92:95], v[48:63]
	v_add_f32_e32 v230, 2.0, v225
	v_add_f32_e32 v231, 0x40400000, v225
	v_cmp_nge_f32_e64 s[12:13], v230, v169
	v_cmp_nle_f32_e64 s[14:15], v230, v223
	v_add_f32_e32 v232, 0x41000000, v225
	v_cmp_nge_f32_e64 s[16:17], v231, v169
	v_cmp_nle_f32_e64 s[20:21], v231, v223
	s_waitcnt lgkmcnt(1)
	v_mfma_f32_32x32x16_bf16 v[48:63], v[226:229], v[100:103], v[48:63]
	v_add_f32_e32 v233, 0x41100000, v225
	v_cmp_nge_f32_e64 s[22:23], v232, v169
	v_cmp_nle_f32_e64 s[24:25], v232, v223
	v_cmp_nge_f32_e64 s[26:27], v233, v169
	v_cmp_nle_f32_e64 s[28:29], v233, v223
	s_waitcnt lgkmcnt(0)
	v_mfma_f32_32x32x16_bf16 v[48:63], v[234:237], v[108:111], v[48:63]
	s_nop 11
	v_fma_f32 v48, v224, |v225|, v48
	v_fma_f32 v49, v224, |v239|, v49
	v_cndmask_b32_e32 v48, v48, v221, vcc
	s_or_b64 vcc, s[8:9], s[10:11]
	v_fma_f32 v50, v224, |v230|, v50
	v_cndmask_b32_e32 v49, v49, v221, vcc
	s_or_b64 vcc, s[12:13], s[14:15]
	v_fma_f32 v51, v224, |v231|, v51
	v_cndmask_b32_e32 v50, v50, v221, vcc
	s_or_b64 vcc, s[16:17], s[20:21]
	v_fma_f32 v52, v224, |v232|, v52
	v_cndmask_b32_e32 v51, v51, v221, vcc
	s_or_b64 vcc, s[22:23], s[24:25]
	v_fma_f32 v53, v224, |v233|, v53
	v_cndmask_b32_e32 v52, v52, v221, vcc
	s_or_b64 vcc, s[26:27], s[28:29]
	v_exp_f32_e32 v227, v49
	v_cndmask_b32_e32 v49, v53, v221, vcc
	v_exp_f32_e32 v231, v49
	v_add_f32_e32 v49, 0x41200000, v225
	v_cmp_nge_f32_e32 vcc, v49, v169
	v_cmp_nle_f32_e64 s[6:7], v49, v223
	v_exp_f32_e32 v228, v50
	v_fma_f32 v50, v224, |v49|, v54
	s_or_b64 vcc, vcc, s[6:7]
	v_cndmask_b32_e32 v49, v50, v221, vcc
	v_exp_f32_e32 v226, v48
	v_exp_f32_e32 v232, v49
	v_add_f32_e32 v49, 0x41300000, v225
	v_cmp_nge_f32_e32 vcc, v49, v169
	v_cmp_nle_f32_e64 s[6:7], v49, v223
	v_fma_f32 v50, v224, |v49|, v55
	s_or_b64 vcc, vcc, s[6:7]
	v_exp_f32_e32 v229, v51
	v_cndmask_b32_e32 v49, v50, v221, vcc
	v_exp_f32_e32 v230, v52
	v_add_f32_e32 v48, 0, v226
	v_exp_f32_e32 v55, v49
	v_add_f32_e32 v49, 0x41800000, v225
	v_add_f32_e32 v48, v227, v48
	v_cmp_nge_f32_e32 vcc, v49, v169
	v_cmp_nle_f32_e64 s[6:7], v49, v223
	v_add_f32_e32 v48, v228, v48
	v_fma_f32 v50, v224, |v49|, v56
	s_or_b64 vcc, vcc, s[6:7]
	v_add_f32_e32 v48, v229, v48
	v_cndmask_b32_e32 v49, v50, v221, vcc
	v_add_f32_e32 v48, v230, v48
	v_exp_f32_e32 v233, v49
	v_add_f32_e32 v48, v231, v48
	v_add_f32_e32 v48, v232, v48
	v_add_f32_e32 v48, v55, v48
	v_add_f32_e32 v234, v233, v48
	v_add_f32_e32 v48, 0x41880000, v225
	v_cmp_nge_f32_e32 vcc, v48, v169
	v_cmp_nle_f32_e64 s[6:7], v48, v223
	v_fma_f32 v49, v224, |v48|, v57
	s_or_b64 vcc, vcc, s[6:7]
	v_cndmask_b32_e32 v48, v49, v221, vcc
	v_exp_f32_e32 v235, v48
	v_add_f32_e32 v48, 0x41900000, v225
	v_cmp_nge_f32_e32 vcc, v48, v169
	v_cmp_nle_f32_e64 s[6:7], v48, v223
	v_fma_f32 v49, v224, |v48|, v58
	s_or_b64 vcc, vcc, s[6:7]
	v_cndmask_b32_e32 v48, v49, v221, vcc
	v_exp_f32_e32 v236, v48
	v_add_f32_e32 v48, 0x41980000, v225
	v_cmp_nge_f32_e32 vcc, v48, v169
	v_cmp_nle_f32_e64 s[6:7], v48, v223
	v_fma_f32 v49, v224, |v48|, v59
	s_or_b64 vcc, vcc, s[6:7]
	v_cndmask_b32_e32 v48, v49, v221, vcc
	v_exp_f32_e32 v237, v48
	v_add_f32_e32 v48, 0x41c00000, v225
	v_cmp_nge_f32_e32 vcc, v48, v169
	v_cmp_nle_f32_e64 s[6:7], v48, v223
	v_fma_f32 v49, v224, |v48|, v60
	s_or_b64 vcc, vcc, s[6:7]
	v_cndmask_b32_e32 v48, v49, v221, vcc
	v_exp_f32_e32 v60, v48
	v_add_f32_e32 v48, 0x41c80000, v225
	v_cmp_nge_f32_e32 vcc, v48, v169
	v_cmp_nle_f32_e64 s[6:7], v48, v223
	v_fma_f32 v49, v224, |v48|, v61
	s_or_b64 vcc, vcc, s[6:7]
	v_cndmask_b32_e32 v48, v49, v221, vcc
	v_exp_f32_e32 v61, v48
	v_add_f32_e32 v48, 0x41d00000, v225
	v_cmp_nge_f32_e32 vcc, v48, v169
	v_cmp_nle_f32_e64 s[6:7], v48, v223
	v_fma_f32 v49, v224, |v48|, v62
	s_or_b64 vcc, vcc, s[6:7]
	v_cndmask_b32_e32 v52, v49, v221, vcc
	ds_read_b64_tr_b16 v[48:49], v204 offset:55296
	ds_read_b64_tr_b16 v[50:51], v204 offset:56832
	ds_read_b64_tr_b16 v[58:59], v204 offset:56896
	ds_read_b64_tr_b16 v[56:57], v204 offset:55360
	v_exp_f32_e32 v62, v52
	v_add_f32_e32 v239, 0x41d80000, v225
	v_cvt_pk_bf16_f32 v52, v226, v227
	v_cvt_pk_bf16_f32 v53, v228, v229
	v_cvt_pk_bf16_f32 v54, v230, v231
	v_cvt_pk_bf16_f32 v55, v232, v55
	v_cmp_nge_f32_e32 vcc, v239, v169
	v_cmp_nle_f32_e64 s[6:7], v239, v223
	s_waitcnt lgkmcnt(2)
	v_mfma_f32_32x32x16_bf16 v[32:47], v[48:51], v[52:55], v[32:47]
	v_fma_f32 v48, v224, |v239|, v63
	s_or_b64 vcc, vcc, s[6:7]
	v_cndmask_b32_e32 v63, v48, v221, vcc
	ds_read_b64_tr_b16 v[48:49], v204 offset:58368
	ds_read_b64_tr_b16 v[50:51], v204 offset:59904
	v_exp_f32_e32 v63, v63
	s_waitcnt lgkmcnt(2)
	v_mfma_f32_32x32x16_bf16 v[16:31], v[56:59], v[52:55], v[16:31]
	ds_read_b64_tr_b16 v[58:59], v204 offset:59968
	ds_read_b64_tr_b16 v[56:57], v204 offset:58432
	v_cvt_pk_bf16_f32 v52, v233, v235
	v_cvt_pk_bf16_f32 v53, v236, v237
	v_cvt_pk_bf16_f32 v54, v60, v61
	v_cvt_pk_bf16_f32 v55, v62, v63
	s_waitcnt lgkmcnt(2)
; #define LAS __attribute__((address_space(3)))
; __device__ __forceinline__ unsigned pk2(float lo, float hi) { f32x2_t v = {lo, hi}; bf16x2_t b = __builtin_convertvector(v, bf16x2_t); return __builtin_bit_cast(unsigned, b); }
; __device__ __forceinline__ s16x4 trrd(LAS const unsigned char* p) { return __builtin_bit_cast(s16x4, __builtin_amdgcn_ds_read_tr16_b64_v4i16((LAS v4i16_t*)p)); }
; __device__ __forceinline__ float attn_tile_exp(f32x16& st, int j, float tlf, float bsl, float rlo, float rhi) {
;     float sum = 0.f;
; #pragma unroll
;     for (int i = 0; i < 16; ++i) { const float tmp = (float)(32 * j - 64 + (i & 3) + 8 * (i >> 2)) + tlf;
;         float arg = __builtin_fmaf(-bsl, __builtin_fabsf(tmp), st[i]);
;         arg = (tmp >= rlo && tmp <= rhi) ? arg : -1.0e30f;
;         const float pe = __builtin_amdgcn_exp2f(arg); st[i] = pe; sum += pe; }
;     return sum;
; }
; template <bool FUSED> __device__ __forceinline__ void attn_phase(const Args& a, LAS unsigned char* lds, int tid, int lane, int wave) {
;     ...
; #pragma unroll
;         for (int j = 0; j < 5; ++j) {
;             f32x16 st;
; #pragma unroll
;             for (int i = 0; i < 16; ++i) st[i] = -mb;
;             LAS const unsigned char* kp = lds + (32 * wave + 32 * j + l31) * KP + 16 * h;
; #pragma unroll
;             for (int ks = 0; ks < 4; ++ks) { const bf16x8 kf = *(LAS const bf16x8*)(kp + 32 * ks); st = __builtin_amdgcn_mfma_f32_32x32x16_bf16(kf, qf[ks], st, 0, 0, 0); }
;             sum += attn_tile_exp(st, j, tlf, bsl, rlo, rhi);
; #pragma unroll
;             for (int s2 = 0; s2 < 2; ++s2) { u32x4 pw; pw.x = pk2(st[8 * s2 + 0], st[8 * s2 + 1]); pw.y = pk2(st[8 * s2 + 2], st[8 * s2 + 3]); pw.z = pk2(st[8 * s2 + 4], st[8 * s2 + 5]); pw.w = pk2(st[8 * s2 + 6], st[8 * s2 + 7]);
;                 const bf16x8 pf = __builtin_bit_cast(bf16x8, pw);
;                 LAS const unsigned char* vp = lds + LDS_VOFF + (32 * wave + 32 * j + 16 * s2 + 4 * h + q) * VP + 32 * blk + 8 * p;
; #pragma unroll
;                 for (int dt = 0; dt < 2; ++dt) { const s16x4 lo = trrd(vp + dt * 64), hi = trrd(vp + 8 * VP + dt * 64);
;                     const bf16x8 vf = __builtin_shufflevector(lo, hi, 0, 1, 2, 3, 4, 5, 6, 7);
;                     o[dt] = __builtin_amdgcn_mfma_f32_32x32x16_bf16(vf, pf, o[dt], 0, 0, 0); } }
;             __builtin_amdgcn_sched_barrier(0);
;         }
	s_nop 0
	v_mfma_f32_32x32x16_bf16 v[32:47], v[48:51], v[52:55], v[32:47]
	v_add_f32_e32 v48, v235, v234
	v_add_f32_e32 v48, v236, v48
	v_add_f32_e32 v48, v237, v48
	v_add_f32_e32 v48, v60, v48
	v_add_f32_e32 v48, v61, v48
	v_add_f32_e32 v48, v62, v48
	v_add_f32_e32 v48, v63, v48
	s_waitcnt lgkmcnt(0)
	v_mfma_f32_32x32x16_bf16 v[16:31], v[56:59], v[52:55], v[16:31]
	v_add_f32_e32 v238, v238, v48
	ds_read_b128 v[226:229], v205
	ds_read_b128 v[230:233], v205 offset:32
	v_add_f32_e32 v239, 0x42000000, v225
	v_add_f32_e32 v240, 0x42040000, v225
	v_cmp_nge_f32_e32 vcc, v239, v169
	s_waitcnt lgkmcnt(1)
	v_mfma_f32_32x32x16_bf16 v[48:63], v[226:229], v[88:91], v[0:15]
	ds_read_b128 v[226:229], v205 offset:64
	ds_read_b128 v[234:237], v205 offset:96
	v_cmp_nle_f32_e64 s[6:7], v239, v223
	v_add_f32_e32 v241, 0x42080000, v225
	v_cmp_nge_f32_e64 s[8:9], v240, v169
	v_cmp_nle_f32_e64 s[10:11], v240, v223
	s_or_b64 vcc, vcc, s[6:7]
	v_add_f32_e32 v242, 0x420c0000, v225
	s_waitcnt lgkmcnt(2)
	v_mfma_f32_32x32x16_bf16 v[48:63], v[230:233], v[92:95], v[48:63]
	v_cmp_nge_f32_e64 s[12:13], v241, v169
	v_cmp_nle_f32_e64 s[14:15], v241, v223
	v_add_f32_e32 v230, 0x42200000, v225
	v_cmp_nge_f32_e64 s[16:17], v242, v169
	v_cmp_nle_f32_e64 s[20:21], v242, v223
	v_add_f32_e32 v231, 0x42240000, v225
	v_cmp_nge_f32_e64 s[22:23], v230, v169
	s_waitcnt lgkmcnt(1)
	v_mfma_f32_32x32x16_bf16 v[48:63], v[226:229], v[100:103], v[48:63]
	v_cmp_nle_f32_e64 s[24:25], v230, v223
	v_cmp_nge_f32_e64 s[26:27], v231, v169
	v_cmp_nle_f32_e64 s[28:29], v231, v223
	s_waitcnt lgkmcnt(0)
	v_mfma_f32_32x32x16_bf16 v[48:63], v[234:237], v[108:111], v[48:63]
	s_nop 11
	v_fma_f32 v48, v224, |v239|, v48
	v_fma_f32 v49, v224, |v240|, v49
	v_cndmask_b32_e32 v48, v48, v221, vcc
	s_or_b64 vcc, s[8:9], s[10:11]
	v_fma_f32 v50, v224, |v241|, v50
	v_cndmask_b32_e32 v49, v49, v221, vcc
	s_or_b64 vcc, s[12:13], s[14:15]
	v_fma_f32 v51, v224, |v242|, v51
	v_cndmask_b32_e32 v50, v50, v221, vcc
	s_or_b64 vcc, s[16:17], s[20:21]
	v_fma_f32 v52, v224, |v230|, v52
	v_cndmask_b32_e32 v51, v51, v221, vcc
	s_or_b64 vcc, s[22:23], s[24:25]
	v_fma_f32 v53, v224, |v231|, v53
	v_cndmask_b32_e32 v52, v52, v221, vcc
	s_or_b64 vcc, s[26:27], s[28:29]
	v_exp_f32_e32 v227, v49
	v_cndmask_b32_e32 v49, v53, v221, vcc
	v_exp_f32_e32 v231, v49
	v_add_f32_e32 v49, 0x42280000, v225
	v_cmp_nge_f32_e32 vcc, v49, v169
	v_cmp_nle_f32_e64 s[6:7], v49, v223
	v_exp_f32_e32 v228, v50
	v_fma_f32 v50, v224, |v49|, v54
	s_or_b64 vcc, vcc, s[6:7]
	v_cndmask_b32_e32 v49, v50, v221, vcc
	v_exp_f32_e32 v226, v48
	v_exp_f32_e32 v232, v49
	v_add_f32_e32 v49, 0x422c0000, v225
	v_cmp_nge_f32_e32 vcc, v49, v169
	v_cmp_nle_f32_e64 s[6:7], v49, v223
	v_fma_f32 v50, v224, |v49|, v55
	s_or_b64 vcc, vcc, s[6:7]
	v_exp_f32_e32 v229, v51
	v_cndmask_b32_e32 v49, v50, v221, vcc
	v_exp_f32_e32 v230, v52
	v_add_f32_e32 v48, 0, v226
	v_exp_f32_e32 v55, v49
	v_add_f32_e32 v49, 0x42400000, v225
	v_add_f32_e32 v48, v227, v48
	v_cmp_nge_f32_e32 vcc, v49, v169
	v_cmp_nle_f32_e64 s[6:7], v49, v223
	v_add_f32_e32 v48, v228, v48
	v_fma_f32 v50, v224, |v49|, v56
	s_or_b64 vcc, vcc, s[6:7]
	v_add_f32_e32 v48, v229, v48
	v_cndmask_b32_e32 v49, v50, v221, vcc
	v_add_f32_e32 v48, v230, v48
	v_exp_f32_e32 v233, v49
	v_add_f32_e32 v48, v231, v48
	v_add_f32_e32 v48, v232, v48
	v_add_f32_e32 v48, v55, v48
	v_add_f32_e32 v234, v233, v48
	v_add_f32_e32 v48, 0x42440000, v225
	v_cmp_nge_f32_e32 vcc, v48, v169
	v_cmp_nle_f32_e64 s[6:7], v48, v223
	v_fma_f32 v49, v224, |v48|, v57
	s_or_b64 vcc, vcc, s[6:7]
	v_cndmask_b32_e32 v48, v49, v221, vcc
	v_exp_f32_e32 v235, v48
	v_add_f32_e32 v48, 0x42480000, v225
	v_cmp_nge_f32_e32 vcc, v48, v169
	v_cmp_nle_f32_e64 s[6:7], v48, v223
	v_fma_f32 v49, v224, |v48|, v58
	s_or_b64 vcc, vcc, s[6:7]
	v_cndmask_b32_e32 v48, v49, v221, vcc
	v_exp_f32_e32 v236, v48
	v_add_f32_e32 v48, 0x424c0000, v225
	v_cmp_nge_f32_e32 vcc, v48, v169
	v_cmp_nle_f32_e64 s[6:7], v48, v223
	v_fma_f32 v49, v224, |v48|, v59
	s_or_b64 vcc, vcc, s[6:7]
	v_cndmask_b32_e32 v48, v49, v221, vcc
	v_exp_f32_e32 v237, v48
	v_add_f32_e32 v48, 0x42600000, v225
	v_cmp_nge_f32_e32 vcc, v48, v169
	v_cmp_nle_f32_e64 s[6:7], v48, v223
	v_fma_f32 v49, v224, |v48|, v60
	s_or_b64 vcc, vcc, s[6:7]
	v_cndmask_b32_e32 v48, v49, v221, vcc
	v_exp_f32_e32 v60, v48
	v_add_f32_e32 v48, 0x42640000, v225
	v_cmp_nge_f32_e32 vcc, v48, v169
	v_cmp_nle_f32_e64 s[6:7], v48, v223
	v_fma_f32 v49, v224, |v48|, v61
	s_or_b64 vcc, vcc, s[6:7]
	v_cndmask_b32_e32 v48, v49, v221, vcc
	v_exp_f32_e32 v61, v48
	v_add_f32_e32 v48, 0x42680000, v225
	v_cmp_nge_f32_e32 vcc, v48, v169
	v_cmp_nle_f32_e64 s[6:7], v48, v223
	v_fma_f32 v49, v224, |v48|, v62
	s_or_b64 vcc, vcc, s[6:7]
	v_cndmask_b32_e32 v52, v49, v221, vcc
	ds_read_b64_tr_b16 v[48:49], v206 offset:55296
	ds_read_b64_tr_b16 v[50:51], v206 offset:56832
	ds_read_b64_tr_b16 v[58:59], v206 offset:56896
	ds_read_b64_tr_b16 v[56:57], v206 offset:55360
	v_exp_f32_e32 v62, v52
	v_add_f32_e32 v239, 0x426c0000, v225
	v_cvt_pk_bf16_f32 v52, v226, v227
	v_cvt_pk_bf16_f32 v53, v228, v229
	v_cvt_pk_bf16_f32 v54, v230, v231
	v_cvt_pk_bf16_f32 v55, v232, v55
	v_cmp_nge_f32_e32 vcc, v239, v169
	v_cmp_nle_f32_e64 s[6:7], v239, v223
	s_waitcnt lgkmcnt(2)
	v_mfma_f32_32x32x16_bf16 v[32:47], v[48:51], v[52:55], v[32:47]
	v_fma_f32 v48, v224, |v239|, v63
	s_or_b64 vcc, vcc, s[6:7]
	v_cndmask_b32_e32 v63, v48, v221, vcc
	ds_read_b64_tr_b16 v[48:49], v206 offset:58368
	ds_read_b64_tr_b16 v[50:51], v206 offset:59904
	v_exp_f32_e32 v63, v63
	s_waitcnt lgkmcnt(2)
	v_mfma_f32_32x32x16_bf16 v[16:31], v[56:59], v[52:55], v[16:31]
	ds_read_b64_tr_b16 v[58:59], v206 offset:59968
	ds_read_b64_tr_b16 v[56:57], v206 offset:58432
	v_cvt_pk_bf16_f32 v52, v233, v235
	v_cvt_pk_bf16_f32 v53, v236, v237
	v_cvt_pk_bf16_f32 v54, v60, v61
	v_cvt_pk_bf16_f32 v55, v62, v63
	s_waitcnt lgkmcnt(2)
	s_nop 0
	v_mfma_f32_32x32x16_bf16 v[32:47], v[48:51], v[52:55], v[32:47]
	v_add_f32_e32 v48, v235, v234
	v_add_f32_e32 v48, v236, v48
	v_add_f32_e32 v48, v237, v48
	v_add_f32_e32 v48, v60, v48
	v_add_f32_e32 v48, v61, v48
	v_add_f32_e32 v48, v62, v48
	v_add_f32_e32 v48, v63, v48
	s_waitcnt lgkmcnt(0)
	v_mfma_f32_32x32x16_bf16 v[16:31], v[56:59], v[52:55], v[16:31]
	v_add_f32_e32 v60, v238, v48
; #define LAS __attribute__((address_space(3)))
; __device__ __forceinline__ unsigned pk2(float lo, float hi) { f32x2_t v = {lo, hi}; bf16x2_t b = __builtin_convertvector(v, bf16x2_t); return __builtin_bit_cast(unsigned, b); }
; __device__ __forceinline__ s16x4 trrd(LAS const unsigned char* p) { return __builtin_bit_cast(s16x4, __builtin_amdgcn_ds_read_tr16_b64_v4i16((LAS v4i16_t*)p)); }
; #define ATTN_QLOAD(W) do { const bf16_t* qr_ = Qb + ((size_t)((W).b * 24 + (W).hd) * SEQ + (size_t)((W).r * (W).L + (W).i0 + 32 * wave + l31)) * 64; \
;         _Pragma("unroll") for (int ks_ = 0; ks_ < 4; ++ks_) qv[ks_] = *(const u32x4*)(qr_ + 16 * ks_ + 8 * h); } while (0)
; template <bool FUSED> __device__ __forceinline__ void attn_phase(const Args& a, LAS unsigned char* lds, int tid, int lane, int wave) {
;     ...
; #pragma unroll
;         for (int j = 0; j < 5; ++j) {
;             f32x16 st;
; #pragma unroll
;             for (int i = 0; i < 16; ++i) st[i] = -mb;
;             LAS const unsigned char* kp = lds + (32 * wave + 32 * j + l31) * KP + 16 * h;
; #pragma unroll
;             for (int ks = 0; ks < 4; ++ks) { const bf16x8 kf = *(LAS const bf16x8*)(kp + 32 * ks); st = __builtin_amdgcn_mfma_f32_32x32x16_bf16(kf, qf[ks], st, 0, 0, 0); }
;             sum += attn_tile_exp(st, j, tlf, bsl, rlo, rhi);
; #pragma unroll
;             for (int s2 = 0; s2 < 2; ++s2) { u32x4 pw; pw.x = pk2(st[8 * s2 + 0], st[8 * s2 + 1]); pw.y = pk2(st[8 * s2 + 2], st[8 * s2 + 3]); pw.z = pk2(st[8 * s2 + 4], st[8 * s2 + 5]); pw.w = pk2(st[8 * s2 + 6], st[8 * s2 + 7]);
;                 const bf16x8 pf = __builtin_bit_cast(bf16x8, pw);
;                 LAS const unsigned char* vp = lds + LDS_VOFF + (32 * wave + 32 * j + 16 * s2 + 4 * h + q) * VP + 32 * blk + 8 * p;
; #pragma unroll
;                 for (int dt = 0; dt < 2; ++dt) { const s16x4 lo = trrd(vp + dt * 64), hi = trrd(vp + 8 * VP + dt * 64);
;                     const bf16x8 vf = __builtin_shufflevector(lo, hi, 0, 1, 2, 3, 4, 5, 6, 7);
;                     o[dt] = __builtin_amdgcn_mfma_f32_32x32x16_bf16(vf, pf, o[dt], 0, 0, 0); } }
;             __builtin_amdgcn_sched_barrier(0);
;         }
;         sum += __shfl_xor(sum, 32);
;         if (un < NU) { const AUnit wq = attn_decode(un, HD0, NH); ATTN_QLOAD(wq); }
.Lattn1_t4:
	ds_read_b128 v[48:51], v207
	ds_read_b128 v[52:55], v207 offset:32
	v_add_f32_e32 v61, 0x42800000, v225
	v_add_f32_e32 v62, 0x42820000, v225
	v_cmp_nge_f32_e32 vcc, v61, v169
	s_waitcnt lgkmcnt(1)
	v_mfma_f32_32x32x16_bf16 v[0:15], v[48:51], v[88:91], v[0:15]
	ds_read_b128 v[48:51], v207 offset:64
	ds_read_b128 v[56:59], v207 offset:96
	v_cmp_nle_f32_e64 s[6:7], v61, v223
	v_add_f32_e32 v63, 0x42840000, v225
	v_cmp_nge_f32_e64 s[8:9], v62, v169
	v_cmp_nle_f32_e64 s[10:11], v62, v223
	s_or_b64 vcc, vcc, s[6:7]
	v_add_f32_e32 v136, 0x42860000, v225
	s_waitcnt lgkmcnt(2)
	v_mfma_f32_32x32x16_bf16 v[0:15], v[52:55], v[92:95], v[0:15]
	v_cmp_nge_f32_e64 s[12:13], v63, v169
	v_cmp_nle_f32_e64 s[14:15], v63, v223
	v_add_f32_e32 v52, 0x42900000, v225
	v_cmp_nge_f32_e64 s[16:17], v136, v169
	v_cmp_nle_f32_e64 s[20:21], v136, v223
	v_add_f32_e32 v53, 0x42920000, v225
	v_cmp_nge_f32_e64 s[22:23], v52, v169
	s_waitcnt lgkmcnt(1)
	v_mfma_f32_32x32x16_bf16 v[0:15], v[48:51], v[100:103], v[0:15]
	v_cmp_nle_f32_e64 s[24:25], v52, v223
	v_cmp_nge_f32_e64 s[26:27], v53, v169
	v_cmp_nle_f32_e64 s[28:29], v53, v223
	s_waitcnt lgkmcnt(0)
	v_mfma_f32_32x32x16_bf16 v[0:15], v[56:59], v[108:111], v[0:15]
	s_nop 11
	v_fma_f32 v0, v224, |v61|, v0
	v_fma_f32 v1, v224, |v62|, v1
	v_cndmask_b32_e32 v0, v0, v221, vcc
	s_or_b64 vcc, s[8:9], s[10:11]
	v_fma_f32 v2, v224, |v63|, v2
	v_cndmask_b32_e32 v1, v1, v221, vcc
	s_or_b64 vcc, s[12:13], s[14:15]
	v_fma_f32 v3, v224, |v136|, v3
	v_cndmask_b32_e32 v2, v2, v221, vcc
	s_or_b64 vcc, s[16:17], s[20:21]
	v_fma_f32 v4, v224, |v52|, v4
	v_cndmask_b32_e32 v3, v3, v221, vcc
	s_or_b64 vcc, s[22:23], s[24:25]
	v_fma_f32 v5, v224, |v53|, v5
	v_cndmask_b32_e32 v4, v4, v221, vcc
	s_or_b64 vcc, s[26:27], s[28:29]
	v_exp_f32_e32 v49, v1
	v_cndmask_b32_e32 v1, v5, v221, vcc
	v_exp_f32_e32 v53, v1
	v_add_f32_e32 v1, 0x42940000, v225
	v_cmp_nge_f32_e32 vcc, v1, v169
	v_cmp_nle_f32_e64 s[6:7], v1, v223
	v_exp_f32_e32 v50, v2
	v_fma_f32 v2, v224, |v1|, v6
	s_or_b64 vcc, vcc, s[6:7]
	v_cndmask_b32_e32 v1, v2, v221, vcc
	v_exp_f32_e32 v48, v0
	v_exp_f32_e32 v54, v1
	v_add_f32_e32 v1, 0x42960000, v225
	v_cmp_nge_f32_e32 vcc, v1, v169
	v_cmp_nle_f32_e64 s[6:7], v1, v223
	v_fma_f32 v2, v224, |v1|, v7
	s_or_b64 vcc, vcc, s[6:7]
	v_exp_f32_e32 v51, v3
	v_cndmask_b32_e32 v1, v2, v221, vcc
	v_exp_f32_e32 v52, v4
	v_add_f32_e32 v0, 0, v48
	v_exp_f32_e32 v7, v1
	v_add_f32_e32 v1, 0x42a00000, v225
	v_add_f32_e32 v0, v49, v0
	v_cmp_nge_f32_e32 vcc, v1, v169
	v_cmp_nle_f32_e64 s[6:7], v1, v223
	v_add_f32_e32 v0, v50, v0
	v_fma_f32 v2, v224, |v1|, v8
	s_or_b64 vcc, vcc, s[6:7]
	v_add_f32_e32 v0, v51, v0
	v_cndmask_b32_e32 v1, v2, v221, vcc
	v_add_f32_e32 v0, v52, v0
	v_exp_f32_e32 v55, v1
	v_add_f32_e32 v0, v53, v0
	v_add_f32_e32 v0, v54, v0
	v_add_f32_e32 v0, v7, v0
	v_add_f32_e32 v56, v55, v0
	v_add_f32_e32 v0, 0x42a20000, v225
	v_cmp_nge_f32_e32 vcc, v0, v169
	v_cmp_nle_f32_e64 s[6:7], v0, v223
	v_fma_f32 v1, v224, |v0|, v9
	s_or_b64 vcc, vcc, s[6:7]
	v_cndmask_b32_e32 v0, v1, v221, vcc
	v_exp_f32_e32 v57, v0
	v_add_f32_e32 v0, 0x42a40000, v225
	v_cmp_nge_f32_e32 vcc, v0, v169
	v_cmp_nle_f32_e64 s[6:7], v0, v223
	v_fma_f32 v1, v224, |v0|, v10
	s_or_b64 vcc, vcc, s[6:7]
	v_cndmask_b32_e32 v0, v1, v221, vcc
	v_exp_f32_e32 v58, v0
	v_add_f32_e32 v0, 0x42a60000, v225
	v_cmp_nge_f32_e32 vcc, v0, v169
	v_cmp_nle_f32_e64 s[6:7], v0, v223
	v_fma_f32 v1, v224, |v0|, v11
	s_or_b64 vcc, vcc, s[6:7]
	v_cndmask_b32_e32 v0, v1, v221, vcc
	v_exp_f32_e32 v59, v0
	v_add_f32_e32 v0, 0x42b00000, v225
	v_cmp_nge_f32_e32 vcc, v0, v169
	v_cmp_nle_f32_e64 s[6:7], v0, v223
	v_fma_f32 v1, v224, |v0|, v12
	s_or_b64 vcc, vcc, s[6:7]
	v_cndmask_b32_e32 v0, v1, v221, vcc
	v_exp_f32_e32 v12, v0
	v_add_f32_e32 v0, 0x42b20000, v225
	v_cmp_nge_f32_e32 vcc, v0, v169
	v_cmp_nle_f32_e64 s[6:7], v0, v223
	v_fma_f32 v1, v224, |v0|, v13
	s_or_b64 vcc, vcc, s[6:7]
	v_cndmask_b32_e32 v0, v1, v221, vcc
	v_exp_f32_e32 v13, v0
	v_add_f32_e32 v0, 0x42b40000, v225
	v_cmp_nge_f32_e32 vcc, v0, v169
	v_cmp_nle_f32_e64 s[6:7], v0, v223
	v_fma_f32 v1, v224, |v0|, v14
	s_or_b64 vcc, vcc, s[6:7]
	v_cndmask_b32_e32 v4, v1, v221, vcc
	ds_read_b64_tr_b16 v[0:1], v208 offset:55296
	ds_read_b64_tr_b16 v[2:3], v208 offset:56832
	ds_read_b64_tr_b16 v[10:11], v208 offset:56896
	ds_read_b64_tr_b16 v[8:9], v208 offset:55360
	v_exp_f32_e32 v14, v4
	v_add_f32_e32 v61, 0x42b60000, v225
	v_cvt_pk_bf16_f32 v4, v48, v49
	v_cvt_pk_bf16_f32 v5, v50, v51
	v_cvt_pk_bf16_f32 v6, v52, v53
	v_cvt_pk_bf16_f32 v7, v54, v7
	v_cmp_nge_f32_e32 vcc, v61, v169
	v_cmp_nle_f32_e64 s[6:7], v61, v223
	s_waitcnt lgkmcnt(2)
	v_mfma_f32_32x32x16_bf16 v[32:47], v[0:3], v[4:7], v[32:47]
	v_fma_f32 v0, v224, |v61|, v15
	s_or_b64 vcc, vcc, s[6:7]
	v_cndmask_b32_e32 v15, v0, v221, vcc
	ds_read_b64_tr_b16 v[0:1], v208 offset:58368
	ds_read_b64_tr_b16 v[2:3], v208 offset:59904
	v_exp_f32_e32 v15, v15
	s_waitcnt lgkmcnt(2)
	v_mfma_f32_32x32x16_bf16 v[16:31], v[8:11], v[4:7], v[16:31]
	ds_read_b64_tr_b16 v[10:11], v208 offset:59968
	ds_read_b64_tr_b16 v[8:9], v208 offset:58432
	v_cvt_pk_bf16_f32 v4, v55, v57
	v_cvt_pk_bf16_f32 v5, v58, v59
	v_cvt_pk_bf16_f32 v6, v12, v13
	v_cvt_pk_bf16_f32 v7, v14, v15
	s_waitcnt lgkmcnt(2)
	s_nop 0
	v_mfma_f32_32x32x16_bf16 v[32:47], v[0:3], v[4:7], v[32:47]
	v_add_f32_e32 v0, v57, v56
	v_add_f32_e32 v0, v58, v0
	v_add_f32_e32 v0, v59, v0
	v_add_f32_e32 v0, v12, v0
	v_add_f32_e32 v0, v13, v0
	v_add_f32_e32 v0, v14, v0
	v_add_f32_e32 v0, v15, v0
	s_waitcnt lgkmcnt(0)
	v_mfma_f32_32x32x16_bf16 v[16:31], v[8:11], v[4:7], v[16:31]
	v_add_f32_e32 v0, v60, v0
	ds_bpermute_b32 v1, v153, v0
	s_andn2_b64 vcc, exec, s[72:73]
	s_cbranch_vccnz .LBB0_284
	s_ashr_i32 s7, s69, 5
	s_lshr_b32 s8, s7, 28
	s_add_i32 s8, s7, s8
	s_and_b32 s8, s8, -16
	s_sub_i32 s7, s7, s8
	s_add_i32 s7, s7, 8
	s_ashr_i32 s8, s69, 31
	s_ashr_i32 s9, s7, 2
	s_lshr_b32 s8, s8, 23
	s_and_b32 s9, s9, -2
	s_add_i32 s8, s69, s8
	s_lshr_b32 s10, 32, s9
	s_and_b32 s6, s69, 31
	s_ashr_i32 s8, s8, 9
	s_lshr_b32 s11, 0x2000, s9
	s_sub_i32 s9, 5, s9
	s_add_i32 s10, s10, -1
	s_lshr_b32 s9, s6, s9
	s_and_b32 s6, s10, s6
	s_mul_i32 s8, s8, 24
	s_lshl_b32 s10, s6, 8
	s_add_i32 s6, s7, s8
	s_mul_i32 s9, s9, s11
	s_ashr_i32 s7, s6, 31
	s_add_i32 s10, s10, s9
	v_add_u32_e32 v2, s10, v145
	s_lshl_b64 s[6:7], s[6:7], 20
	v_ashrrev_i32_e32 v3, 31, v2
	s_add_u32 s6, s40, s6
	s_addc_u32 s7, s41, s7
	v_lshlrev_b64 v[2:3], 7, v[2:3]
	v_lshl_add_u64 v[2:3], s[6:7], 0, v[2:3]
	v_lshl_add_u64 v[2:3], v[148:149], 1, v[2:3]
	global_load_dwordx4 v[88:91], v[2:3], off
	global_load_dwordx4 v[92:95], v[2:3], off offset:32
	global_load_dwordx4 v[100:103], v[2:3], off offset:64
	global_load_dwordx4 v[108:111], v[2:3], off offset:96

; #define LAS __attribute__((address_space(3)))
; __device__ __forceinline__ void attn_issue(const AUnit& w, const bf16_t* Qb, const bf16_t* Kb, const bf16_t* Vb, int tid, int wave, int lane, u32x4 (&kv)[6], u32x4 (&vv)[6]) {
;     const int ch = tid & 7;
; #pragma unroll
;     for (int i = 0; i < 6; ++i) { const int row = (tid + 512 * i) >> 3; int pk = w.i0 - 64 + row; pk = pk < 0 ? 0 : (pk >= w.L ? w.L - 1 : pk);
;         const size_t off = ((size_t)(w.b * 24 + w.hd) * SEQ + (size_t)(w.r * w.L + pk)) * 64 + ch * 8; kv[i] = *(const u32x4*)(Kb + off); vv[i] = *(const u32x4*)(Vb + off); }
; }
; template <bool FUSED> __device__ __forceinline__ void attn_phase(const Args& a, LAS unsigned char* lds, int tid, int lane, int wave) {
;     ...
;         {
;             const int ch = tid & 7;
;             const f32x4 g0 = *(const f32x4*)(a.kw + hd * 64 + ch * 8), g1 = *(const f32x4*)(a.kw + hd * 64 + ch * 8 + 4);
; #pragma unroll
;             for (int i = 0; i < 6; ++i) { const int row = (tid + 512 * i) >> 3;
;                 const float e0 = bflo(kv[i].x), e1 = bfhi(kv[i].x), e2 = bflo(kv[i].y), e3 = bfhi(kv[i].y), e4 = bflo(kv[i].z), e5 = bfhi(kv[i].z), e6 = bflo(kv[i].w), e7 = bfhi(kv[i].w);
;                 float ss = (e0 * e0 + e1 * e1) + (e2 * e2 + e3 * e3) + (e4 * e4 + e5 * e5) + (e6 * e6 + e7 * e7);
;                 ss += dpp_movf<0xB1>(ss); ss += dpp_movf<0x4E>(ss); ss += dpp_movf<0x141>(ss);
;                 const float rk = __builtin_amdgcn_rsqf(ss * (1.f / 64.f) + 1e-6f);
;                 u32x4 wv; wv.x = pk2(e0 * rk * g0.x, e1 * rk * g0.y); wv.y = pk2(e2 * rk * g0.z, e3 * rk * g0.w); wv.z = pk2(e4 * rk * g1.x, e5 * rk * g1.y); wv.w = pk2(e6 * rk * g1.z, e7 * rk * g1.w);
;                 *(LAS u32x4*)(lds + row * KP + ch * 16) = wv;
;                 *(LAS u32x4*)(lds + LDS_VOFF + row * VP + ch * 16) = vv[i];
;                 if (i & 1) __builtin_amdgcn_sched_barrier(0); }
;         }
;         bf16x8 qf[4];
;         {
;             float ss = 0.f;
; #pragma unroll
;             for (int ks = 0; ks < 4; ++ks)
; #pragma unroll
;                 for (int e = 0; e < 4; ++e) { const float lo = bflo(qv[ks][e]), hi = bfhi(qv[ks][e]); ss += lo * lo + hi * hi; }
;             ss += __shfl_xor(ss, 32);
;             const float rq = 0.125f * LOG2E * __builtin_amdgcn_rsqf(ss * (1.f / 64.f) + 1e-6f);
; #pragma unroll
.LBB0_402:
	s_ashr_i32 s6, s46, 5
	s_lshr_b32 s7, s6, 29
	s_add_i32 s7, s6, s7
	s_and_b32 s7, s7, -8
	s_sub_i32 s6, s6, s7
	s_ashr_i32 s7, s6, 31
	s_lshl_b64 s[8:9], s[6:7], 2
	s_add_u32 s8, s87, s8
	s_addc_u32 s9, s88, s9
	global_load_dword v229, v147, s[8:9]
	s_waitcnt vmcnt(15)
	ds_write_b128 v194, v[64:67]
	ds_write_b128 v195, v[68:71] offset:55296
	s_waitcnt vmcnt(13)
	ds_write_b128 v196, v[72:75]
	ds_write_b128 v197, v[76:79] offset:55296
	s_waitcnt vmcnt(11)
	ds_write_b128 v198, v[80:83]
	ds_write_b128 v199, v[84:87] offset:55296
	s_waitcnt vmcnt(9)
	ds_write_b128 v200, v[88:91]
	ds_write_b128 v201, v[92:95] offset:55296
	s_waitcnt vmcnt(7)
	ds_write_b128 v202, v[112:115]
	ds_write_b128 v203, v[116:119] offset:55296
	s_waitcnt vmcnt(5)
	ds_write_b128 v204, v[120:123]
	ds_write_b128 v205, v[124:127] offset:55296
	s_add_i32 s64, s46, s54
	s_cmpk_lt_i32 s64, 0x800
	s_cselect_b64 s[44:45], -1, 0
	s_cmpk_gt_i32 s64, 0x7ff
	s_cselect_b64 s[42:43], -1, 0
	s_and_b64 vcc, exec, s[42:43]
	s_waitcnt vmcnt(1)
	s_waitcnt lgkmcnt(0)
	s_barrier
	s_cbranch_vccnz .LBB0_404
	s_ashr_i32 s8, s64, 5
	s_lshr_b32 s9, s8, 29
	s_add_i32 s9, s8, s9
	s_and_b32 s9, s9, -8
	s_sub_i32 s8, s8, s9
	s_ashr_i32 s10, s8, 2
	s_and_b32 s10, s10, -2
	s_lshr_b32 s11, 32, s10
	s_and_b32 s7, s64, 31
	s_lshr_b32 s12, 0x2000, s10
	s_sub_i32 s10, 5, s10
	s_add_i32 s11, s11, -1
	s_lshr_b32 s10, s7, s10
	s_and_b32 s7, s11, s7
	s_lshl_b32 s7, s7, 8
	s_add_i32 s11, s12, -1
	s_mul_i32 s10, s10, s12
	s_ashr_i32 s9, s64, 31
	s_lshr_b32 s9, s9, 24
	s_add_i32 s9, s64, s9
	s_ashr_i32 s9, s9, 8
	s_mul_i32 s9, s9, 24
	s_add_i32 s8, s9, s8
	s_ashr_i32 s9, s8, 31
	s_lshl_b64 s[8:9], s[8:9], 20
	s_add_u32 s94, s58, s8
	s_addc_u32 s95, s59, s9
	s_add_u32 s96, s60, s8
	s_addc_u32 s97, s61, s9
	v_add_u32_e32 v68, s7, v153
	v_med3_i32 v68, v68, 0, s11
	v_add_lshl_u32 v68, v68, s10, 7
	v_lshl_or_b32 v68, v144, 1, v68
	global_load_dwordx4 v[64:67], v68, s[94:95]
	global_load_dwordx4 v[68:71], v68, s[96:97]
	v_add_u32_e32 v76, s7, v155
	v_med3_i32 v76, v76, 0, s11
	v_add_lshl_u32 v76, v76, s10, 7
	v_lshl_or_b32 v76, v144, 1, v76
	global_load_dwordx4 v[72:75], v76, s[94:95]
	global_load_dwordx4 v[76:79], v76, s[96:97]
	v_add_u32_e32 v84, s7, v159
	v_med3_i32 v84, v84, 0, s11
	v_add_lshl_u32 v84, v84, s10, 7
	v_lshl_or_b32 v84, v144, 1, v84
	global_load_dwordx4 v[80:83], v84, s[94:95]
	global_load_dwordx4 v[84:87], v84, s[96:97]
	v_add_u32_e32 v92, s7, v161
	v_med3_i32 v92, v92, 0, s11
	v_add_lshl_u32 v92, v92, s10, 7
	v_lshl_or_b32 v92, v144, 1, v92
	global_load_dwordx4 v[88:91], v92, s[94:95]
	global_load_dwordx4 v[92:95], v92, s[96:97]
	v_add_u32_e32 v116, s7, v163
	v_med3_i32 v116, v116, 0, s11
	v_add_lshl_u32 v116, v116, s10, 7
	v_lshl_or_b32 v116, v144, 1, v116
	global_load_dwordx4 v[112:115], v116, s[94:95]
	global_load_dwordx4 v[116:119], v116, s[96:97]
	v_add_u32_e32 v124, s7, v176
	v_med3_i32 v124, v124, 0, s11
	v_add_lshl_u32 v124, v124, s10, 7
	v_lshl_or_b32 v124, v144, 1, v124
	global_load_dwordx4 v[120:123], v124, s[94:95]
	global_load_dwordx4 v[124:127], v124, s[96:97]
	v_mov_b32_e32 v28, v177
	ds_read_b128 v[24:27], v206 offset:32
	s_and_b32 s65, s6, 7
	ds_read_b128 v[20:23], v206
	s_ashr_i32 s7, s6, 2
	s_add_i32 s6, s65, 1
	s_and_b32 s7, s7, -2
	s_lshr_b32 s8, 32, s7
	s_add_i32 s8, s8, -1
	s_and_b32 s8, s46, s8
	s_waitcnt vmcnt(12)
	s_branch .Lattn2_join

; #define LAS __attribute__((address_space(3)))
; __device__ __forceinline__ unsigned pk2(float lo, float hi) { f32x2_t v = {lo, hi}; bf16x2_t b = __builtin_convertvector(v, bf16x2_t); return __builtin_bit_cast(unsigned, b); }
; __device__ __forceinline__ s16x4 trrd(LAS const unsigned char* p) { return __builtin_bit_cast(s16x4, __builtin_amdgcn_ds_read_tr16_b64_v4i16((LAS v4i16_t*)p)); }
; template <bool FUSED> __device__ __forceinline__ void attn_phase(const Args& a, LAS unsigned char* lds, int tid, int lane, int wave) {
;     ...
;         const float bsl = __builtin_amdgcn_exp2f(-(float)(slot + 1)) * (float)w.dil * LOG2E;
;         int tl = 4 * h - l31; asm volatile("" : "+v"(tl));
;         const float tlf = (float)tl;
;         const int lo_i = -iq > -64 ? -iq : -64, hi_i = (L - 1 - iq) < 64 ? (L - 1 - iq) : 64;
;         const float rlo = (float)lo_i, rhi = (float)hi_i;
;         const int wq0 = i0 + 32 * wave;
;         const bool edge = (wq0 < 64) || (wq0 + 32 > L - 64);
;         float sum = 0.f;
;         f32x16 o[2]; o[0] = f32x16{}; o[1] = f32x16{};
; #pragma unroll
;         for (int j = 0; j < 5; ++j) {
;             f32x16 st;
; #pragma unroll
;             for (int i = 0; i < 16; ++i) st[i] = -mb;
;             LAS const unsigned char* kp = lds + (32 * wave + 32 * j + l31) * KP + 16 * h;
; #pragma unroll
;             for (int ks = 0; ks < 4; ++ks) { const bf16x8 kf = *(LAS const bf16x8*)(kp + 32 * ks); st = __builtin_amdgcn_mfma_f32_32x32x16_bf16(kf, qf[ks], st, 0, 0, 0); }
;             sum += attn_tile_exp(st, j, tlf, bsl, rlo, rhi);
; #pragma unroll
;             for (int s2 = 0; s2 < 2; ++s2) { u32x4 pw; pw.x = pk2(st[8 * s2 + 0], st[8 * s2 + 1]); pw.y = pk2(st[8 * s2 + 2], st[8 * s2 + 3]); pw.z = pk2(st[8 * s2 + 4], st[8 * s2 + 5]); pw.w = pk2(st[8 * s2 + 6], st[8 * s2 + 7]);
;                 const bf16x8 pf = __builtin_bit_cast(bf16x8, pw);
;                 LAS const unsigned char* vp = lds + LDS_VOFF + (32 * wave + 32 * j + 16 * s2 + 4 * h + q) * VP + 32 * blk + 8 * p;
; #pragma unroll
;                 for (int dt = 0; dt < 2; ++dt) { const s16x4 lo = trrd(vp + dt * 64), hi = trrd(vp + 8 * VP + dt * 64);
;                     const bf16x8 vf = __builtin_shufflevector(lo, hi, 0, 1, 2, 3, 4, 5, 6, 7);
;                     o[dt] = __builtin_amdgcn_mfma_f32_32x32x16_bf16(vf, pf, o[dt], 0, 0, 0); } }
.Lattn2_join:
	v_xor_b32_e32 v32, 0x80000000, v229
	v_mov_b32_e32 v33, v32
	v_mov_b32_e32 v34, v32
	v_mov_b32_e32 v35, v32
	v_mov_b32_e32 v36, v32
	v_mov_b32_e32 v37, v32
	v_mov_b32_e32 v38, v32
	v_mov_b32_e32 v39, v32
	v_mov_b32_e32 v40, v32
	v_mov_b32_e32 v41, v32
	v_mov_b32_e32 v42, v32
	v_mov_b32_e32 v43, v32
	v_mov_b32_e32 v44, v32
	v_mov_b32_e32 v45, v32
	v_mov_b32_e32 v46, v32
	v_mov_b32_e32 v47, v32
	s_and_b32 s8, s8, 31
	s_waitcnt lgkmcnt(0)
	v_mfma_f32_32x32x16_bf16 v[0:15], v[20:23], v[96:99], v[32:47]
	ds_read_b128 v[20:23], v206 offset:64
	v_cvt_f32_ubyte0_e32 v16, s6
	v_exp_f32_e64 v29, -v16
	v_mfma_f32_32x32x16_bf16 v[0:15], v[24:27], v[100:103], v[0:15]
	s_lshl_b32 s66, s8, 8
	ds_read_b128 v[16:19], v206 offset:96
	s_add_i32 s66, s66, s48
	s_lshl_b32 s9, 1, s7
	s_lshr_b32 s7, 0x2000, s7
	s_waitcnt lgkmcnt(1)
	v_mfma_f32_32x32x16_bf16 v[0:15], v[20:23], v[104:107], v[0:15]
	v_or_b32_e32 v62, s66, v145
	v_sub_u32_e32 v20, 0, v62
	v_xad_u32 v21, v62, -1, s7
	v_cvt_f32_u32_e32 v24, s9
	v_cvt_f32_i32_e32 v171, v28
	v_max_i32_e32 v20, 0xffffffc0, v20
	v_min_i32_e32 v21, 64, v21
	s_waitcnt lgkmcnt(0)
	v_mfma_f32_32x32x16_bf16 v[0:15], v[16:19], v[108:111], v[0:15]
	v_cvt_f32_i32_e32 v168, v20
	v_cvt_f32_i32_e32 v169, v21
	v_mul_f32_e32 v24, v29, v24
	v_add_f32_e32 v16, 0xc2800000, v171
	v_mul_f32_e32 v170, 0xbfb8aa3b, v24
	v_cmp_nge_f32_e32 vcc, v16, v168
	v_cmp_nle_f32_e64 s[6:7], v16, v169
	s_nop 4
	v_fma_f32 v0, v170, |v16|, v0
	s_or_b64 vcc, vcc, s[6:7]
	v_add_f32_e32 v17, 0xc27c0000, v171
	v_cndmask_b32_e32 v0, v0, v228, vcc
	v_cmp_nge_f32_e32 vcc, v17, v168
	v_cmp_nle_f32_e64 s[6:7], v17, v169
	v_fma_f32 v1, v170, |v17|, v1
	s_or_b64 vcc, vcc, s[6:7]
	v_cndmask_b32_e32 v1, v1, v228, vcc
	v_exp_f32_e32 v17, v1
	v_add_f32_e32 v1, 0xc2780000, v171
	v_cmp_nge_f32_e32 vcc, v1, v168
	v_cmp_nle_f32_e64 s[6:7], v1, v169
	v_fma_f32 v2, v170, |v1|, v2
	s_or_b64 vcc, vcc, s[6:7]
	v_cndmask_b32_e32 v1, v2, v228, vcc
	v_exp_f32_e32 v18, v1
	v_add_f32_e32 v1, 0xc2740000, v171
	v_cmp_nge_f32_e32 vcc, v1, v168
	v_cmp_nle_f32_e64 s[6:7], v1, v169
	v_fma_f32 v2, v170, |v1|, v3
	s_or_b64 vcc, vcc, s[6:7]
	v_cndmask_b32_e32 v1, v2, v228, vcc
	v_exp_f32_e32 v19, v1
	v_add_f32_e32 v1, 0xc2600000, v171
	v_cmp_nge_f32_e32 vcc, v1, v168
	v_cmp_nle_f32_e64 s[6:7], v1, v169
	v_fma_f32 v2, v170, |v1|, v4
	s_or_b64 vcc, vcc, s[6:7]
	v_cndmask_b32_e32 v1, v2, v228, vcc
	v_exp_f32_e32 v20, v1
	v_add_f32_e32 v1, 0xc25c0000, v171
	v_cmp_nge_f32_e32 vcc, v1, v168
	v_cmp_nle_f32_e64 s[6:7], v1, v169
	v_fma_f32 v2, v170, |v1|, v5
	s_or_b64 vcc, vcc, s[6:7]
	v_cndmask_b32_e32 v1, v2, v228, vcc
	v_exp_f32_e32 v21, v1
	v_add_f32_e32 v1, 0xc2580000, v171
	v_cmp_nge_f32_e32 vcc, v1, v168
	v_cmp_nle_f32_e64 s[6:7], v1, v169
	v_fma_f32 v2, v170, |v1|, v6
	s_or_b64 vcc, vcc, s[6:7]
	v_cndmask_b32_e32 v1, v2, v228, vcc
	v_exp_f32_e32 v16, v0
	v_exp_f32_e32 v22, v1
	v_add_f32_e32 v1, 0xc2540000, v171
	v_cmp_nge_f32_e32 vcc, v1, v168
	v_cmp_nle_f32_e64 s[6:7], v1, v169
	v_fma_f32 v2, v170, |v1|, v7
	s_or_b64 vcc, vcc, s[6:7]
	v_cndmask_b32_e32 v1, v2, v228, vcc
	v_add_f32_e32 v0, 0, v16
	v_exp_f32_e32 v7, v1
	v_add_f32_e32 v1, 0xc2400000, v171
	v_add_f32_e32 v0, v17, v0
	v_cmp_nge_f32_e32 vcc, v1, v168
	v_cmp_nle_f32_e64 s[6:7], v1, v169
	v_add_f32_e32 v0, v18, v0
	v_fma_f32 v2, v170, |v1|, v8
	s_or_b64 vcc, vcc, s[6:7]
	v_add_f32_e32 v0, v19, v0
	v_cndmask_b32_e32 v1, v2, v228, vcc
	v_add_f32_e32 v0, v20, v0
	v_exp_f32_e32 v52, v1
	v_add_f32_e32 v0, v21, v0
	v_add_f32_e32 v0, v22, v0
	v_add_f32_e32 v0, v7, v0
	v_add_f32_e32 v60, v52, v0
	v_add_f32_e32 v0, 0xc23c0000, v171
	v_cmp_nge_f32_e32 vcc, v0, v168
	v_cmp_nle_f32_e64 s[6:7], v0, v169
	v_fma_f32 v1, v170, |v0|, v9
	s_or_b64 vcc, vcc, s[6:7]
	v_cndmask_b32_e32 v0, v1, v228, vcc
	v_exp_f32_e32 v61, v0
	v_add_f32_e32 v0, 0xc2380000, v171
	v_cmp_nge_f32_e32 vcc, v0, v168
	v_cmp_nle_f32_e64 s[6:7], v0, v169
	v_fma_f32 v1, v170, |v0|, v10
	s_or_b64 vcc, vcc, s[6:7]
	v_cndmask_b32_e32 v0, v1, v228, vcc
	v_exp_f32_e32 v62, v0
	v_add_f32_e32 v0, 0xc2340000, v171
	v_cmp_nge_f32_e32 vcc, v0, v168
	v_cmp_nle_f32_e64 s[6:7], v0, v169
	v_fma_f32 v1, v170, |v0|, v11
	s_or_b64 vcc, vcc, s[6:7]
	v_cndmask_b32_e32 v0, v1, v228, vcc
	v_exp_f32_e32 v63, v0
	v_add_f32_e32 v0, 0xc2200000, v171
	v_cmp_nge_f32_e32 vcc, v0, v168
	v_cmp_nle_f32_e64 s[6:7], v0, v169
	v_fma_f32 v1, v170, |v0|, v12
	s_or_b64 vcc, vcc, s[6:7]
	v_cndmask_b32_e32 v0, v1, v228, vcc
	v_exp_f32_e32 v172, v0
	v_add_f32_e32 v0, 0xc21c0000, v171
	v_cmp_nge_f32_e32 vcc, v0, v168
	v_cmp_nle_f32_e64 s[6:7], v0, v169
	v_fma_f32 v1, v170, |v0|, v13
	s_or_b64 vcc, vcc, s[6:7]
	v_cndmask_b32_e32 v0, v1, v228, vcc
	v_exp_f32_e32 v173, v0
	v_add_f32_e32 v0, 0xc2180000, v171
	v_cmp_nge_f32_e32 vcc, v0, v168
	v_cmp_nle_f32_e64 s[6:7], v0, v169
	v_fma_f32 v1, v170, |v0|, v14
	s_or_b64 vcc, vcc, s[6:7]
	v_cndmask_b32_e32 v4, v1, v228, vcc
	ds_read_b64_tr_b16 v[0:1], v207 offset:55296
	ds_read_b64_tr_b16 v[2:3], v207 offset:56832
	ds_read_b64_tr_b16 v[10:11], v207 offset:56896
	ds_read_b64_tr_b16 v[8:9], v207 offset:55360
	v_add_f32_e32 v12, 0xc2140000, v171
	v_exp_f32_e32 v174, v4
	v_cvt_pk_bf16_f32 v4, v16, v17
	v_cvt_pk_bf16_f32 v5, v18, v19
	v_cvt_pk_bf16_f32 v6, v20, v21
	v_cvt_pk_bf16_f32 v7, v22, v7
	v_cmp_nge_f32_e32 vcc, v12, v168
	v_cmp_nle_f32_e64 s[6:7], v12, v169
	s_waitcnt lgkmcnt(2)
	v_mfma_f32_32x32x16_bf16 v[16:31], v[0:3], v[4:7], 0
	v_fma_f32 v0, v170, |v12|, v15
	s_or_b64 vcc, vcc, s[6:7]
	v_cndmask_b32_e32 v53, v0, v228, vcc
	ds_read_b64_tr_b16 v[48:49], v207 offset:58368
	ds_read_b64_tr_b16 v[50:51], v207 offset:59904
	v_exp_f32_e32 v175, v53
	ds_read_b64_tr_b16 v[58:59], v207 offset:59968
	ds_read_b64_tr_b16 v[56:57], v207 offset:58432
	v_cvt_pk_bf16_f32 v52, v52, v61
	s_waitcnt lgkmcnt(4)
	v_mfma_f32_32x32x16_bf16 v[0:15], v[8:11], v[4:7], 0
	v_cvt_pk_bf16_f32 v53, v62, v63
	v_cvt_pk_bf16_f32 v54, v172, v173
	v_cvt_pk_bf16_f32 v55, v174, v175
	s_waitcnt lgkmcnt(2)
	s_nop 0
	v_mfma_f32_32x32x16_bf16 v[16:31], v[48:51], v[52:55], v[16:31]
	v_add_f32_e32 v48, v61, v60
	v_add_f32_e32 v48, v62, v48
	v_add_f32_e32 v48, v63, v48
	v_add_f32_e32 v48, v172, v48
	v_add_f32_e32 v48, v173, v48
	v_add_f32_e32 v48, v174, v48
	v_add_f32_e32 v48, v175, v48
	s_waitcnt lgkmcnt(0)
	v_mfma_f32_32x32x16_bf16 v[0:15], v[56:59], v[52:55], v[0:15]
	v_add_f32_e32 v238, 0, v48
	v_cmp_neq_f32_e32 vcc, 0xc2800000, v168
	s_mov_b64 s[6:7], vcc
	v_cmp_neq_f32_e32 vcc, 0x42800000, v169
	s_or_b64 vcc, vcc, s[6:7]
	s_cbranch_vccnz .Lattn2_slow
; #define LAS __attribute__((address_space(3)))
; __device__ __forceinline__ unsigned pk2(float lo, float hi) { f32x2_t v = {lo, hi}; bf16x2_t b = __builtin_convertvector(v, bf16x2_t); return __builtin_bit_cast(unsigned, b); }
; __device__ __forceinline__ s16x4 trrd(LAS const unsigned char* p) { return __builtin_bit_cast(s16x4, __builtin_amdgcn_ds_read_tr16_b64_v4i16((LAS v4i16_t*)p)); }
; __device__ __forceinline__ float attn_tile_exp(f32x16& st, int j, float tlf, float bsl, float rlo, float rhi) {
;     float sum = 0.f;
; #pragma unroll
;     for (int i = 0; i < 16; ++i) { const float tmp = (float)(32 * j - 64 + (i & 3) + 8 * (i >> 2)) + tlf;
;         float arg = __builtin_fmaf(-bsl, __builtin_fabsf(tmp), st[i]);
;         arg = (tmp >= rlo && tmp <= rhi) ? arg : -1.0e30f;
;         const float pe = __builtin_amdgcn_exp2f(arg); st[i] = pe; sum += pe; }
;     return sum;
; }
; template <bool FUSED> __device__ __forceinline__ void attn_phase(const Args& a, LAS unsigned char* lds, int tid, int lane, int wave) {
;     ...
; #pragma unroll
;         for (int j = 0; j < 5; ++j) {
;             f32x16 st;
; #pragma unroll
;             for (int i = 0; i < 16; ++i) st[i] = -mb;
;             LAS const unsigned char* kp = lds + (32 * wave + 32 * j + l31) * KP + 16 * h;
; #pragma unroll
;             for (int ks = 0; ks < 4; ++ks) { const bf16x8 kf = *(LAS const bf16x8*)(kp + 32 * ks); st = __builtin_amdgcn_mfma_f32_32x32x16_bf16(kf, qf[ks], st, 0, 0, 0); }
;             sum += attn_tile_exp(st, j, tlf, bsl, rlo, rhi);
; #pragma unroll
;             for (int s2 = 0; s2 < 2; ++s2) { u32x4 pw; pw.x = pk2(st[8 * s2 + 0], st[8 * s2 + 1]); pw.y = pk2(st[8 * s2 + 2], st[8 * s2 + 3]); pw.z = pk2(st[8 * s2 + 4], st[8 * s2 + 5]); pw.w = pk2(st[8 * s2 + 6], st[8 * s2 + 7]);
;                 const bf16x8 pf = __builtin_bit_cast(bf16x8, pw);
;                 LAS const unsigned char* vp = lds + LDS_VOFF + (32 * wave + 32 * j + 16 * s2 + 4 * h + q) * VP + 32 * blk + 8 * p;
; #pragma unroll
;                 for (int dt = 0; dt < 2; ++dt) { const s16x4 lo = trrd(vp + dt * 64), hi = trrd(vp + 8 * VP + dt * 64);
;                     const bf16x8 vf = __builtin_shufflevector(lo, hi, 0, 1, 2, 3, 4, 5, 6, 7);
;                     o[dt] = __builtin_amdgcn_mfma_f32_32x32x16_bf16(vf, pf, o[dt], 0, 0, 0); } }
	ds_read_b128 v[172:175], v208
	ds_read_b128 v[230:233], v208 offset:32
	v_add_f32_e32 v239, 0xc2000000, v171
	v_add_f32_e32 v240, 0xc1f80000, v171
	s_waitcnt lgkmcnt(1)
	v_mfma_f32_32x32x16_bf16 v[48:63], v[172:175], v[96:99], v[32:47]
	ds_read_b128 v[172:175], v208 offset:64
	ds_read_b128 v[234:237], v208 offset:96
	v_add_f32_e32 v241, 0xc1f00000, v171
	v_add_f32_e32 v242, 0xc1e80000, v171
	s_waitcnt lgkmcnt(2)
	v_mfma_f32_32x32x16_bf16 v[48:63], v[230:233], v[100:103], v[48:63]
	v_add_f32_e32 v230, 0xc1c00000, v171
	v_add_f32_e32 v231, 0xc1b80000, v171
	s_waitcnt lgkmcnt(1)
	v_mfma_f32_32x32x16_bf16 v[48:63], v[172:175], v[104:107], v[48:63]
	s_waitcnt lgkmcnt(0)
	v_mfma_f32_32x32x16_bf16 v[48:63], v[234:237], v[108:111], v[48:63]
	s_nop 11
	v_fma_f32 v48, v170, |v239|, v48
	v_fma_f32 v49, v170, |v240|, v49
	v_fma_f32 v50, v170, |v241|, v50
	v_fma_f32 v51, v170, |v242|, v51
	v_fma_f32 v52, v170, |v230|, v52
	v_fma_f32 v53, v170, |v231|, v53
	v_exp_f32_e32 v173, v49
	v_mov_b32_e32 v49, v53
	v_exp_f32_e32 v231, v49
	v_add_f32_e32 v49, 0xc1b00000, v171
	v_exp_f32_e32 v174, v50
	v_fma_f32 v49, v170, |v49|, v54
	v_exp_f32_e32 v172, v48
	v_exp_f32_e32 v232, v49
	v_add_f32_e32 v49, 0xc1a80000, v171
	v_fma_f32 v49, v170, |v49|, v55
	v_exp_f32_e32 v175, v51
	v_exp_f32_e32 v230, v52
	v_add_f32_e32 v48, 0, v172
	v_exp_f32_e32 v55, v49
	v_add_f32_e32 v49, 0xc1800000, v171
	v_add_f32_e32 v48, v173, v48
	v_add_f32_e32 v48, v174, v48
	v_fma_f32 v49, v170, |v49|, v56
	v_add_f32_e32 v48, v175, v48
	v_add_f32_e32 v48, v230, v48
	v_exp_f32_e32 v233, v49
	v_add_f32_e32 v48, v231, v48
	v_add_f32_e32 v48, v232, v48
	v_add_f32_e32 v48, v55, v48
	v_add_f32_e32 v234, v233, v48
	v_add_f32_e32 v48, 0xc1700000, v171
	v_fma_f32 v48, v170, |v48|, v57
	v_exp_f32_e32 v235, v48
	v_add_f32_e32 v48, 0xc1600000, v171
	v_fma_f32 v48, v170, |v48|, v58
	v_exp_f32_e32 v236, v48
	v_add_f32_e32 v48, 0xc1500000, v171
	v_fma_f32 v48, v170, |v48|, v59
	v_exp_f32_e32 v237, v48
	v_add_f32_e32 v48, 0xc1000000, v171
	v_fma_f32 v48, v170, |v48|, v60
	v_exp_f32_e32 v60, v48
	v_add_f32_e32 v48, 0xc0e00000, v171
	v_fma_f32 v48, v170, |v48|, v61
	v_exp_f32_e32 v61, v48
	v_add_f32_e32 v48, 0xc0c00000, v171
	v_fma_f32 v52, v170, |v48|, v62
	ds_read_b64_tr_b16 v[48:49], v209 offset:55296
	ds_read_b64_tr_b16 v[50:51], v209 offset:56832
	ds_read_b64_tr_b16 v[58:59], v209 offset:56896
	ds_read_b64_tr_b16 v[56:57], v209 offset:55360
	v_exp_f32_e32 v62, v52
	v_add_f32_e32 v239, 0xc0a00000, v171
	v_cvt_pk_bf16_f32 v52, v172, v173
	v_cvt_pk_bf16_f32 v53, v174, v175
	v_cvt_pk_bf16_f32 v54, v230, v231
	v_cvt_pk_bf16_f32 v55, v232, v55
	s_waitcnt lgkmcnt(2)
	s_nop 0
	v_mfma_f32_32x32x16_bf16 v[16:31], v[48:51], v[52:55], v[16:31]
	v_fma_f32 v63, v170, |v239|, v63
	ds_read_b64_tr_b16 v[48:49], v209 offset:58368
	ds_read_b64_tr_b16 v[50:51], v209 offset:59904
	v_exp_f32_e32 v63, v63
	s_waitcnt lgkmcnt(2)
	v_mfma_f32_32x32x16_bf16 v[0:15], v[56:59], v[52:55], v[0:15]
	ds_read_b64_tr_b16 v[58:59], v209 offset:59968
	ds_read_b64_tr_b16 v[56:57], v209 offset:58432
	v_cvt_pk_bf16_f32 v52, v233, v235
	v_cvt_pk_bf16_f32 v53, v236, v237
	v_cvt_pk_bf16_f32 v54, v60, v61
	v_cvt_pk_bf16_f32 v55, v62, v63
	s_waitcnt lgkmcnt(2)
	s_nop 0
	v_mfma_f32_32x32x16_bf16 v[16:31], v[48:51], v[52:55], v[16:31]
	v_add_f32_e32 v48, v235, v234
	v_add_f32_e32 v48, v236, v48
	v_add_f32_e32 v48, v237, v48
	v_add_f32_e32 v48, v60, v48
	v_add_f32_e32 v48, v61, v48
	v_add_f32_e32 v48, v62, v48
	v_add_f32_e32 v48, v63, v48
	s_waitcnt lgkmcnt(0)
	v_mfma_f32_32x32x16_bf16 v[0:15], v[56:59], v[52:55], v[0:15]
	v_add_f32_e32 v238, v238, v48
	ds_read_b128 v[172:175], v210
	ds_read_b128 v[230:233], v210 offset:32
	v_add_f32_e32 v239, 1.0, v171
	s_waitcnt lgkmcnt(1)
	v_mfma_f32_32x32x16_bf16 v[48:63], v[172:175], v[96:99], v[32:47]
	ds_read_b128 v[172:175], v210 offset:64
	ds_read_b128 v[234:237], v210 offset:96
	s_waitcnt lgkmcnt(2)
	v_mfma_f32_32x32x16_bf16 v[48:63], v[230:233], v[100:103], v[48:63]
	v_add_f32_e32 v230, 2.0, v171
	v_add_f32_e32 v231, 0x40400000, v171
	v_add_f32_e32 v232, 0x41000000, v171
	s_waitcnt lgkmcnt(1)
	v_mfma_f32_32x32x16_bf16 v[48:63], v[172:175], v[104:107], v[48:63]
	v_add_f32_e32 v233, 0x41100000, v171
	s_waitcnt lgkmcnt(0)
	v_mfma_f32_32x32x16_bf16 v[48:63], v[234:237], v[108:111], v[48:63]
	s_nop 11
	v_fma_f32 v48, v170, |v171|, v48
	v_fma_f32 v49, v170, |v239|, v49
	v_fma_f32 v50, v170, |v230|, v50
	v_fma_f32 v51, v170, |v231|, v51
	v_fma_f32 v52, v170, |v232|, v52
	v_fma_f32 v53, v170, |v233|, v53
	v_exp_f32_e32 v173, v49
	v_mov_b32_e32 v49, v53
	v_exp_f32_e32 v231, v49
	v_add_f32_e32 v49, 0x41200000, v171
	v_exp_f32_e32 v174, v50
	v_fma_f32 v49, v170, |v49|, v54
	v_exp_f32_e32 v172, v48
	v_exp_f32_e32 v232, v49
	v_add_f32_e32 v49, 0x41300000, v171
	v_fma_f32 v49, v170, |v49|, v55
	v_exp_f32_e32 v175, v51
	v_exp_f32_e32 v230, v52
	v_add_f32_e32 v48, 0, v172
	v_exp_f32_e32 v55, v49
	v_add_f32_e32 v49, 0x41800000, v171
	v_add_f32_e32 v48, v173, v48
	v_add_f32_e32 v48, v174, v48
	v_fma_f32 v49, v170, |v49|, v56
	v_add_f32_e32 v48, v175, v48
	v_add_f32_e32 v48, v230, v48
	v_exp_f32_e32 v233, v49
	v_add_f32_e32 v48, v231, v48
	v_add_f32_e32 v48, v232, v48
	v_add_f32_e32 v48, v55, v48
	v_add_f32_e32 v234, v233, v48
	v_add_f32_e32 v48, 0x41880000, v171
	v_fma_f32 v48, v170, |v48|, v57
	v_exp_f32_e32 v235, v48
	v_add_f32_e32 v48, 0x41900000, v171
	v_fma_f32 v48, v170, |v48|, v58
	v_exp_f32_e32 v236, v48
	v_add_f32_e32 v48, 0x41980000, v171
	v_fma_f32 v48, v170, |v48|, v59
	v_exp_f32_e32 v237, v48
	v_add_f32_e32 v48, 0x41c00000, v171
	v_fma_f32 v48, v170, |v48|, v60
	v_exp_f32_e32 v60, v48
	v_add_f32_e32 v48, 0x41c80000, v171
	v_fma_f32 v48, v170, |v48|, v61
	v_exp_f32_e32 v61, v48
	v_add_f32_e32 v48, 0x41d00000, v171
	v_fma_f32 v52, v170, |v48|, v62
	ds_read_b64_tr_b16 v[48:49], v211 offset:55296
	ds_read_b64_tr_b16 v[50:51], v211 offset:56832
	ds_read_b64_tr_b16 v[58:59], v211 offset:56896
	ds_read_b64_tr_b16 v[56:57], v211 offset:55360
	v_exp_f32_e32 v62, v52
	v_add_f32_e32 v239, 0x41d80000, v171
	v_cvt_pk_bf16_f32 v52, v172, v173
	v_cvt_pk_bf16_f32 v53, v174, v175
	v_cvt_pk_bf16_f32 v54, v230, v231
	v_cvt_pk_bf16_f32 v55, v232, v55
	s_waitcnt lgkmcnt(2)
; #define LAS __attribute__((address_space(3)))
; __device__ __forceinline__ unsigned pk2(float lo, float hi) { f32x2_t v = {lo, hi}; bf16x2_t b = __builtin_convertvector(v, bf16x2_t); return __builtin_bit_cast(unsigned, b); }
; __device__ __forceinline__ s16x4 trrd(LAS const unsigned char* p) { return __builtin_bit_cast(s16x4, __builtin_amdgcn_ds_read_tr16_b64_v4i16((LAS v4i16_t*)p)); }
; __device__ __forceinline__ float attn_tile_exp(f32x16& st, int j, float tlf, float bsl, float rlo, float rhi) {
;     float sum = 0.f;
; #pragma unroll
;     for (int i = 0; i < 16; ++i) { const float tmp = (float)(32 * j - 64 + (i & 3) + 8 * (i >> 2)) + tlf;
;         float arg = __builtin_fmaf(-bsl, __builtin_fabsf(tmp), st[i]);
;         arg = (tmp >= rlo && tmp <= rhi) ? arg : -1.0e30f;
;         const float pe = __builtin_amdgcn_exp2f(arg); st[i] = pe; sum += pe; }
;     return sum;
; }
; template <bool FUSED> __device__ __forceinline__ void attn_phase(const Args& a, LAS unsigned char* lds, int tid, int lane, int wave) {
;     ...
; #pragma unroll
;         for (int j = 0; j < 5; ++j) {
;             f32x16 st;
; #pragma unroll
;             for (int i = 0; i < 16; ++i) st[i] = -mb;
;             LAS const unsigned char* kp = lds + (32 * wave + 32 * j + l31) * KP + 16 * h;
; #pragma unroll
;             for (int ks = 0; ks < 4; ++ks) { const bf16x8 kf = *(LAS const bf16x8*)(kp + 32 * ks); st = __builtin_amdgcn_mfma_f32_32x32x16_bf16(kf, qf[ks], st, 0, 0, 0); }
;             sum += attn_tile_exp(st, j, tlf, bsl, rlo, rhi);
; #pragma unroll
;             for (int s2 = 0; s2 < 2; ++s2) { u32x4 pw; pw.x = pk2(st[8 * s2 + 0], st[8 * s2 + 1]); pw.y = pk2(st[8 * s2 + 2], st[8 * s2 + 3]); pw.z = pk2(st[8 * s2 + 4], st[8 * s2 + 5]); pw.w = pk2(st[8 * s2 + 6], st[8 * s2 + 7]);
;                 const bf16x8 pf = __builtin_bit_cast(bf16x8, pw);
;                 LAS const unsigned char* vp = lds + LDS_VOFF + (32 * wave + 32 * j + 16 * s2 + 4 * h + q) * VP + 32 * blk + 8 * p;
; #pragma unroll
;                 for (int dt = 0; dt < 2; ++dt) { const s16x4 lo = trrd(vp + dt * 64), hi = trrd(vp + 8 * VP + dt * 64);
;                     const bf16x8 vf = __builtin_shufflevector(lo, hi, 0, 1, 2, 3, 4, 5, 6, 7);
;                     o[dt] = __builtin_amdgcn_mfma_f32_32x32x16_bf16(vf, pf, o[dt], 0, 0, 0); } }
;             __builtin_amdgcn_sched_barrier(0);
;         }
	s_nop 0
	v_mfma_f32_32x32x16_bf16 v[16:31], v[48:51], v[52:55], v[16:31]
	v_fma_f32 v63, v170, |v239|, v63
	ds_read_b64_tr_b16 v[48:49], v211 offset:58368
	ds_read_b64_tr_b16 v[50:51], v211 offset:59904
	v_exp_f32_e32 v63, v63
	s_waitcnt lgkmcnt(2)
	v_mfma_f32_32x32x16_bf16 v[0:15], v[56:59], v[52:55], v[0:15]
	ds_read_b64_tr_b16 v[58:59], v211 offset:59968
	ds_read_b64_tr_b16 v[56:57], v211 offset:58432
	v_cvt_pk_bf16_f32 v52, v233, v235
	v_cvt_pk_bf16_f32 v53, v236, v237
	v_cvt_pk_bf16_f32 v54, v60, v61
	v_cvt_pk_bf16_f32 v55, v62, v63
	s_waitcnt lgkmcnt(2)
	s_nop 0
	v_mfma_f32_32x32x16_bf16 v[16:31], v[48:51], v[52:55], v[16:31]
	v_add_f32_e32 v48, v235, v234
	v_add_f32_e32 v48, v236, v48
	v_add_f32_e32 v48, v237, v48
	v_add_f32_e32 v48, v60, v48
	v_add_f32_e32 v48, v61, v48
	v_add_f32_e32 v48, v62, v48
	v_add_f32_e32 v48, v63, v48
	s_waitcnt lgkmcnt(0)
	v_mfma_f32_32x32x16_bf16 v[0:15], v[56:59], v[52:55], v[0:15]
	v_add_f32_e32 v238, v238, v48
	ds_read_b128 v[172:175], v212
	ds_read_b128 v[230:233], v212 offset:32
	v_add_f32_e32 v239, 0x42000000, v171
	v_add_f32_e32 v240, 0x42040000, v171
	s_waitcnt lgkmcnt(1)
	v_mfma_f32_32x32x16_bf16 v[48:63], v[172:175], v[96:99], v[32:47]
	ds_read_b128 v[172:175], v212 offset:64
	ds_read_b128 v[234:237], v212 offset:96
	v_add_f32_e32 v241, 0x42080000, v171
	v_add_f32_e32 v242, 0x420c0000, v171
	s_waitcnt lgkmcnt(2)
	v_mfma_f32_32x32x16_bf16 v[48:63], v[230:233], v[100:103], v[48:63]
	v_add_f32_e32 v230, 0x42200000, v171
	v_add_f32_e32 v231, 0x42240000, v171
	s_waitcnt lgkmcnt(1)
	v_mfma_f32_32x32x16_bf16 v[48:63], v[172:175], v[104:107], v[48:63]
	s_waitcnt lgkmcnt(0)
	v_mfma_f32_32x32x16_bf16 v[48:63], v[234:237], v[108:111], v[48:63]
	s_nop 11
	v_fma_f32 v48, v170, |v239|, v48
	v_fma_f32 v49, v170, |v240|, v49
	v_fma_f32 v50, v170, |v241|, v50
	v_fma_f32 v51, v170, |v242|, v51
	v_fma_f32 v52, v170, |v230|, v52
	v_fma_f32 v53, v170, |v231|, v53
	v_exp_f32_e32 v173, v49
	v_mov_b32_e32 v49, v53
	v_exp_f32_e32 v231, v49
	v_add_f32_e32 v49, 0x42280000, v171
	v_exp_f32_e32 v174, v50
	v_fma_f32 v49, v170, |v49|, v54
	v_exp_f32_e32 v172, v48
	v_exp_f32_e32 v232, v49
	v_add_f32_e32 v49, 0x422c0000, v171
	v_fma_f32 v49, v170, |v49|, v55
	v_exp_f32_e32 v175, v51
	v_exp_f32_e32 v230, v52
	v_add_f32_e32 v48, 0, v172
	v_exp_f32_e32 v55, v49
	v_add_f32_e32 v49, 0x42400000, v171
	v_add_f32_e32 v48, v173, v48
	v_add_f32_e32 v48, v174, v48
	v_fma_f32 v49, v170, |v49|, v56
	v_add_f32_e32 v48, v175, v48
	v_add_f32_e32 v48, v230, v48
	v_exp_f32_e32 v233, v49
	v_add_f32_e32 v48, v231, v48
	v_add_f32_e32 v48, v232, v48
	v_add_f32_e32 v48, v55, v48
	v_add_f32_e32 v234, v233, v48
	v_add_f32_e32 v48, 0x42440000, v171
	v_fma_f32 v48, v170, |v48|, v57
	v_exp_f32_e32 v235, v48
	v_add_f32_e32 v48, 0x42480000, v171
	v_fma_f32 v48, v170, |v48|, v58
	v_exp_f32_e32 v236, v48
	v_add_f32_e32 v48, 0x424c0000, v171
	v_fma_f32 v48, v170, |v48|, v59
	v_exp_f32_e32 v237, v48
	v_add_f32_e32 v48, 0x42600000, v171
	v_fma_f32 v48, v170, |v48|, v60
	v_exp_f32_e32 v60, v48
	v_add_f32_e32 v48, 0x42640000, v171
	v_fma_f32 v48, v170, |v48|, v61
	v_exp_f32_e32 v61, v48
	v_add_f32_e32 v48, 0x42680000, v171
	v_fma_f32 v52, v170, |v48|, v62
	ds_read_b64_tr_b16 v[48:49], v213 offset:55296
	ds_read_b64_tr_b16 v[50:51], v213 offset:56832
	ds_read_b64_tr_b16 v[58:59], v213 offset:56896
	ds_read_b64_tr_b16 v[56:57], v213 offset:55360
	v_exp_f32_e32 v62, v52
	v_add_f32_e32 v239, 0x426c0000, v171
	v_cvt_pk_bf16_f32 v52, v172, v173
	v_cvt_pk_bf16_f32 v53, v174, v175
	v_cvt_pk_bf16_f32 v54, v230, v231
	v_cvt_pk_bf16_f32 v55, v232, v55
	s_waitcnt lgkmcnt(2)
	s_nop 0
	v_mfma_f32_32x32x16_bf16 v[16:31], v[48:51], v[52:55], v[16:31]
	v_fma_f32 v63, v170, |v239|, v63
	ds_read_b64_tr_b16 v[48:49], v213 offset:58368
	ds_read_b64_tr_b16 v[50:51], v213 offset:59904
	v_exp_f32_e32 v63, v63
	s_waitcnt lgkmcnt(2)
	v_mfma_f32_32x32x16_bf16 v[0:15], v[56:59], v[52:55], v[0:15]
	ds_read_b64_tr_b16 v[58:59], v213 offset:59968
	ds_read_b64_tr_b16 v[56:57], v213 offset:58432
	v_cvt_pk_bf16_f32 v52, v233, v235
	v_cvt_pk_bf16_f32 v53, v236, v237
	v_cvt_pk_bf16_f32 v54, v60, v61
	v_cvt_pk_bf16_f32 v55, v62, v63
	s_waitcnt lgkmcnt(2)
	s_nop 0
	v_mfma_f32_32x32x16_bf16 v[16:31], v[48:51], v[52:55], v[16:31]
	v_add_f32_e32 v48, v235, v234
	v_add_f32_e32 v48, v236, v48
	v_add_f32_e32 v48, v237, v48
	v_add_f32_e32 v48, v60, v48
	v_add_f32_e32 v48, v61, v48
	v_add_f32_e32 v48, v62, v48
	v_add_f32_e32 v48, v63, v48
	s_waitcnt lgkmcnt(0)
	v_mfma_f32_32x32x16_bf16 v[0:15], v[56:59], v[52:55], v[0:15]
	v_add_f32_e32 v60, v238, v48
	s_branch .Lattn2_t4
; #define LAS __attribute__((address_space(3)))
; __device__ __forceinline__ unsigned pk2(float lo, float hi) { f32x2_t v = {lo, hi}; bf16x2_t b = __builtin_convertvector(v, bf16x2_t); return __builtin_bit_cast(unsigned, b); }
; __device__ __forceinline__ s16x4 trrd(LAS const unsigned char* p) { return __builtin_bit_cast(s16x4, __builtin_amdgcn_ds_read_tr16_b64_v4i16((LAS v4i16_t*)p)); }
; __device__ __forceinline__ float attn_tile_exp(f32x16& st, int j, float tlf, float bsl, float rlo, float rhi) {
;     float sum = 0.f;
; #pragma unroll
;     for (int i = 0; i < 16; ++i) { const float tmp = (float)(32 * j - 64 + (i & 3) + 8 * (i >> 2)) + tlf;
;         float arg = __builtin_fmaf(-bsl, __builtin_fabsf(tmp), st[i]);
;         arg = (tmp >= rlo && tmp <= rhi) ? arg : -1.0e30f;
;         const float pe = __builtin_amdgcn_exp2f(arg); st[i] = pe; sum += pe; }
;     return sum;
; }
; template <bool FUSED> __device__ __forceinline__ void attn_phase(const Args& a, LAS unsigned char* lds, int tid, int lane, int wave) {
;     ...
; #pragma unroll
;         for (int j = 0; j < 5; ++j) {
;             f32x16 st;
; #pragma unroll
;             for (int i = 0; i < 16; ++i) st[i] = -mb;
;             LAS const unsigned char* kp = lds + (32 * wave + 32 * j + l31) * KP + 16 * h;
; #pragma unroll
;             for (int ks = 0; ks < 4; ++ks) { const bf16x8 kf = *(LAS const bf16x8*)(kp + 32 * ks); st = __builtin_amdgcn_mfma_f32_32x32x16_bf16(kf, qf[ks], st, 0, 0, 0); }
;             sum += attn_tile_exp(st, j, tlf, bsl, rlo, rhi);
; #pragma unroll
;             for (int s2 = 0; s2 < 2; ++s2) { u32x4 pw; pw.x = pk2(st[8 * s2 + 0], st[8 * s2 + 1]); pw.y = pk2(st[8 * s2 + 2], st[8 * s2 + 3]); pw.z = pk2(st[8 * s2 + 4], st[8 * s2 + 5]); pw.w = pk2(st[8 * s2 + 6], st[8 * s2 + 7]);
;                 const bf16x8 pf = __builtin_bit_cast(bf16x8, pw);
;                 LAS const unsigned char* vp = lds + LDS_VOFF + (32 * wave + 32 * j + 16 * s2 + 4 * h + q) * VP + 32 * blk + 8 * p;
; #pragma unroll
;                 for (int dt = 0; dt < 2; ++dt) { const s16x4 lo = trrd(vp + dt * 64), hi = trrd(vp + 8 * VP + dt * 64);
;                     const bf16x8 vf = __builtin_shufflevector(lo, hi, 0, 1, 2, 3, 4, 5, 6, 7);
;                     o[dt] = __builtin_amdgcn_mfma_f32_32x32x16_bf16(vf, pf, o[dt], 0, 0, 0); } }
.Lattn2_slow:
	ds_read_b128 v[172:175], v208
	ds_read_b128 v[230:233], v208 offset:32
	v_add_f32_e32 v239, 0xc2000000, v171
	v_add_f32_e32 v240, 0xc1f80000, v171
	v_cmp_nge_f32_e32 vcc, v239, v168
	s_waitcnt lgkmcnt(1)
	v_mfma_f32_32x32x16_bf16 v[48:63], v[172:175], v[96:99], v[32:47]
	ds_read_b128 v[172:175], v208 offset:64
	ds_read_b128 v[234:237], v208 offset:96
	v_cmp_nle_f32_e64 s[6:7], v239, v169
	v_add_f32_e32 v241, 0xc1f00000, v171
	v_cmp_nge_f32_e64 s[8:9], v240, v168
	v_cmp_nle_f32_e64 s[10:11], v240, v169
	s_or_b64 vcc, vcc, s[6:7]
	v_add_f32_e32 v242, 0xc1e80000, v171
	s_waitcnt lgkmcnt(2)
	v_mfma_f32_32x32x16_bf16 v[48:63], v[230:233], v[100:103], v[48:63]
	v_cmp_nge_f32_e64 s[12:13], v241, v168
	v_cmp_nle_f32_e64 s[14:15], v241, v169
	v_add_f32_e32 v230, 0xc1c00000, v171
	v_cmp_nge_f32_e64 s[16:17], v242, v168
	v_cmp_nle_f32_e64 s[20:21], v242, v169
	v_add_f32_e32 v231, 0xc1b80000, v171
	v_cmp_nge_f32_e64 s[22:23], v230, v168
	s_waitcnt lgkmcnt(1)
	v_mfma_f32_32x32x16_bf16 v[48:63], v[172:175], v[104:107], v[48:63]
	v_cmp_nle_f32_e64 s[24:25], v230, v169
	v_cmp_nge_f32_e64 s[26:27], v231, v168
	v_cmp_nle_f32_e64 s[28:29], v231, v169
	s_waitcnt lgkmcnt(0)
	v_mfma_f32_32x32x16_bf16 v[48:63], v[234:237], v[108:111], v[48:63]
	s_nop 11
	v_fma_f32 v48, v170, |v239|, v48
	v_fma_f32 v49, v170, |v240|, v49
	v_cndmask_b32_e32 v48, v48, v228, vcc
	s_or_b64 vcc, s[8:9], s[10:11]
	v_fma_f32 v50, v170, |v241|, v50
	v_cndmask_b32_e32 v49, v49, v228, vcc
	s_or_b64 vcc, s[12:13], s[14:15]
	v_fma_f32 v51, v170, |v242|, v51
	v_cndmask_b32_e32 v50, v50, v228, vcc
	s_or_b64 vcc, s[16:17], s[20:21]
	v_fma_f32 v52, v170, |v230|, v52
	v_cndmask_b32_e32 v51, v51, v228, vcc
	s_or_b64 vcc, s[22:23], s[24:25]
	v_fma_f32 v53, v170, |v231|, v53
	v_cndmask_b32_e32 v52, v52, v228, vcc
	s_or_b64 vcc, s[26:27], s[28:29]
	v_exp_f32_e32 v173, v49
	v_cndmask_b32_e32 v49, v53, v228, vcc
	v_exp_f32_e32 v231, v49
	v_add_f32_e32 v49, 0xc1b00000, v171
	v_cmp_nge_f32_e32 vcc, v49, v168
	v_cmp_nle_f32_e64 s[6:7], v49, v169
	v_exp_f32_e32 v174, v50
	v_fma_f32 v50, v170, |v49|, v54
	s_or_b64 vcc, vcc, s[6:7]
	v_cndmask_b32_e32 v49, v50, v228, vcc
	v_exp_f32_e32 v172, v48
	v_exp_f32_e32 v232, v49
	v_add_f32_e32 v49, 0xc1a80000, v171
	v_cmp_nge_f32_e32 vcc, v49, v168
	v_cmp_nle_f32_e64 s[6:7], v49, v169
	v_fma_f32 v50, v170, |v49|, v55
	s_or_b64 vcc, vcc, s[6:7]
	v_exp_f32_e32 v175, v51
	v_cndmask_b32_e32 v49, v50, v228, vcc
	v_exp_f32_e32 v230, v52
	v_add_f32_e32 v48, 0, v172
	v_exp_f32_e32 v55, v49
	v_add_f32_e32 v49, 0xc1800000, v171
	v_add_f32_e32 v48, v173, v48
	v_cmp_nge_f32_e32 vcc, v49, v168
	v_cmp_nle_f32_e64 s[6:7], v49, v169
	v_add_f32_e32 v48, v174, v48
	v_fma_f32 v50, v170, |v49|, v56
	s_or_b64 vcc, vcc, s[6:7]
	v_add_f32_e32 v48, v175, v48
	v_cndmask_b32_e32 v49, v50, v228, vcc
	v_add_f32_e32 v48, v230, v48
	v_exp_f32_e32 v233, v49
	v_add_f32_e32 v48, v231, v48
	v_add_f32_e32 v48, v232, v48
	v_add_f32_e32 v48, v55, v48
	v_add_f32_e32 v234, v233, v48
	v_add_f32_e32 v48, 0xc1700000, v171
	v_cmp_nge_f32_e32 vcc, v48, v168
	v_cmp_nle_f32_e64 s[6:7], v48, v169
	v_fma_f32 v49, v170, |v48|, v57
	s_or_b64 vcc, vcc, s[6:7]
	v_cndmask_b32_e32 v48, v49, v228, vcc
	v_exp_f32_e32 v235, v48
	v_add_f32_e32 v48, 0xc1600000, v171
	v_cmp_nge_f32_e32 vcc, v48, v168
	v_cmp_nle_f32_e64 s[6:7], v48, v169
	v_fma_f32 v49, v170, |v48|, v58
	s_or_b64 vcc, vcc, s[6:7]
	v_cndmask_b32_e32 v48, v49, v228, vcc
	v_exp_f32_e32 v236, v48
	v_add_f32_e32 v48, 0xc1500000, v171
	v_cmp_nge_f32_e32 vcc, v48, v168
	v_cmp_nle_f32_e64 s[6:7], v48, v169
	v_fma_f32 v49, v170, |v48|, v59
	s_or_b64 vcc, vcc, s[6:7]
	v_cndmask_b32_e32 v48, v49, v228, vcc
	v_exp_f32_e32 v237, v48
	v_add_f32_e32 v48, 0xc1000000, v171
	v_cmp_nge_f32_e32 vcc, v48, v168
	v_cmp_nle_f32_e64 s[6:7], v48, v169
	v_fma_f32 v49, v170, |v48|, v60
	s_or_b64 vcc, vcc, s[6:7]
	v_cndmask_b32_e32 v48, v49, v228, vcc
	v_exp_f32_e32 v60, v48
	v_add_f32_e32 v48, 0xc0e00000, v171
	v_cmp_nge_f32_e32 vcc, v48, v168
	v_cmp_nle_f32_e64 s[6:7], v48, v169
	v_fma_f32 v49, v170, |v48|, v61
	s_or_b64 vcc, vcc, s[6:7]
	v_cndmask_b32_e32 v48, v49, v228, vcc
	v_exp_f32_e32 v61, v48
	v_add_f32_e32 v48, 0xc0c00000, v171
	v_cmp_nge_f32_e32 vcc, v48, v168
	v_cmp_nle_f32_e64 s[6:7], v48, v169
	v_fma_f32 v49, v170, |v48|, v62
	s_or_b64 vcc, vcc, s[6:7]
	v_cndmask_b32_e32 v52, v49, v228, vcc
	ds_read_b64_tr_b16 v[48:49], v209 offset:55296
	ds_read_b64_tr_b16 v[50:51], v209 offset:56832
	ds_read_b64_tr_b16 v[58:59], v209 offset:56896
	ds_read_b64_tr_b16 v[56:57], v209 offset:55360
	v_exp_f32_e32 v62, v52
	v_add_f32_e32 v239, 0xc0a00000, v171
	v_cvt_pk_bf16_f32 v52, v172, v173
	v_cvt_pk_bf16_f32 v53, v174, v175
	v_cvt_pk_bf16_f32 v54, v230, v231
	v_cvt_pk_bf16_f32 v55, v232, v55
	v_cmp_nge_f32_e32 vcc, v239, v168
	v_cmp_nle_f32_e64 s[6:7], v239, v169
	s_waitcnt lgkmcnt(2)
	v_mfma_f32_32x32x16_bf16 v[16:31], v[48:51], v[52:55], v[16:31]
	v_fma_f32 v48, v170, |v239|, v63
	s_or_b64 vcc, vcc, s[6:7]
	v_cndmask_b32_e32 v63, v48, v228, vcc
	ds_read_b64_tr_b16 v[48:49], v209 offset:58368
	ds_read_b64_tr_b16 v[50:51], v209 offset:59904
	v_exp_f32_e32 v63, v63
	s_waitcnt lgkmcnt(2)
	v_mfma_f32_32x32x16_bf16 v[0:15], v[56:59], v[52:55], v[0:15]
	ds_read_b64_tr_b16 v[58:59], v209 offset:59968
	ds_read_b64_tr_b16 v[56:57], v209 offset:58432
	v_cvt_pk_bf16_f32 v52, v233, v235
	v_cvt_pk_bf16_f32 v53, v236, v237
	v_cvt_pk_bf16_f32 v54, v60, v61
	v_cvt_pk_bf16_f32 v55, v62, v63
	s_waitcnt lgkmcnt(2)
	s_nop 0
	v_mfma_f32_32x32x16_bf16 v[16:31], v[48:51], v[52:55], v[16:31]
	v_add_f32_e32 v48, v235, v234
	v_add_f32_e32 v48, v236, v48
	v_add_f32_e32 v48, v237, v48
	v_add_f32_e32 v48, v60, v48
	v_add_f32_e32 v48, v61, v48
	v_add_f32_e32 v48, v62, v48
	v_add_f32_e32 v48, v63, v48
	s_waitcnt lgkmcnt(0)
; #define LAS __attribute__((address_space(3)))
; __device__ __forceinline__ unsigned pk2(float lo, float hi) { f32x2_t v = {lo, hi}; bf16x2_t b = __builtin_convertvector(v, bf16x2_t); return __builtin_bit_cast(unsigned, b); }
; __device__ __forceinline__ s16x4 trrd(LAS const unsigned char* p) { return __builtin_bit_cast(s16x4, __builtin_amdgcn_ds_read_tr16_b64_v4i16((LAS v4i16_t*)p)); }
; __device__ __forceinline__ float attn_tile_exp(f32x16& st, int j, float tlf, float bsl, float rlo, float rhi) {
;     float sum = 0.f;
; #pragma unroll
;     for (int i = 0; i < 16; ++i) { const float tmp = (float)(32 * j - 64 + (i & 3) + 8 * (i >> 2)) + tlf;
;         float arg = __builtin_fmaf(-bsl, __builtin_fabsf(tmp), st[i]);
;         arg = (tmp >= rlo && tmp <= rhi) ? arg : -1.0e30f;
;         const float pe = __builtin_amdgcn_exp2f(arg); st[i] = pe; sum += pe; }
;     return sum;
; }
; template <bool FUSED> __device__ __forceinline__ void attn_phase(const Args& a, LAS unsigned char* lds, int tid, int lane, int wave) {
;     ...
; #pragma unroll
;         for (int j = 0; j < 5; ++j) {
;             f32x16 st;
; #pragma unroll
;             for (int i = 0; i < 16; ++i) st[i] = -mb;
;             LAS const unsigned char* kp = lds + (32 * wave + 32 * j + l31) * KP + 16 * h;
; #pragma unroll
;             for (int ks = 0; ks < 4; ++ks) { const bf16x8 kf = *(LAS const bf16x8*)(kp + 32 * ks); st = __builtin_amdgcn_mfma_f32_32x32x16_bf16(kf, qf[ks], st, 0, 0, 0); }
;             sum += attn_tile_exp(st, j, tlf, bsl, rlo, rhi);
; #pragma unroll
;             for (int s2 = 0; s2 < 2; ++s2) { u32x4 pw; pw.x = pk2(st[8 * s2 + 0], st[8 * s2 + 1]); pw.y = pk2(st[8 * s2 + 2], st[8 * s2 + 3]); pw.z = pk2(st[8 * s2 + 4], st[8 * s2 + 5]); pw.w = pk2(st[8 * s2 + 6], st[8 * s2 + 7]);
;                 const bf16x8 pf = __builtin_bit_cast(bf16x8, pw);
;                 LAS const unsigned char* vp = lds + LDS_VOFF + (32 * wave + 32 * j + 16 * s2 + 4 * h + q) * VP + 32 * blk + 8 * p;
; #pragma unroll
;                 for (int dt = 0; dt < 2; ++dt) { const s16x4 lo = trrd(vp + dt * 64), hi = trrd(vp + 8 * VP + dt * 64);
;                     const bf16x8 vf = __builtin_shufflevector(lo, hi, 0, 1, 2, 3, 4, 5, 6, 7);
;                     o[dt] = __builtin_amdgcn_mfma_f32_32x32x16_bf16(vf, pf, o[dt], 0, 0, 0); } }
	v_mfma_f32_32x32x16_bf16 v[0:15], v[56:59], v[52:55], v[0:15]
	v_add_f32_e32 v238, v238, v48
	ds_read_b128 v[172:175], v210
	ds_read_b128 v[230:233], v210 offset:32
	v_cmp_nge_f32_e32 vcc, v171, v168
	v_cmp_nle_f32_e64 s[6:7], v171, v169
	v_add_f32_e32 v239, 1.0, v171
	s_waitcnt lgkmcnt(1)
	v_mfma_f32_32x32x16_bf16 v[48:63], v[172:175], v[96:99], v[32:47]
	ds_read_b128 v[172:175], v210 offset:64
	ds_read_b128 v[234:237], v210 offset:96
	v_cmp_nge_f32_e64 s[8:9], v239, v168
	v_cmp_nle_f32_e64 s[10:11], v239, v169
	s_or_b64 vcc, vcc, s[6:7]
	s_waitcnt lgkmcnt(2)
	v_mfma_f32_32x32x16_bf16 v[48:63], v[230:233], v[100:103], v[48:63]
	v_add_f32_e32 v230, 2.0, v171
	v_add_f32_e32 v231, 0x40400000, v171
	v_cmp_nge_f32_e64 s[12:13], v230, v168
	v_cmp_nle_f32_e64 s[14:15], v230, v169
	v_add_f32_e32 v232, 0x41000000, v171
	v_cmp_nge_f32_e64 s[16:17], v231, v168
	v_cmp_nle_f32_e64 s[20:21], v231, v169
	s_waitcnt lgkmcnt(1)
	v_mfma_f32_32x32x16_bf16 v[48:63], v[172:175], v[104:107], v[48:63]
	v_add_f32_e32 v233, 0x41100000, v171
	v_cmp_nge_f32_e64 s[22:23], v232, v168
	v_cmp_nle_f32_e64 s[24:25], v232, v169
	v_cmp_nge_f32_e64 s[26:27], v233, v168
	v_cmp_nle_f32_e64 s[28:29], v233, v169
	s_waitcnt lgkmcnt(0)
	v_mfma_f32_32x32x16_bf16 v[48:63], v[234:237], v[108:111], v[48:63]
	s_nop 11
	v_fma_f32 v48, v170, |v171|, v48
	v_fma_f32 v49, v170, |v239|, v49
	v_cndmask_b32_e32 v48, v48, v228, vcc
	s_or_b64 vcc, s[8:9], s[10:11]
	v_fma_f32 v50, v170, |v230|, v50
	v_cndmask_b32_e32 v49, v49, v228, vcc
	s_or_b64 vcc, s[12:13], s[14:15]
	v_fma_f32 v51, v170, |v231|, v51
	v_cndmask_b32_e32 v50, v50, v228, vcc
	s_or_b64 vcc, s[16:17], s[20:21]
	v_fma_f32 v52, v170, |v232|, v52
	v_cndmask_b32_e32 v51, v51, v228, vcc
	s_or_b64 vcc, s[22:23], s[24:25]
	v_fma_f32 v53, v170, |v233|, v53
	v_cndmask_b32_e32 v52, v52, v228, vcc
	s_or_b64 vcc, s[26:27], s[28:29]
	v_exp_f32_e32 v173, v49
	v_cndmask_b32_e32 v49, v53, v228, vcc
	v_exp_f32_e32 v231, v49
	v_add_f32_e32 v49, 0x41200000, v171
	v_cmp_nge_f32_e32 vcc, v49, v168
	v_cmp_nle_f32_e64 s[6:7], v49, v169
	v_exp_f32_e32 v174, v50
	v_fma_f32 v50, v170, |v49|, v54
	s_or_b64 vcc, vcc, s[6:7]
	v_cndmask_b32_e32 v49, v50, v228, vcc
	v_exp_f32_e32 v172, v48
	v_exp_f32_e32 v232, v49
	v_add_f32_e32 v49, 0x41300000, v171
	v_cmp_nge_f32_e32 vcc, v49, v168
	v_cmp_nle_f32_e64 s[6:7], v49, v169
	v_fma_f32 v50, v170, |v49|, v55
	s_or_b64 vcc, vcc, s[6:7]
	v_exp_f32_e32 v175, v51
	v_cndmask_b32_e32 v49, v50, v228, vcc
	v_exp_f32_e32 v230, v52
	v_add_f32_e32 v48, 0, v172
	v_exp_f32_e32 v55, v49
	v_add_f32_e32 v49, 0x41800000, v171
	v_add_f32_e32 v48, v173, v48
	v_cmp_nge_f32_e32 vcc, v49, v168
	v_cmp_nle_f32_e64 s[6:7], v49, v169
	v_add_f32_e32 v48, v174, v48
	v_fma_f32 v50, v170, |v49|, v56
	s_or_b64 vcc, vcc, s[6:7]
	v_add_f32_e32 v48, v175, v48
	v_cndmask_b32_e32 v49, v50, v228, vcc
	v_add_f32_e32 v48, v230, v48
	v_exp_f32_e32 v233, v49
	v_add_f32_e32 v48, v231, v48
	v_add_f32_e32 v48, v232, v48
	v_add_f32_e32 v48, v55, v48
	v_add_f32_e32 v234, v233, v48
	v_add_f32_e32 v48, 0x41880000, v171
	v_cmp_nge_f32_e32 vcc, v48, v168
	v_cmp_nle_f32_e64 s[6:7], v48, v169
	v_fma_f32 v49, v170, |v48|, v57
	s_or_b64 vcc, vcc, s[6:7]
	v_cndmask_b32_e32 v48, v49, v228, vcc
	v_exp_f32_e32 v235, v48
	v_add_f32_e32 v48, 0x41900000, v171
	v_cmp_nge_f32_e32 vcc, v48, v168
	v_cmp_nle_f32_e64 s[6:7], v48, v169
	v_fma_f32 v49, v170, |v48|, v58
	s_or_b64 vcc, vcc, s[6:7]
	v_cndmask_b32_e32 v48, v49, v228, vcc
	v_exp_f32_e32 v236, v48
	v_add_f32_e32 v48, 0x41980000, v171
	v_cmp_nge_f32_e32 vcc, v48, v168
	v_cmp_nle_f32_e64 s[6:7], v48, v169
	v_fma_f32 v49, v170, |v48|, v59
	s_or_b64 vcc, vcc, s[6:7]
	v_cndmask_b32_e32 v48, v49, v228, vcc
	v_exp_f32_e32 v237, v48
	v_add_f32_e32 v48, 0x41c00000, v171
	v_cmp_nge_f32_e32 vcc, v48, v168
	v_cmp_nle_f32_e64 s[6:7], v48, v169
	v_fma_f32 v49, v170, |v48|, v60
	s_or_b64 vcc, vcc, s[6:7]
	v_cndmask_b32_e32 v48, v49, v228, vcc
	v_exp_f32_e32 v60, v48
	v_add_f32_e32 v48, 0x41c80000, v171
	v_cmp_nge_f32_e32 vcc, v48, v168
	v_cmp_nle_f32_e64 s[6:7], v48, v169
	v_fma_f32 v49, v170, |v48|, v61
	s_or_b64 vcc, vcc, s[6:7]
	v_cndmask_b32_e32 v48, v49, v228, vcc
	v_exp_f32_e32 v61, v48
	v_add_f32_e32 v48, 0x41d00000, v171
	v_cmp_nge_f32_e32 vcc, v48, v168
	v_cmp_nle_f32_e64 s[6:7], v48, v169
	v_fma_f32 v49, v170, |v48|, v62
	s_or_b64 vcc, vcc, s[6:7]
	v_cndmask_b32_e32 v52, v49, v228, vcc
	ds_read_b64_tr_b16 v[48:49], v211 offset:55296
	ds_read_b64_tr_b16 v[50:51], v211 offset:56832
	ds_read_b64_tr_b16 v[58:59], v211 offset:56896
	ds_read_b64_tr_b16 v[56:57], v211 offset:55360
	v_exp_f32_e32 v62, v52
	v_add_f32_e32 v239, 0x41d80000, v171
	v_cvt_pk_bf16_f32 v52, v172, v173
	v_cvt_pk_bf16_f32 v53, v174, v175
	v_cvt_pk_bf16_f32 v54, v230, v231
	v_cvt_pk_bf16_f32 v55, v232, v55
	v_cmp_nge_f32_e32 vcc, v239, v168
	v_cmp_nle_f32_e64 s[6:7], v239, v169
	s_waitcnt lgkmcnt(2)
	v_mfma_f32_32x32x16_bf16 v[16:31], v[48:51], v[52:55], v[16:31]
	v_fma_f32 v48, v170, |v239|, v63
	s_or_b64 vcc, vcc, s[6:7]
	v_cndmask_b32_e32 v63, v48, v228, vcc
	ds_read_b64_tr_b16 v[48:49], v211 offset:58368
	ds_read_b64_tr_b16 v[50:51], v211 offset:59904
	v_exp_f32_e32 v63, v63
	s_waitcnt lgkmcnt(2)
	v_mfma_f32_32x32x16_bf16 v[0:15], v[56:59], v[52:55], v[0:15]
	ds_read_b64_tr_b16 v[58:59], v211 offset:59968
	ds_read_b64_tr_b16 v[56:57], v211 offset:58432
	v_cvt_pk_bf16_f32 v52, v233, v235
	v_cvt_pk_bf16_f32 v53, v236, v237
	v_cvt_pk_bf16_f32 v54, v60, v61
	v_cvt_pk_bf16_f32 v55, v62, v63
	s_waitcnt lgkmcnt(2)
; #define LAS __attribute__((address_space(3)))
; __device__ __forceinline__ unsigned pk2(float lo, float hi) { f32x2_t v = {lo, hi}; bf16x2_t b = __builtin_convertvector(v, bf16x2_t); return __builtin_bit_cast(unsigned, b); }
; __device__ __forceinline__ s16x4 trrd(LAS const unsigned char* p) { return __builtin_bit_cast(s16x4, __builtin_amdgcn_ds_read_tr16_b64_v4i16((LAS v4i16_t*)p)); }
; __device__ __forceinline__ float attn_tile_exp(f32x16& st, int j, float tlf, float bsl, float rlo, float rhi) {
;     float sum = 0.f;
; #pragma unroll
;     for (int i = 0; i < 16; ++i) { const float tmp = (float)(32 * j - 64 + (i & 3) + 8 * (i >> 2)) + tlf;
;         float arg = __builtin_fmaf(-bsl, __builtin_fabsf(tmp), st[i]);
;         arg = (tmp >= rlo && tmp <= rhi) ? arg : -1.0e30f;
;         const float pe = __builtin_amdgcn_exp2f(arg); st[i] = pe; sum += pe; }
;     return sum;
; template <bool FUSED> __device__ __forceinline__ void attn_phase(const Args& a, LAS unsigned char* lds, int tid, int lane, int wave) {
;     ...
;         for (int j = 0; j < 5; ++j) {
;             f32x16 st;
; #pragma unroll
;             for (int i = 0; i < 16; ++i) st[i] = -mb;
;             LAS const unsigned char* kp = lds + (32 * wave + 32 * j + l31) * KP + 16 * h;
; #pragma unroll
;             for (int ks = 0; ks < 4; ++ks) { const bf16x8 kf = *(LAS const bf16x8*)(kp + 32 * ks); st = __builtin_amdgcn_mfma_f32_32x32x16_bf16(kf, qf[ks], st, 0, 0, 0); }
;             sum += attn_tile_exp(st, j, tlf, bsl, rlo, rhi);
; #pragma unroll
;             for (int s2 = 0; s2 < 2; ++s2) { u32x4 pw; pw.x = pk2(st[8 * s2 + 0], st[8 * s2 + 1]); pw.y = pk2(st[8 * s2 + 2], st[8 * s2 + 3]); pw.z = pk2(st[8 * s2 + 4], st[8 * s2 + 5]); pw.w = pk2(st[8 * s2 + 6], st[8 * s2 + 7]);
;                 const bf16x8 pf = __builtin_bit_cast(bf16x8, pw);
;                 LAS const unsigned char* vp = lds + LDS_VOFF + (32 * wave + 32 * j + 16 * s2 + 4 * h + q) * VP + 32 * blk + 8 * p;
; #pragma unroll
;                 for (int dt = 0; dt < 2; ++dt) { const s16x4 lo = trrd(vp + dt * 64), hi = trrd(vp + 8 * VP + dt * 64);
;                     const bf16x8 vf = __builtin_shufflevector(lo, hi, 0, 1, 2, 3, 4, 5, 6, 7);
;                     o[dt] = __builtin_amdgcn_mfma_f32_32x32x16_bf16(vf, pf, o[dt], 0, 0, 0); } }
;             __builtin_amdgcn_sched_barrier(0);
;         }
	s_nop 0
	v_mfma_f32_32x32x16_bf16 v[16:31], v[48:51], v[52:55], v[16:31]
	v_add_f32_e32 v48, v235, v234
	v_add_f32_e32 v48, v236, v48
	v_add_f32_e32 v48, v237, v48
	v_add_f32_e32 v48, v60, v48
	v_add_f32_e32 v48, v61, v48
	v_add_f32_e32 v48, v62, v48
	v_add_f32_e32 v48, v63, v48
	s_waitcnt lgkmcnt(0)
	v_mfma_f32_32x32x16_bf16 v[0:15], v[56:59], v[52:55], v[0:15]
	v_add_f32_e32 v238, v238, v48
	ds_read_b128 v[172:175], v212
	ds_read_b128 v[230:233], v212 offset:32
	v_add_f32_e32 v239, 0x42000000, v171
	v_add_f32_e32 v240, 0x42040000, v171
	v_cmp_nge_f32_e32 vcc, v239, v168
	s_waitcnt lgkmcnt(1)
	v_mfma_f32_32x32x16_bf16 v[48:63], v[172:175], v[96:99], v[32:47]
	ds_read_b128 v[172:175], v212 offset:64
	ds_read_b128 v[234:237], v212 offset:96
	v_cmp_nle_f32_e64 s[6:7], v239, v169
	v_add_f32_e32 v241, 0x42080000, v171
	v_cmp_nge_f32_e64 s[8:9], v240, v168
	v_cmp_nle_f32_e64 s[10:11], v240, v169
	s_or_b64 vcc, vcc, s[6:7]
	v_add_f32_e32 v242, 0x420c0000, v171
	s_waitcnt lgkmcnt(2)
	v_mfma_f32_32x32x16_bf16 v[48:63], v[230:233], v[100:103], v[48:63]
	v_cmp_nge_f32_e64 s[12:13], v241, v168
	v_cmp_nle_f32_e64 s[14:15], v241, v169
	v_add_f32_e32 v230, 0x42200000, v171
	v_cmp_nge_f32_e64 s[16:17], v242, v168
	v_cmp_nle_f32_e64 s[20:21], v242, v169
	v_add_f32_e32 v231, 0x42240000, v171
	v_cmp_nge_f32_e64 s[22:23], v230, v168
	s_waitcnt lgkmcnt(1)
	v_mfma_f32_32x32x16_bf16 v[48:63], v[172:175], v[104:107], v[48:63]
	v_cmp_nle_f32_e64 s[24:25], v230, v169
	v_cmp_nge_f32_e64 s[26:27], v231, v168
	v_cmp_nle_f32_e64 s[28:29], v231, v169
	s_waitcnt lgkmcnt(0)
	v_mfma_f32_32x32x16_bf16 v[48:63], v[234:237], v[108:111], v[48:63]
	s_nop 11
	v_fma_f32 v48, v170, |v239|, v48
	v_fma_f32 v49, v170, |v240|, v49
	v_cndmask_b32_e32 v48, v48, v228, vcc
	s_or_b64 vcc, s[8:9], s[10:11]
	v_fma_f32 v50, v170, |v241|, v50
	v_cndmask_b32_e32 v49, v49, v228, vcc
	s_or_b64 vcc, s[12:13], s[14:15]
	v_fma_f32 v51, v170, |v242|, v51
	v_cndmask_b32_e32 v50, v50, v228, vcc
	s_or_b64 vcc, s[16:17], s[20:21]
	v_fma_f32 v52, v170, |v230|, v52
	v_cndmask_b32_e32 v51, v51, v228, vcc
	s_or_b64 vcc, s[22:23], s[24:25]
	v_fma_f32 v53, v170, |v231|, v53
	v_cndmask_b32_e32 v52, v52, v228, vcc
	s_or_b64 vcc, s[26:27], s[28:29]
	v_exp_f32_e32 v173, v49
	v_cndmask_b32_e32 v49, v53, v228, vcc
	v_exp_f32_e32 v231, v49
	v_add_f32_e32 v49, 0x42280000, v171
	v_cmp_nge_f32_e32 vcc, v49, v168
	v_cmp_nle_f32_e64 s[6:7], v49, v169
	v_exp_f32_e32 v174, v50
	v_fma_f32 v50, v170, |v49|, v54
	s_or_b64 vcc, vcc, s[6:7]
	v_cndmask_b32_e32 v49, v50, v228, vcc
	v_exp_f32_e32 v172, v48
	v_exp_f32_e32 v232, v49
	v_add_f32_e32 v49, 0x422c0000, v171
	v_cmp_nge_f32_e32 vcc, v49, v168
	v_cmp_nle_f32_e64 s[6:7], v49, v169
	v_fma_f32 v50, v170, |v49|, v55
	s_or_b64 vcc, vcc, s[6:7]
	v_exp_f32_e32 v175, v51
	v_cndmask_b32_e32 v49, v50, v228, vcc
	v_exp_f32_e32 v230, v52
	v_add_f32_e32 v48, 0, v172
	v_exp_f32_e32 v55, v49
	v_add_f32_e32 v49, 0x42400000, v171
	v_add_f32_e32 v48, v173, v48
	v_cmp_nge_f32_e32 vcc, v49, v168
	v_cmp_nle_f32_e64 s[6:7], v49, v169
	v_add_f32_e32 v48, v174, v48
	v_fma_f32 v50, v170, |v49|, v56
	s_or_b64 vcc, vcc, s[6:7]
	v_add_f32_e32 v48, v175, v48
	v_cndmask_b32_e32 v49, v50, v228, vcc
	v_add_f32_e32 v48, v230, v48
	v_exp_f32_e32 v233, v49
	v_add_f32_e32 v48, v231, v48
	v_add_f32_e32 v48, v232, v48
	v_add_f32_e32 v48, v55, v48
	v_add_f32_e32 v234, v233, v48
	v_add_f32_e32 v48, 0x42440000, v171
	v_cmp_nge_f32_e32 vcc, v48, v168
	v_cmp_nle_f32_e64 s[6:7], v48, v169
	v_fma_f32 v49, v170, |v48|, v57
	s_or_b64 vcc, vcc, s[6:7]
	v_cndmask_b32_e32 v48, v49, v228, vcc
	v_exp_f32_e32 v235, v48
	v_add_f32_e32 v48, 0x42480000, v171
	v_cmp_nge_f32_e32 vcc, v48, v168
	v_cmp_nle_f32_e64 s[6:7], v48, v169
	v_fma_f32 v49, v170, |v48|, v58
	s_or_b64 vcc, vcc, s[6:7]
	v_cndmask_b32_e32 v48, v49, v228, vcc
	v_exp_f32_e32 v236, v48
	v_add_f32_e32 v48, 0x424c0000, v171
	v_cmp_nge_f32_e32 vcc, v48, v168
	v_cmp_nle_f32_e64 s[6:7], v48, v169
	v_fma_f32 v49, v170, |v48|, v59
	s_or_b64 vcc, vcc, s[6:7]
	v_cndmask_b32_e32 v48, v49, v228, vcc
	v_exp_f32_e32 v237, v48
	v_add_f32_e32 v48, 0x42600000, v171
	v_cmp_nge_f32_e32 vcc, v48, v168
	v_cmp_nle_f32_e64 s[6:7], v48, v169
	v_fma_f32 v49, v170, |v48|, v60
	s_or_b64 vcc, vcc, s[6:7]
	v_cndmask_b32_e32 v48, v49, v228, vcc
	v_exp_f32_e32 v60, v48
	v_add_f32_e32 v48, 0x42640000, v171
	v_cmp_nge_f32_e32 vcc, v48, v168
	v_cmp_nle_f32_e64 s[6:7], v48, v169
	v_fma_f32 v49, v170, |v48|, v61
	s_or_b64 vcc, vcc, s[6:7]
	v_cndmask_b32_e32 v48, v49, v228, vcc
	v_exp_f32_e32 v61, v48
	v_add_f32_e32 v48, 0x42680000, v171
	v_cmp_nge_f32_e32 vcc, v48, v168
	v_cmp_nle_f32_e64 s[6:7], v48, v169
	v_fma_f32 v49, v170, |v48|, v62
	s_or_b64 vcc, vcc, s[6:7]
	v_cndmask_b32_e32 v52, v49, v228, vcc
	ds_read_b64_tr_b16 v[48:49], v213 offset:55296
	ds_read_b64_tr_b16 v[50:51], v213 offset:56832
	ds_read_b64_tr_b16 v[58:59], v213 offset:56896
	ds_read_b64_tr_b16 v[56:57], v213 offset:55360
	v_exp_f32_e32 v62, v52
	v_add_f32_e32 v239, 0x426c0000, v171
	v_cvt_pk_bf16_f32 v52, v172, v173
	v_cvt_pk_bf16_f32 v53, v174, v175
	v_cvt_pk_bf16_f32 v54, v230, v231
	v_cvt_pk_bf16_f32 v55, v232, v55
	v_cmp_nge_f32_e32 vcc, v239, v168
	v_cmp_nle_f32_e64 s[6:7], v239, v169
	s_waitcnt lgkmcnt(2)
	v_mfma_f32_32x32x16_bf16 v[16:31], v[48:51], v[52:55], v[16:31]
	v_fma_f32 v48, v170, |v239|, v63
	s_or_b64 vcc, vcc, s[6:7]
	v_cndmask_b32_e32 v63, v48, v228, vcc
	ds_read_b64_tr_b16 v[48:49], v213 offset:58368
	ds_read_b64_tr_b16 v[50:51], v213 offset:59904
	v_exp_f32_e32 v63, v63
	s_waitcnt lgkmcnt(2)
	v_mfma_f32_32x32x16_bf16 v[0:15], v[56:59], v[52:55], v[0:15]
	ds_read_b64_tr_b16 v[58:59], v213 offset:59968
	ds_read_b64_tr_b16 v[56:57], v213 offset:58432
	v_cvt_pk_bf16_f32 v52, v233, v235
	v_cvt_pk_bf16_f32 v53, v236, v237
	v_cvt_pk_bf16_f32 v54, v60, v61
	v_cvt_pk_bf16_f32 v55, v62, v63
	s_waitcnt lgkmcnt(2)
	s_nop 0
	v_mfma_f32_32x32x16_bf16 v[16:31], v[48:51], v[52:55], v[16:31]
	v_add_f32_e32 v48, v235, v234
	v_add_f32_e32 v48, v236, v48
	v_add_f32_e32 v48, v237, v48
	v_add_f32_e32 v48, v60, v48
	v_add_f32_e32 v48, v61, v48
	v_add_f32_e32 v48, v62, v48
	v_add_f32_e32 v48, v63, v48
	s_waitcnt lgkmcnt(0)
	v_mfma_f32_32x32x16_bf16 v[0:15], v[56:59], v[52:55], v[0:15]
	v_add_f32_e32 v60, v238, v48
; #define LAS __attribute__((address_space(3)))
; __device__ __forceinline__ unsigned pk2(float lo, float hi) { f32x2_t v = {lo, hi}; bf16x2_t b = __builtin_convertvector(v, bf16x2_t); return __builtin_bit_cast(unsigned, b); }
; __device__ __forceinline__ s16x4 trrd(LAS const unsigned char* p) { return __builtin_bit_cast(s16x4, __builtin_amdgcn_ds_read_tr16_b64_v4i16((LAS v4i16_t*)p)); }
; #define ATTN_QLOAD(W) do { const bf16_t* qr_ = Qb + ((size_t)((W).b * 24 + (W).hd) * SEQ + (size_t)((W).r * (W).L + (W).i0 + 32 * wave + l31)) * 64; \
;         _Pragma("unroll") for (int ks_ = 0; ks_ < 4; ++ks_) qv[ks_] = *(const u32x4*)(qr_ + 16 * ks_ + 8 * h); } while (0)
; template <bool FUSED> __device__ __forceinline__ void attn_phase(const Args& a, LAS unsigned char* lds, int tid, int lane, int wave) {
;     ...
;         for (int j = 0; j < 5; ++j) {
;             f32x16 st;
; #pragma unroll
;             for (int i = 0; i < 16; ++i) st[i] = -mb;
;             LAS const unsigned char* kp = lds + (32 * wave + 32 * j + l31) * KP + 16 * h;
; #pragma unroll
;             for (int ks = 0; ks < 4; ++ks) { const bf16x8 kf = *(LAS const bf16x8*)(kp + 32 * ks); st = __builtin_amdgcn_mfma_f32_32x32x16_bf16(kf, qf[ks], st, 0, 0, 0); }
;             sum += attn_tile_exp(st, j, tlf, bsl, rlo, rhi);
; #pragma unroll
;             for (int s2 = 0; s2 < 2; ++s2) { u32x4 pw; pw.x = pk2(st[8 * s2 + 0], st[8 * s2 + 1]); pw.y = pk2(st[8 * s2 + 2], st[8 * s2 + 3]); pw.z = pk2(st[8 * s2 + 4], st[8 * s2 + 5]); pw.w = pk2(st[8 * s2 + 6], st[8 * s2 + 7]);
;                 const bf16x8 pf = __builtin_bit_cast(bf16x8, pw);
;                 LAS const unsigned char* vp = lds + LDS_VOFF + (32 * wave + 32 * j + 16 * s2 + 4 * h + q) * VP + 32 * blk + 8 * p;
; #pragma unroll
;                 for (int dt = 0; dt < 2; ++dt) { const s16x4 lo = trrd(vp + dt * 64), hi = trrd(vp + 8 * VP + dt * 64);
;                     const bf16x8 vf = __builtin_shufflevector(lo, hi, 0, 1, 2, 3, 4, 5, 6, 7);
;                     o[dt] = __builtin_amdgcn_mfma_f32_32x32x16_bf16(vf, pf, o[dt], 0, 0, 0); } }
;             __builtin_amdgcn_sched_barrier(0);
;         }
;         sum += __shfl_xor(sum, 32);
;         if (un < NU) { const AUnit wq = attn_decode(un, HD0, NH); ATTN_QLOAD(wq); }
.Lattn2_t4:
	ds_read_b128 v[48:51], v214
	ds_read_b128 v[52:55], v214 offset:32
	v_add_f32_e32 v61, 0x42800000, v171
	v_add_f32_e32 v62, 0x42820000, v171
	v_cmp_nge_f32_e32 vcc, v61, v168
	s_waitcnt lgkmcnt(1)
	v_mfma_f32_32x32x16_bf16 v[32:47], v[48:51], v[96:99], v[32:47]
	ds_read_b128 v[48:51], v214 offset:64
	ds_read_b128 v[56:59], v214 offset:96
	v_cmp_nle_f32_e64 s[6:7], v61, v169
	v_add_f32_e32 v63, 0x42840000, v171
	v_cmp_nge_f32_e64 s[8:9], v62, v168
	v_cmp_nle_f32_e64 s[10:11], v62, v169
	s_or_b64 vcc, vcc, s[6:7]
	v_add_f32_e32 v136, 0x42860000, v171
	s_waitcnt lgkmcnt(2)
	v_mfma_f32_32x32x16_bf16 v[32:47], v[52:55], v[100:103], v[32:47]
	v_cmp_nge_f32_e64 s[12:13], v63, v168
	v_cmp_nle_f32_e64 s[14:15], v63, v169
	v_add_f32_e32 v52, 0x42900000, v171
	v_cmp_nge_f32_e64 s[16:17], v136, v168
	v_cmp_nle_f32_e64 s[20:21], v136, v169
	v_add_f32_e32 v53, 0x42920000, v171
	v_cmp_nge_f32_e64 s[22:23], v52, v168
	s_waitcnt lgkmcnt(1)
	v_mfma_f32_32x32x16_bf16 v[32:47], v[48:51], v[104:107], v[32:47]
	v_cmp_nle_f32_e64 s[24:25], v52, v169
	v_cmp_nge_f32_e64 s[26:27], v53, v168
	v_cmp_nle_f32_e64 s[28:29], v53, v169
	s_waitcnt lgkmcnt(0)
	v_mfma_f32_32x32x16_bf16 v[32:47], v[56:59], v[108:111], v[32:47]
	s_nop 11
	v_fma_f32 v32, v170, |v61|, v32
	v_fma_f32 v33, v170, |v62|, v33
	v_cndmask_b32_e32 v32, v32, v228, vcc
	s_or_b64 vcc, s[8:9], s[10:11]
	v_fma_f32 v34, v170, |v63|, v34
	v_cndmask_b32_e32 v33, v33, v228, vcc
	s_or_b64 vcc, s[12:13], s[14:15]
	v_fma_f32 v35, v170, |v136|, v35
	v_cndmask_b32_e32 v34, v34, v228, vcc
	s_or_b64 vcc, s[16:17], s[20:21]
	v_fma_f32 v36, v170, |v52|, v36
	v_cndmask_b32_e32 v35, v35, v228, vcc
	s_or_b64 vcc, s[22:23], s[24:25]
	v_fma_f32 v37, v170, |v53|, v37
	v_cndmask_b32_e32 v36, v36, v228, vcc
	s_or_b64 vcc, s[26:27], s[28:29]
	v_exp_f32_e32 v49, v33
	v_cndmask_b32_e32 v33, v37, v228, vcc
	v_exp_f32_e32 v53, v33
	v_add_f32_e32 v33, 0x42940000, v171
	v_cmp_nge_f32_e32 vcc, v33, v168
	v_cmp_nle_f32_e64 s[6:7], v33, v169
	v_exp_f32_e32 v50, v34
	v_fma_f32 v34, v170, |v33|, v38
	s_or_b64 vcc, vcc, s[6:7]
	v_cndmask_b32_e32 v33, v34, v228, vcc
	v_exp_f32_e32 v48, v32
	v_exp_f32_e32 v54, v33
	v_add_f32_e32 v33, 0x42960000, v171
	v_cmp_nge_f32_e32 vcc, v33, v168
	v_cmp_nle_f32_e64 s[6:7], v33, v169
	v_fma_f32 v34, v170, |v33|, v39
	s_or_b64 vcc, vcc, s[6:7]
	v_exp_f32_e32 v51, v35
	v_cndmask_b32_e32 v33, v34, v228, vcc
	v_exp_f32_e32 v52, v36
	v_add_f32_e32 v32, 0, v48
	v_exp_f32_e32 v39, v33
	v_add_f32_e32 v33, 0x42a00000, v171
	v_add_f32_e32 v32, v49, v32
	v_cmp_nge_f32_e32 vcc, v33, v168
	v_cmp_nle_f32_e64 s[6:7], v33, v169
	v_add_f32_e32 v32, v50, v32
	v_fma_f32 v34, v170, |v33|, v40
	s_or_b64 vcc, vcc, s[6:7]
	v_add_f32_e32 v32, v51, v32
	v_cndmask_b32_e32 v33, v34, v228, vcc
	v_add_f32_e32 v32, v52, v32
	v_exp_f32_e32 v55, v33
	v_add_f32_e32 v32, v53, v32
	v_add_f32_e32 v32, v54, v32
	v_add_f32_e32 v32, v39, v32
	v_add_f32_e32 v56, v55, v32
	v_add_f32_e32 v32, 0x42a20000, v171
	v_cmp_nge_f32_e32 vcc, v32, v168
	v_cmp_nle_f32_e64 s[6:7], v32, v169
	v_fma_f32 v33, v170, |v32|, v41
	s_or_b64 vcc, vcc, s[6:7]
	v_cndmask_b32_e32 v32, v33, v228, vcc
	v_exp_f32_e32 v57, v32
	v_add_f32_e32 v32, 0x42a40000, v171
	v_cmp_nge_f32_e32 vcc, v32, v168
	v_cmp_nle_f32_e64 s[6:7], v32, v169
	v_fma_f32 v33, v170, |v32|, v42
	s_or_b64 vcc, vcc, s[6:7]
	v_cndmask_b32_e32 v32, v33, v228, vcc
	v_exp_f32_e32 v58, v32
	v_add_f32_e32 v32, 0x42a60000, v171
	v_cmp_nge_f32_e32 vcc, v32, v168
	v_cmp_nle_f32_e64 s[6:7], v32, v169
	v_fma_f32 v33, v170, |v32|, v43
	s_or_b64 vcc, vcc, s[6:7]
	v_cndmask_b32_e32 v32, v33, v228, vcc
	v_exp_f32_e32 v59, v32
	v_add_f32_e32 v32, 0x42b00000, v171
	v_cmp_nge_f32_e32 vcc, v32, v168
	v_cmp_nle_f32_e64 s[6:7], v32, v169
	v_fma_f32 v33, v170, |v32|, v44
	s_or_b64 vcc, vcc, s[6:7]
	v_cndmask_b32_e32 v32, v33, v228, vcc
	v_exp_f32_e32 v44, v32
	v_add_f32_e32 v32, 0x42b20000, v171
	v_cmp_nge_f32_e32 vcc, v32, v168
	v_cmp_nle_f32_e64 s[6:7], v32, v169
	v_fma_f32 v33, v170, |v32|, v45
	s_or_b64 vcc, vcc, s[6:7]
	v_cndmask_b32_e32 v32, v33, v228, vcc
	v_exp_f32_e32 v45, v32
	v_add_f32_e32 v32, 0x42b40000, v171
	v_cmp_nge_f32_e32 vcc, v32, v168
	v_cmp_nle_f32_e64 s[6:7], v32, v169
	v_fma_f32 v33, v170, |v32|, v46
	s_or_b64 vcc, vcc, s[6:7]
	v_cndmask_b32_e32 v36, v33, v228, vcc
	ds_read_b64_tr_b16 v[32:33], v215 offset:55296
	ds_read_b64_tr_b16 v[34:35], v215 offset:56832
	ds_read_b64_tr_b16 v[42:43], v215 offset:56896
	ds_read_b64_tr_b16 v[40:41], v215 offset:55360
	v_exp_f32_e32 v46, v36
	v_add_f32_e32 v61, 0x42b60000, v171
	v_cvt_pk_bf16_f32 v36, v48, v49
	v_cvt_pk_bf16_f32 v37, v50, v51
	v_cvt_pk_bf16_f32 v38, v52, v53
	v_cvt_pk_bf16_f32 v39, v54, v39
	v_cmp_nge_f32_e32 vcc, v61, v168
	v_cmp_nle_f32_e64 s[6:7], v61, v169
	s_waitcnt lgkmcnt(2)
	v_mfma_f32_32x32x16_bf16 v[16:31], v[32:35], v[36:39], v[16:31]
	v_fma_f32 v32, v170, |v61|, v47
	s_or_b64 vcc, vcc, s[6:7]
	v_cndmask_b32_e32 v47, v32, v228, vcc
	ds_read_b64_tr_b16 v[32:33], v215 offset:58368
	ds_read_b64_tr_b16 v[34:35], v215 offset:59904
	v_exp_f32_e32 v47, v47
	s_waitcnt lgkmcnt(2)
	v_mfma_f32_32x32x16_bf16 v[0:15], v[40:43], v[36:39], v[0:15]
	ds_read_b64_tr_b16 v[42:43], v215 offset:59968
	ds_read_b64_tr_b16 v[40:41], v215 offset:58432
	v_cvt_pk_bf16_f32 v36, v55, v57
	v_cvt_pk_bf16_f32 v37, v58, v59
	v_cvt_pk_bf16_f32 v38, v44, v45
	v_cvt_pk_bf16_f32 v39, v46, v47
	s_waitcnt lgkmcnt(2)
	s_nop 0
	v_mfma_f32_32x32x16_bf16 v[16:31], v[32:35], v[36:39], v[16:31]
	v_add_f32_e32 v32, v57, v56
	v_add_f32_e32 v32, v58, v32
	v_add_f32_e32 v32, v59, v32
	v_add_f32_e32 v32, v44, v32
	v_add_f32_e32 v32, v45, v32
	v_add_f32_e32 v32, v46, v32
	v_add_f32_e32 v32, v47, v32
	s_waitcnt lgkmcnt(0)
	v_mfma_f32_32x32x16_bf16 v[0:15], v[40:43], v[36:39], v[0:15]
	v_add_f32_e32 v236, v60, v32
	ds_bpermute_b32 v237, v151, v236
	s_andn2_b64 vcc, exec, s[44:45]
	s_cbranch_vccnz .LBB0_406
	s_ashr_i32 s7, s64, 5
	s_lshr_b32 s8, s7, 29
	s_add_i32 s8, s7, s8
	s_and_b32 s8, s8, -8
	s_sub_i32 s7, s7, s8
	s_ashr_i32 s9, s7, 2
	s_ashr_i32 s8, s64, 31
	s_and_b32 s9, s9, -2
	s_lshr_b32 s8, s8, 24
	s_lshr_b32 s10, 32, s9
	s_and_b32 s6, s64, 31
	s_add_i32 s8, s64, s8
	s_lshr_b32 s11, 0x2000, s9
	s_sub_i32 s9, 5, s9
	s_add_i32 s10, s10, -1
	s_ashr_i32 s8, s8, 8
	s_lshr_b32 s9, s6, s9
	s_and_b32 s6, s10, s6
	s_lshl_b32 s10, s6, 8
	s_mul_i32 s6, s8, 24
	s_add_i32 s6, s6, s7
	s_mul_i32 s9, s9, s11
	s_ashr_i32 s7, s6, 31
	s_add_i32 s10, s10, s9
	v_add_u32_e32 v32, s10, v187
	s_lshl_b64 s[6:7], s[6:7], 20
	v_ashrrev_i32_e32 v33, 31, v32
	s_add_u32 s6, s40, s6
	s_addc_u32 s7, s41, s7
	v_lshlrev_b64 v[32:33], 7, v[32:33]
	v_lshl_add_u64 v[32:33], s[6:7], 0, v[32:33]
	v_lshl_add_u64 v[32:33], v[148:149], 1, v[32:33]
	global_load_dwordx4 v[96:99], v[32:33], off
	global_load_dwordx4 v[100:103], v[32:33], off offset:32
	global_load_dwordx4 v[104:107], v[32:33], off offset:64
	global_load_dwordx4 v[108:111], v[32:33], off offset:96
